# decode-group cross attention: the read-once f32 K/V cache rows loaded with the non-temporal hint
# speedup vs baseline: 1.0103x; 1.0026x over previous
.LBB0_501:
	s_mov_b64 s[0:1], s[58:59]
	s_load_dwordx2 s[0:1], s[0:1], 0x158
	s_mov_b64 s[2:3], s[58:59]
	s_ashr_i32 s6, s9, 2
	s_load_dwordx2 s[4:5], s[2:3], 0x38
	s_mov_b64 s[2:3], s[58:59]
	s_mov_b64 s[10:11], s[58:59]
	s_lshl_b32 s36, s6, 3
	s_and_b32 s29, s8, 0x300
	s_load_dwordx2 s[2:3], s[2:3], 0x40
	s_add_i32 s20, s36, 0x4000
	s_lshl_b32 s30, s29, 1
	s_load_dwordx2 s[10:11], s[10:11], 0x158
	v_mbcnt_lo_u32_b32 v130, -1, 0
	v_mbcnt_hi_u32_b32 v130, -1, v130
	s_waitcnt lgkmcnt(0)
	s_add_u32 s0, s0, s30
	v_and_b32_e32 v131, 63, v130
	s_addc_u32 s1, s1, 0
	v_lshlrev_b32_e32 v156, 3, v131
	v_lshl_add_u64 v[0:1], s[0:1], 0, v[156:157]
	s_ashr_i32 s21, s20, 31
	v_lshl_add_u64 v[0:1], v[0:1], 0, s[62:63]
	s_lshl_b64 s[0:1], s[20:21], 11
	s_ashr_i32 s37, s36, 31
	v_lshl_add_u64 v[2:3], v[0:1], 0, s[0:1]
	s_lshl_b64 s[0:1], s[36:37], 11
	v_lshl_add_u64 v[0:1], v[0:1], 0, s[0:1]
	s_brev_b32 s0, 64
	v_add_co_u32_e32 v4, vcc, s0, v0
	s_mov_b32 s0, 0x2002000
	s_nop 0
	v_addc_co_u32_e32 v5, vcc, 0, v1, vcc
	v_add_co_u32_e32 v6, vcc, s0, v0
	s_mov_b32 s0, 0x2001000
	s_nop 0
	v_addc_co_u32_e32 v7, vcc, 0, v1, vcc
	v_add_co_u32_e32 v10, vcc, s0, v0
	s_mov_b32 s0, 0x2003000
	s_nop 0
	v_addc_co_u32_e32 v11, vcc, 0, v1, vcc
	v_add_co_u32_e32 v0, vcc, s0, v0
	global_load_dwordx2 v[2:3], v[2:3], off
	s_nop 0
	v_addc_co_u32_e32 v1, vcc, 0, v1, vcc
	global_load_dwordx2 v[4:5], v[4:5], off offset:2048
	v_add_u32_e32 v132, s61, v130
	global_load_dwordx2 v[8:9], v[6:7], off offset:-4096
	s_nop 0
	global_load_dwordx2 v[10:11], v[10:11], off offset:2048
	s_nop 0
	global_load_dwordx2 v[12:13], v[6:7], off
	s_nop 0
	global_load_dwordx2 v[6:7], v[6:7], off offset:2048
	s_nop 0
	global_load_dwordx2 v[14:15], v[0:1], off
	s_nop 0
	global_load_dwordx2 v[0:1], v[0:1], off offset:2048
	s_ashr_i32 s7, s6, 31
	v_ashrrev_i32_e32 v129, 6, v132
	s_lshl_b64 s[0:1], s[6:7], 8
	v_lshlrev_b32_e32 v16, 5, v129
	s_add_u32 s0, s0, s15
	v_ashrrev_i32_e32 v17, 31, v16
	s_addc_u32 s1, s1, 0
	v_lshl_add_u64 v[16:17], s[0:1], 0, v[16:17]
	v_lshlrev_b32_e32 v128, 2, v131
	v_lshlrev_b64 v[16:17], 10, v[16:17]
	v_or3_b32 v16, v16, s29, v128
	v_lshlrev_b64 v[16:17], 2, v[16:17]
	v_lshl_add_u64 v[116:117], s[4:5], 0, v[16:17]
	global_load_dwordx4 v[60:63], v[116:117], off nt
	v_lshl_add_u64 v[124:125], s[2:3], 0, v[16:17]
	v_and_b32_e32 v82, 16, v130
	v_cmp_eq_u32_e64 s[2:3], 0, v82
	v_and_b32_e32 v83, 8, v130
	v_cmp_eq_u32_e64 s[4:5], 0, v83
	s_mov_b32 s0, 0x15000
	s_waitcnt vmcnt(0)
	v_lshlrev_b32_e32 v92, 16, v3
	v_and_b32_e32 v93, 0xffff0000, v3
	v_lshlrev_b32_e32 v84, 16, v2
	v_lshlrev_b32_e32 v96, 16, v5
	v_and_b32_e32 v97, 0xffff0000, v5
	v_lshlrev_b32_e32 v94, 16, v12
	v_and_b32_e32 v95, 0xffff0000, v12
	v_lshlrev_b32_e32 v106, 16, v0
	v_and_b32_e32 v107, 0xffff0000, v0
	v_add_co_u32_e32 v0, vcc, s93, v116
	v_lshlrev_b32_e32 v114, 16, v1
	v_and_b32_e32 v115, 0xffff0000, v1
	v_addc_co_u32_e32 v1, vcc, 0, v117, vcc
	global_load_dwordx4 v[64:67], v[0:1], off offset:-4096 nt
	global_load_dwordx4 v[52:55], v[0:1], off nt
	v_add_co_u32_e32 v0, vcc, s88, v116
	v_lshlrev_b32_e32 v108, 16, v13
	s_nop 0
	v_addc_co_u32_e32 v1, vcc, 0, v117, vcc
	global_load_dwordx4 v[48:51], v[0:1], off offset:-4096 nt
	global_load_dwordx4 v[44:47], v[0:1], off nt
	v_add_co_u32_e32 v0, vcc, s45, v116
	v_and_b32_e32 v109, 0xffff0000, v13
	s_nop 0
	v_addc_co_u32_e32 v1, vcc, 0, v117, vcc
	v_add_co_u32_e32 v58, vcc, s35, v116
	global_load_dwordx4 v[40:43], v[0:1], off offset:-4096 nt
	global_load_dwordx4 v[36:39], v[0:1], off nt
	v_addc_co_u32_e32 v59, vcc, 0, v117, vcc
	v_add_co_u32_e32 v0, vcc, s93, v124
	global_load_dwordx4 v[32:35], v[58:59], off offset:-4096 nt
	global_load_dwordx4 v[28:31], v[124:125], off nt
	v_addc_co_u32_e32 v1, vcc, 0, v125, vcc
	global_load_dwordx4 v[24:27], v[0:1], off offset:-4096 nt
	global_load_dwordx4 v[20:23], v[0:1], off nt
	v_add_co_u32_e32 v0, vcc, s88, v124
	v_lshlrev_b32_e32 v102, 16, v14
	s_nop 0
	v_addc_co_u32_e32 v1, vcc, 0, v125, vcc
	v_and_b32_e32 v103, 0xffff0000, v14
	v_lshlrev_b32_e32 v112, 16, v15
	v_and_b32_e32 v113, 0xffff0000, v15
	global_load_dwordx4 v[16:19], v[0:1], off offset:-4096 nt
	global_load_dwordx4 v[12:15], v[0:1], off nt
	v_add_co_u32_e32 v0, vcc, s45, v124
	v_lshlrev_b32_e32 v100, 16, v9
	v_and_b32_e32 v101, 0xffff0000, v9
	v_lshlrev_b32_e32 v104, 16, v11
	v_and_b32_e32 v105, 0xffff0000, v11
	v_lshlrev_b32_e32 v110, 16, v7
	v_and_b32_e32 v111, 0xffff0000, v7
	v_addc_co_u32_e32 v1, vcc, 0, v125, vcc
	v_and_b32_e32 v85, 0xffff0000, v2
	v_lshlrev_b32_e32 v86, 16, v4
	v_and_b32_e32 v87, 0xffff0000, v4
	v_lshlrev_b32_e32 v88, 16, v8
	v_and_b32_e32 v89, 0xffff0000, v8
	v_lshlrev_b32_e32 v90, 16, v10
	v_and_b32_e32 v91, 0xffff0000, v10
	v_lshlrev_b32_e32 v98, 16, v6
	v_and_b32_e32 v99, 0xffff0000, v6
	v_add_co_u32_e32 v56, vcc, s35, v124
	v_pk_mul_f32 v[68:69], v[62:63], v[92:93]
	v_pk_mul_f32 v[70:71], v[62:63], v[96:97]
	v_pk_mul_f32 v[72:73], v[62:63], v[100:101]
	v_pk_mul_f32 v[74:75], v[62:63], v[104:105]
	v_pk_mul_f32 v[76:77], v[62:63], v[108:109]
	v_pk_mul_f32 v[78:79], v[62:63], v[110:111]
	v_pk_mul_f32 v[80:81], v[62:63], v[112:113]
	v_pk_mul_f32 v[62:63], v[62:63], v[114:115]
	v_addc_co_u32_e32 v57, vcc, 0, v125, vcc
	v_pk_fma_f32 v[68:69], v[60:61], v[84:85], v[68:69]
	v_pk_fma_f32 v[70:71], v[60:61], v[86:87], v[70:71]
	v_pk_fma_f32 v[72:73], v[60:61], v[88:89], v[72:73]
	v_pk_fma_f32 v[74:75], v[60:61], v[90:91], v[74:75]
	v_pk_fma_f32 v[76:77], v[60:61], v[94:95], v[76:77]
	v_pk_fma_f32 v[78:79], v[60:61], v[98:99], v[78:79]
	v_pk_fma_f32 v[80:81], v[60:61], v[102:103], v[80:81]
	v_pk_fma_f32 v[60:61], v[60:61], v[106:107], v[62:63]
	v_pk_add_f32 v[68:69], v[68:69], v[68:69] op_sel:[0,1] op_sel_hi:[1,0]
	v_pk_add_f32 v[76:77], v[76:77], v[76:77] op_sel:[0,1] op_sel_hi:[1,0]
	v_pk_add_f32 v[60:61], v[60:61], v[60:61] op_sel:[0,1] op_sel_hi:[1,0]
	v_cmp_lt_u32_e32 vcc, 31, v131
	global_load_dwordx4 v[8:11], v[0:1], off offset:-4096 nt
	global_load_dwordx4 v[4:7], v[0:1], off nt
	v_cndmask_b32_e32 v61, v76, v68, vcc
	v_mov_b32_e32 v63, v61
	global_load_dwordx4 v[0:3], v[56:57], off offset:-4096 nt
	v_pk_add_f32 v[70:71], v[70:71], v[70:71] op_sel:[0,1] op_sel_hi:[1,0]
	v_permlane32_swap_b32_e32 v61, v63
	v_pk_add_f32 v[78:79], v[78:79], v[78:79] op_sel:[0,1] op_sel_hi:[1,0]
	v_cndmask_b32_e32 v62, v68, v76, vcc
	v_cndmask_b32_e32 v61, v63, v61, vcc
	v_add_f32_e32 v61, v62, v61
	v_cndmask_b32_e32 v62, v78, v70, vcc
	v_mov_b32_e32 v68, v62
	v_pk_add_f32 v[72:73], v[72:73], v[72:73] op_sel:[0,1] op_sel_hi:[1,0]
	s_nop 0
	v_permlane32_swap_b32_e32 v62, v68
	v_pk_add_f32 v[80:81], v[80:81], v[80:81] op_sel:[0,1] op_sel_hi:[1,0]
	v_cndmask_b32_e32 v63, v70, v78, vcc
	v_cndmask_b32_e32 v62, v68, v62, vcc
	v_add_f32_e32 v62, v63, v62
	v_cndmask_b32_e32 v63, v80, v72, vcc
	v_mov_b32_e32 v69, v63
	v_pk_add_f32 v[74:75], v[74:75], v[74:75] op_sel:[0,1] op_sel_hi:[1,0]
	s_nop 0
	v_permlane32_swap_b32_e32 v63, v69
	v_cndmask_b32_e32 v68, v72, v80, vcc
	v_cndmask_b32_e32 v63, v69, v63, vcc
	v_add_f32_e32 v63, v68, v63
	v_cndmask_b32_e32 v68, v60, v74, vcc
	v_mov_b32_e32 v69, v68
	v_cndmask_b32_e32 v60, v74, v60, vcc
	s_nop 0
	v_permlane32_swap_b32_e32 v68, v69
	v_cndmask_b32_e32 v68, v69, v68, vcc
	v_add_f32_e32 v60, v60, v68
	v_cndmask_b32_e64 v68, v61, v63, s[2:3]
	v_cndmask_b32_e64 v61, v63, v61, s[2:3]
	v_mov_b32_e32 v63, v68
	s_waitcnt vmcnt(14)
	v_pk_mul_f32 v[72:73], v[66:67], v[108:109]
	v_permlane16_swap_b32_e32 v68, v63
	v_cndmask_b32_e64 v63, v68, v63, s[2:3]
	v_add_f32_e32 v61, v61, v63
	v_cndmask_b32_e64 v63, v62, v60, s[2:3]
	v_cndmask_b32_e64 v60, v60, v62, s[2:3]
	v_mov_b32_e32 v62, v63
	v_pk_fma_f32 v[72:73], v[64:65], v[94:95], v[72:73]
	s_nop 0
	v_permlane16_swap_b32_e32 v63, v62
	v_cndmask_b32_e64 v62, v63, v62, s[2:3]
	v_add_f32_e32 v60, v60, v62
	v_cndmask_b32_e64 v62, v61, v60, s[4:5]
	v_cndmask_b32_e64 v60, v60, v61, s[4:5]
	v_pk_add_f32 v[72:73], v[72:73], v[72:73] op_sel:[0,1] op_sel_hi:[1,0]
	v_pk_mul_f32 v[74:75], v[66:67], v[110:111]
	v_add_f32_dpp v60, v62, v60 row_ror:8 row_mask:0xf bank_mask:0xf bound_ctrl:1
	v_pk_mul_f32 v[62:63], v[66:67], v[96:97]
	v_pk_fma_f32 v[74:75], v[64:65], v[98:99], v[74:75]
	v_add_f32_dpp v60, v60, v60 quad_perm:[1,0,3,2] row_mask:0xf bank_mask:0xf bound_ctrl:1
	v_pk_fma_f32 v[62:63], v[64:65], v[86:87], v[62:63]
	v_pk_add_f32 v[74:75], v[74:75], v[74:75] op_sel:[0,1] op_sel_hi:[1,0]
	v_add_f32_dpp v60, v60, v60 quad_perm:[2,3,0,1] row_mask:0xf bank_mask:0xf bound_ctrl:1
	v_pk_add_f32 v[62:63], v[62:63], v[62:63] op_sel:[0,1] op_sel_hi:[1,0]
	v_pk_mul_f32 v[68:69], v[66:67], v[100:101]
	v_add_f32_dpp v133, v60, v60 row_half_mirror row_mask:0xf bank_mask:0xf bound_ctrl:1
	v_pk_mul_f32 v[60:61], v[66:67], v[92:93]
	v_pk_mul_f32 v[76:77], v[66:67], v[112:113]
	v_pk_fma_f32 v[60:61], v[64:65], v[84:85], v[60:61]
	v_pk_fma_f32 v[68:69], v[64:65], v[88:89], v[68:69]
	v_pk_add_f32 v[60:61], v[60:61], v[60:61] op_sel:[0,1] op_sel_hi:[1,0]
	v_pk_mul_f32 v[70:71], v[66:67], v[104:105]
	v_cndmask_b32_e32 v61, v72, v60, vcc
	v_mov_b32_e32 v63, v61
	v_cndmask_b32_e32 v60, v60, v72, vcc
	s_nop 0
	v_permlane32_swap_b32_e32 v61, v63
	v_cndmask_b32_e32 v61, v63, v61, vcc
	v_add_f32_e32 v60, v60, v61
	v_cndmask_b32_e32 v61, v74, v62, vcc
	v_mov_b32_e32 v63, v61
	v_pk_fma_f32 v[76:77], v[64:65], v[102:103], v[76:77]
	v_pk_mul_f32 v[66:67], v[66:67], v[114:115]
	v_permlane32_swap_b32_e32 v61, v63
	v_pk_add_f32 v[68:69], v[68:69], v[68:69] op_sel:[0,1] op_sel_hi:[1,0]
	v_pk_fma_f32 v[70:71], v[64:65], v[90:91], v[70:71]
	v_pk_add_f32 v[76:77], v[76:77], v[76:77] op_sel:[0,1] op_sel_hi:[1,0]
	v_pk_fma_f32 v[64:65], v[64:65], v[106:107], v[66:67]
	v_cndmask_b32_e32 v62, v62, v74, vcc
	v_cndmask_b32_e32 v61, v63, v61, vcc
	v_pk_add_f32 v[64:65], v[64:65], v[64:65] op_sel:[0,1] op_sel_hi:[1,0]
	v_add_f32_e32 v61, v62, v61
	v_cndmask_b32_e32 v62, v76, v68, vcc
	v_mov_b32_e32 v65, v62
	v_pk_add_f32 v[70:71], v[70:71], v[70:71] op_sel:[0,1] op_sel_hi:[1,0]
	s_nop 0
	v_permlane32_swap_b32_e32 v62, v65
	v_cndmask_b32_e32 v63, v68, v76, vcc
	v_cndmask_b32_e32 v62, v65, v62, vcc
	v_add_f32_e32 v62, v63, v62
	v_cndmask_b32_e32 v63, v64, v70, vcc
	v_mov_b32_e32 v65, v63
	v_cndmask_b32_e32 v64, v70, v64, vcc
	s_nop 0
	v_permlane32_swap_b32_e32 v63, v65
	v_cndmask_b32_e32 v63, v65, v63, vcc
	v_add_f32_e32 v63, v64, v63
	v_cndmask_b32_e64 v64, v60, v62, s[2:3]
	v_cndmask_b32_e64 v60, v62, v60, s[2:3]
	v_mov_b32_e32 v62, v64
	s_waitcnt vmcnt(13)
	v_pk_mul_f32 v[66:67], v[54:55], v[104:105]
	v_permlane16_swap_b32_e32 v64, v62
	v_cndmask_b32_e64 v62, v64, v62, s[2:3]
	v_add_f32_e32 v60, v60, v62
	v_cndmask_b32_e64 v62, v61, v63, s[2:3]
	v_cndmask_b32_e64 v61, v63, v61, s[2:3]
	v_mov_b32_e32 v63, v62
	v_pk_mul_f32 v[64:65], v[54:55], v[100:101]
	s_nop 0
	v_permlane16_swap_b32_e32 v62, v63
	v_cndmask_b32_e64 v62, v62, v63, s[2:3]
	v_add_f32_e32 v61, v61, v62
	v_cndmask_b32_e64 v62, v60, v61, s[4:5]
	v_cndmask_b32_e64 v60, v61, v60, s[4:5]
	v_pk_mul_f32 v[68:69], v[54:55], v[108:109]
	v_pk_mul_f32 v[70:71], v[54:55], v[110:111]
	v_add_f32_dpp v60, v62, v60 row_ror:8 row_mask:0xf bank_mask:0xf bound_ctrl:1
	v_pk_mul_f32 v[62:63], v[54:55], v[96:97]
	v_pk_mul_f32 v[72:73], v[54:55], v[112:113]
	v_add_f32_dpp v60, v60, v60 quad_perm:[1,0,3,2] row_mask:0xf bank_mask:0xf bound_ctrl:1
	v_pk_fma_f32 v[62:63], v[52:53], v[86:87], v[62:63]
	v_pk_fma_f32 v[64:65], v[52:53], v[88:89], v[64:65]
	v_add_f32_dpp v60, v60, v60 quad_perm:[2,3,0,1] row_mask:0xf bank_mask:0xf bound_ctrl:1
	v_pk_fma_f32 v[66:67], v[52:53], v[90:91], v[66:67]
	v_pk_fma_f32 v[68:69], v[52:53], v[94:95], v[68:69]
	v_add_f32_dpp v135, v60, v60 row_half_mirror row_mask:0xf bank_mask:0xf bound_ctrl:1
	v_pk_mul_f32 v[60:61], v[54:55], v[92:93]
	v_pk_mul_f32 v[54:55], v[54:55], v[114:115]
	v_pk_fma_f32 v[60:61], v[52:53], v[84:85], v[60:61]
	v_pk_fma_f32 v[70:71], v[52:53], v[98:99], v[70:71]
	v_pk_fma_f32 v[72:73], v[52:53], v[102:103], v[72:73]
	v_pk_fma_f32 v[52:53], v[52:53], v[106:107], v[54:55]
	v_pk_add_f32 v[60:61], v[60:61], v[60:61] op_sel:[0,1] op_sel_hi:[1,0]
	v_pk_add_f32 v[68:69], v[68:69], v[68:69] op_sel:[0,1] op_sel_hi:[1,0]
	v_pk_add_f32 v[52:53], v[52:53], v[52:53] op_sel:[0,1] op_sel_hi:[1,0]
	v_pk_add_f32 v[62:63], v[62:63], v[62:63] op_sel:[0,1] op_sel_hi:[1,0]
	v_cndmask_b32_e32 v53, v68, v60, vcc
	v_mov_b32_e32 v55, v53
	v_pk_add_f32 v[70:71], v[70:71], v[70:71] op_sel:[0,1] op_sel_hi:[1,0]
	s_nop 0
	v_permlane32_swap_b32_e32 v53, v55
	v_cndmask_b32_e32 v54, v60, v68, vcc
	v_cndmask_b32_e32 v53, v55, v53, vcc
	v_add_f32_e32 v53, v54, v53
	v_cndmask_b32_e32 v54, v70, v62, vcc
	v_mov_b32_e32 v60, v54
	v_pk_add_f32 v[64:65], v[64:65], v[64:65] op_sel:[0,1] op_sel_hi:[1,0]
	s_nop 0
	v_permlane32_swap_b32_e32 v54, v60
	v_pk_add_f32 v[72:73], v[72:73], v[72:73] op_sel:[0,1] op_sel_hi:[1,0]
	v_cndmask_b32_e32 v55, v62, v70, vcc
	v_cndmask_b32_e32 v54, v60, v54, vcc
	v_add_f32_e32 v54, v55, v54
	v_cndmask_b32_e32 v55, v72, v64, vcc
	v_mov_b32_e32 v61, v55
	v_pk_add_f32 v[66:67], v[66:67], v[66:67] op_sel:[0,1] op_sel_hi:[1,0]
	s_nop 0
	v_permlane32_swap_b32_e32 v55, v61
	v_cndmask_b32_e32 v60, v64, v72, vcc
	v_cndmask_b32_e32 v55, v61, v55, vcc
	v_add_f32_e32 v55, v60, v55
	v_cndmask_b32_e32 v60, v52, v66, vcc
	v_mov_b32_e32 v61, v60
	v_cndmask_b32_e32 v52, v66, v52, vcc
	s_nop 0
	v_permlane32_swap_b32_e32 v60, v61
	v_cndmask_b32_e32 v60, v61, v60, vcc
	v_add_f32_e32 v52, v52, v60
	v_cndmask_b32_e64 v60, v53, v55, s[2:3]
	v_cndmask_b32_e64 v53, v55, v53, s[2:3]
	v_mov_b32_e32 v55, v60
	s_waitcnt vmcnt(12)
	v_pk_mul_f32 v[62:63], v[50:51], v[104:105]
	v_permlane16_swap_b32_e32 v60, v55
	v_cndmask_b32_e64 v55, v60, v55, s[2:3]
	v_add_f32_e32 v53, v53, v55
	v_cndmask_b32_e64 v55, v54, v52, s[2:3]
	v_cndmask_b32_e64 v52, v52, v54, s[2:3]
	v_mov_b32_e32 v54, v55
	v_pk_mul_f32 v[60:61], v[50:51], v[100:101]
	s_nop 0
	v_permlane16_swap_b32_e32 v55, v54
	v_cndmask_b32_e64 v54, v55, v54, s[2:3]
	v_add_f32_e32 v52, v52, v54
	v_cndmask_b32_e64 v54, v53, v52, s[4:5]
	v_cndmask_b32_e64 v52, v52, v53, s[4:5]
	v_pk_mul_f32 v[64:65], v[50:51], v[108:109]
	v_pk_mul_f32 v[66:67], v[50:51], v[110:111]
	v_add_f32_dpp v52, v54, v52 row_ror:8 row_mask:0xf bank_mask:0xf bound_ctrl:1
	v_pk_mul_f32 v[54:55], v[50:51], v[96:97]
	v_pk_mul_f32 v[68:69], v[50:51], v[112:113]
	v_add_f32_dpp v52, v52, v52 quad_perm:[1,0,3,2] row_mask:0xf bank_mask:0xf bound_ctrl:1
	v_pk_fma_f32 v[54:55], v[48:49], v[86:87], v[54:55]
	v_pk_fma_f32 v[60:61], v[48:49], v[88:89], v[60:61]
	v_add_f32_dpp v52, v52, v52 quad_perm:[2,3,0,1] row_mask:0xf bank_mask:0xf bound_ctrl:1
	v_pk_fma_f32 v[62:63], v[48:49], v[90:91], v[62:63]
	v_pk_fma_f32 v[64:65], v[48:49], v[94:95], v[64:65]
	v_add_f32_dpp v137, v52, v52 row_half_mirror row_mask:0xf bank_mask:0xf bound_ctrl:1
	v_pk_mul_f32 v[52:53], v[50:51], v[92:93]
	v_pk_mul_f32 v[50:51], v[50:51], v[114:115]
	v_pk_fma_f32 v[52:53], v[48:49], v[84:85], v[52:53]
	v_pk_fma_f32 v[66:67], v[48:49], v[98:99], v[66:67]
	v_pk_fma_f32 v[68:69], v[48:49], v[102:103], v[68:69]
	v_pk_fma_f32 v[48:49], v[48:49], v[106:107], v[50:51]
	v_pk_add_f32 v[52:53], v[52:53], v[52:53] op_sel:[0,1] op_sel_hi:[1,0]
	v_pk_add_f32 v[64:65], v[64:65], v[64:65] op_sel:[0,1] op_sel_hi:[1,0]
	v_pk_add_f32 v[48:49], v[48:49], v[48:49] op_sel:[0,1] op_sel_hi:[1,0]
	v_pk_add_f32 v[54:55], v[54:55], v[54:55] op_sel:[0,1] op_sel_hi:[1,0]
	v_cndmask_b32_e32 v49, v64, v52, vcc
	v_mov_b32_e32 v51, v49
	v_pk_add_f32 v[66:67], v[66:67], v[66:67] op_sel:[0,1] op_sel_hi:[1,0]
	s_nop 0
	v_permlane32_swap_b32_e32 v49, v51
	v_cndmask_b32_e32 v50, v52, v64, vcc
	v_cndmask_b32_e32 v49, v51, v49, vcc
	v_add_f32_e32 v49, v50, v49
	v_cndmask_b32_e32 v50, v66, v54, vcc
	v_mov_b32_e32 v52, v50
	v_pk_add_f32 v[60:61], v[60:61], v[60:61] op_sel:[0,1] op_sel_hi:[1,0]
	s_nop 0
	v_permlane32_swap_b32_e32 v50, v52
	v_pk_add_f32 v[68:69], v[68:69], v[68:69] op_sel:[0,1] op_sel_hi:[1,0]
	v_cndmask_b32_e32 v51, v54, v66, vcc
	v_cndmask_b32_e32 v50, v52, v50, vcc
	v_add_f32_e32 v50, v51, v50
	v_cndmask_b32_e32 v51, v68, v60, vcc
	v_mov_b32_e32 v53, v51
	v_pk_add_f32 v[62:63], v[62:63], v[62:63] op_sel:[0,1] op_sel_hi:[1,0]
	s_nop 0
	v_permlane32_swap_b32_e32 v51, v53
	v_cndmask_b32_e32 v52, v60, v68, vcc
	v_cndmask_b32_e32 v51, v53, v51, vcc
	v_add_f32_e32 v51, v52, v51
	v_cndmask_b32_e32 v52, v48, v62, vcc
	v_mov_b32_e32 v53, v52
	v_cndmask_b32_e32 v48, v62, v48, vcc
	s_nop 0
	v_permlane32_swap_b32_e32 v52, v53
	v_cndmask_b32_e32 v52, v53, v52, vcc
	v_add_f32_e32 v48, v48, v52
	v_cndmask_b32_e64 v52, v49, v51, s[2:3]
	v_cndmask_b32_e64 v49, v51, v49, s[2:3]
	v_mov_b32_e32 v51, v52
	s_waitcnt vmcnt(11)
	v_pk_mul_f32 v[54:55], v[46:47], v[104:105]
	v_permlane16_swap_b32_e32 v52, v51
	v_cndmask_b32_e64 v51, v52, v51, s[2:3]
	v_add_f32_e32 v49, v49, v51
	v_cndmask_b32_e64 v51, v50, v48, s[2:3]
	v_cndmask_b32_e64 v48, v48, v50, s[2:3]
	v_mov_b32_e32 v50, v51
	v_pk_mul_f32 v[52:53], v[46:47], v[100:101]
	s_nop 0
	v_permlane16_swap_b32_e32 v51, v50
	v_cndmask_b32_e64 v50, v51, v50, s[2:3]
	v_add_f32_e32 v48, v48, v50
	v_cndmask_b32_e64 v50, v49, v48, s[4:5]
	v_cndmask_b32_e64 v48, v48, v49, s[4:5]
	v_pk_mul_f32 v[60:61], v[46:47], v[108:109]
	v_pk_mul_f32 v[62:63], v[46:47], v[110:111]
	v_add_f32_dpp v48, v50, v48 row_ror:8 row_mask:0xf bank_mask:0xf bound_ctrl:1
	v_pk_mul_f32 v[50:51], v[46:47], v[96:97]
	v_pk_mul_f32 v[64:65], v[46:47], v[112:113]
	v_add_f32_dpp v48, v48, v48 quad_perm:[1,0,3,2] row_mask:0xf bank_mask:0xf bound_ctrl:1
	v_pk_fma_f32 v[50:51], v[44:45], v[86:87], v[50:51]
	v_pk_fma_f32 v[52:53], v[44:45], v[88:89], v[52:53]
	v_add_f32_dpp v48, v48, v48 quad_perm:[2,3,0,1] row_mask:0xf bank_mask:0xf bound_ctrl:1
	v_pk_fma_f32 v[54:55], v[44:45], v[90:91], v[54:55]
	v_pk_fma_f32 v[60:61], v[44:45], v[94:95], v[60:61]
	v_add_f32_dpp v139, v48, v48 row_half_mirror row_mask:0xf bank_mask:0xf bound_ctrl:1
	v_pk_mul_f32 v[48:49], v[46:47], v[92:93]
	v_pk_mul_f32 v[46:47], v[46:47], v[114:115]
	v_pk_fma_f32 v[48:49], v[44:45], v[84:85], v[48:49]
	v_pk_fma_f32 v[62:63], v[44:45], v[98:99], v[62:63]
	v_pk_fma_f32 v[64:65], v[44:45], v[102:103], v[64:65]
	v_pk_fma_f32 v[44:45], v[44:45], v[106:107], v[46:47]
	v_pk_add_f32 v[48:49], v[48:49], v[48:49] op_sel:[0,1] op_sel_hi:[1,0]
	v_pk_add_f32 v[60:61], v[60:61], v[60:61] op_sel:[0,1] op_sel_hi:[1,0]
	v_pk_add_f32 v[44:45], v[44:45], v[44:45] op_sel:[0,1] op_sel_hi:[1,0]
	v_pk_add_f32 v[50:51], v[50:51], v[50:51] op_sel:[0,1] op_sel_hi:[1,0]
	v_cndmask_b32_e32 v45, v60, v48, vcc
	v_mov_b32_e32 v47, v45
	v_pk_add_f32 v[62:63], v[62:63], v[62:63] op_sel:[0,1] op_sel_hi:[1,0]
	s_nop 0
	v_permlane32_swap_b32_e32 v45, v47
	v_cndmask_b32_e32 v46, v48, v60, vcc
	v_cndmask_b32_e32 v45, v47, v45, vcc
	v_add_f32_e32 v45, v46, v45
	v_cndmask_b32_e32 v46, v62, v50, vcc
	v_mov_b32_e32 v48, v46
	v_pk_add_f32 v[52:53], v[52:53], v[52:53] op_sel:[0,1] op_sel_hi:[1,0]
	s_nop 0
	v_permlane32_swap_b32_e32 v46, v48
	v_pk_add_f32 v[64:65], v[64:65], v[64:65] op_sel:[0,1] op_sel_hi:[1,0]
	v_cndmask_b32_e32 v47, v50, v62, vcc
	v_cndmask_b32_e32 v46, v48, v46, vcc
	v_add_f32_e32 v46, v47, v46
	v_cndmask_b32_e32 v47, v64, v52, vcc
	v_mov_b32_e32 v49, v47
	v_pk_add_f32 v[54:55], v[54:55], v[54:55] op_sel:[0,1] op_sel_hi:[1,0]
	s_nop 0
	v_permlane32_swap_b32_e32 v47, v49
	v_cndmask_b32_e32 v48, v52, v64, vcc
	v_cndmask_b32_e32 v47, v49, v47, vcc
	v_add_f32_e32 v47, v48, v47
	v_cndmask_b32_e32 v48, v44, v54, vcc
	v_mov_b32_e32 v49, v48
	v_cndmask_b32_e32 v44, v54, v44, vcc
	s_nop 0
	v_permlane32_swap_b32_e32 v48, v49
	v_cndmask_b32_e32 v48, v49, v48, vcc
	v_add_f32_e32 v44, v44, v48
	v_cndmask_b32_e64 v48, v45, v47, s[2:3]
	v_cndmask_b32_e64 v45, v47, v45, s[2:3]
	v_mov_b32_e32 v47, v48
	s_waitcnt vmcnt(10)
	v_pk_mul_f32 v[50:51], v[42:43], v[104:105]
	v_permlane16_swap_b32_e32 v48, v47
	v_cndmask_b32_e64 v47, v48, v47, s[2:3]
	v_add_f32_e32 v45, v45, v47
	v_cndmask_b32_e64 v47, v46, v44, s[2:3]
	v_cndmask_b32_e64 v44, v44, v46, s[2:3]
	v_mov_b32_e32 v46, v47
	v_pk_mul_f32 v[48:49], v[42:43], v[100:101]
	s_nop 0
	v_permlane16_swap_b32_e32 v47, v46
	v_cndmask_b32_e64 v46, v47, v46, s[2:3]
	v_add_f32_e32 v44, v44, v46
	v_cndmask_b32_e64 v46, v45, v44, s[4:5]
	v_cndmask_b32_e64 v44, v44, v45, s[4:5]
	v_pk_mul_f32 v[52:53], v[42:43], v[108:109]
	v_pk_mul_f32 v[54:55], v[42:43], v[110:111]
	v_add_f32_dpp v44, v46, v44 row_ror:8 row_mask:0xf bank_mask:0xf bound_ctrl:1
	v_pk_mul_f32 v[46:47], v[42:43], v[96:97]
	v_pk_mul_f32 v[60:61], v[42:43], v[112:113]
	v_add_f32_dpp v44, v44, v44 quad_perm:[1,0,3,2] row_mask:0xf bank_mask:0xf bound_ctrl:1
	v_pk_fma_f32 v[46:47], v[40:41], v[86:87], v[46:47]
	v_pk_fma_f32 v[48:49], v[40:41], v[88:89], v[48:49]
	v_add_f32_dpp v44, v44, v44 quad_perm:[2,3,0,1] row_mask:0xf bank_mask:0xf bound_ctrl:1
	v_pk_fma_f32 v[50:51], v[40:41], v[90:91], v[50:51]
	v_pk_fma_f32 v[52:53], v[40:41], v[94:95], v[52:53]
	v_add_f32_dpp v141, v44, v44 row_half_mirror row_mask:0xf bank_mask:0xf bound_ctrl:1
	v_pk_mul_f32 v[44:45], v[42:43], v[92:93]
	v_pk_mul_f32 v[42:43], v[42:43], v[114:115]
	v_pk_fma_f32 v[44:45], v[40:41], v[84:85], v[44:45]
	v_pk_fma_f32 v[54:55], v[40:41], v[98:99], v[54:55]
	v_pk_fma_f32 v[60:61], v[40:41], v[102:103], v[60:61]
	v_pk_fma_f32 v[40:41], v[40:41], v[106:107], v[42:43]
	v_pk_add_f32 v[44:45], v[44:45], v[44:45] op_sel:[0,1] op_sel_hi:[1,0]
	v_pk_add_f32 v[52:53], v[52:53], v[52:53] op_sel:[0,1] op_sel_hi:[1,0]
	v_pk_add_f32 v[40:41], v[40:41], v[40:41] op_sel:[0,1] op_sel_hi:[1,0]
	v_pk_add_f32 v[46:47], v[46:47], v[46:47] op_sel:[0,1] op_sel_hi:[1,0]
	v_cndmask_b32_e32 v41, v52, v44, vcc
	v_mov_b32_e32 v43, v41
	v_pk_add_f32 v[54:55], v[54:55], v[54:55] op_sel:[0,1] op_sel_hi:[1,0]
	s_nop 0
	v_permlane32_swap_b32_e32 v41, v43
	v_cndmask_b32_e32 v42, v44, v52, vcc
	v_cndmask_b32_e32 v41, v43, v41, vcc
	v_add_f32_e32 v41, v42, v41
	v_cndmask_b32_e32 v42, v54, v46, vcc
	v_mov_b32_e32 v44, v42
	v_pk_add_f32 v[48:49], v[48:49], v[48:49] op_sel:[0,1] op_sel_hi:[1,0]
	s_nop 0
	v_permlane32_swap_b32_e32 v42, v44
	v_pk_add_f32 v[60:61], v[60:61], v[60:61] op_sel:[0,1] op_sel_hi:[1,0]
	v_cndmask_b32_e32 v43, v46, v54, vcc
	v_cndmask_b32_e32 v42, v44, v42, vcc
	v_add_f32_e32 v42, v43, v42
	v_cndmask_b32_e32 v43, v60, v48, vcc
	v_mov_b32_e32 v45, v43
	v_pk_add_f32 v[50:51], v[50:51], v[50:51] op_sel:[0,1] op_sel_hi:[1,0]
	s_nop 0
	v_permlane32_swap_b32_e32 v43, v45
	v_cndmask_b32_e32 v44, v48, v60, vcc
	v_cndmask_b32_e32 v43, v45, v43, vcc
	v_add_f32_e32 v43, v44, v43
	v_cndmask_b32_e32 v44, v40, v50, vcc
	v_mov_b32_e32 v45, v44
	v_cndmask_b32_e32 v40, v50, v40, vcc
	s_nop 0
	v_permlane32_swap_b32_e32 v44, v45
	v_cndmask_b32_e32 v44, v45, v44, vcc
	v_add_f32_e32 v40, v40, v44
	v_cndmask_b32_e64 v44, v41, v43, s[2:3]
	v_cndmask_b32_e64 v41, v43, v41, s[2:3]
	v_mov_b32_e32 v43, v44
	s_waitcnt vmcnt(9)
	v_pk_mul_f32 v[46:47], v[38:39], v[104:105]
	v_permlane16_swap_b32_e32 v44, v43
	v_cndmask_b32_e64 v43, v44, v43, s[2:3]
	v_add_f32_e32 v41, v41, v43
	v_cndmask_b32_e64 v43, v42, v40, s[2:3]
	v_cndmask_b32_e64 v40, v40, v42, s[2:3]
	v_mov_b32_e32 v42, v43
	v_pk_mul_f32 v[44:45], v[38:39], v[100:101]
	s_nop 0
	v_permlane16_swap_b32_e32 v43, v42
	v_cndmask_b32_e64 v42, v43, v42, s[2:3]
	v_add_f32_e32 v40, v40, v42
	v_cndmask_b32_e64 v42, v41, v40, s[4:5]
	v_cndmask_b32_e64 v40, v40, v41, s[4:5]
	v_pk_mul_f32 v[48:49], v[38:39], v[108:109]
	v_pk_mul_f32 v[50:51], v[38:39], v[110:111]
	v_add_f32_dpp v40, v42, v40 row_ror:8 row_mask:0xf bank_mask:0xf bound_ctrl:1
	v_pk_mul_f32 v[42:43], v[38:39], v[96:97]
	v_pk_mul_f32 v[52:53], v[38:39], v[112:113]
	v_add_f32_dpp v40, v40, v40 quad_perm:[1,0,3,2] row_mask:0xf bank_mask:0xf bound_ctrl:1
	v_pk_fma_f32 v[42:43], v[36:37], v[86:87], v[42:43]
	v_pk_fma_f32 v[44:45], v[36:37], v[88:89], v[44:45]
	v_add_f32_dpp v40, v40, v40 quad_perm:[2,3,0,1] row_mask:0xf bank_mask:0xf bound_ctrl:1
	v_pk_fma_f32 v[46:47], v[36:37], v[90:91], v[46:47]
	v_pk_fma_f32 v[48:49], v[36:37], v[94:95], v[48:49]
	v_add_f32_dpp v143, v40, v40 row_half_mirror row_mask:0xf bank_mask:0xf bound_ctrl:1
	v_pk_mul_f32 v[40:41], v[38:39], v[92:93]
	v_pk_mul_f32 v[38:39], v[38:39], v[114:115]
	v_pk_fma_f32 v[40:41], v[36:37], v[84:85], v[40:41]
	v_pk_fma_f32 v[50:51], v[36:37], v[98:99], v[50:51]
	v_pk_fma_f32 v[52:53], v[36:37], v[102:103], v[52:53]
	v_pk_fma_f32 v[36:37], v[36:37], v[106:107], v[38:39]
	v_pk_add_f32 v[40:41], v[40:41], v[40:41] op_sel:[0,1] op_sel_hi:[1,0]
	v_pk_add_f32 v[48:49], v[48:49], v[48:49] op_sel:[0,1] op_sel_hi:[1,0]
	v_pk_add_f32 v[36:37], v[36:37], v[36:37] op_sel:[0,1] op_sel_hi:[1,0]
	v_pk_add_f32 v[42:43], v[42:43], v[42:43] op_sel:[0,1] op_sel_hi:[1,0]
	v_cndmask_b32_e32 v37, v48, v40, vcc
	v_mov_b32_e32 v39, v37
	v_pk_add_f32 v[50:51], v[50:51], v[50:51] op_sel:[0,1] op_sel_hi:[1,0]
	s_nop 0
	v_permlane32_swap_b32_e32 v37, v39
	v_cndmask_b32_e32 v38, v40, v48, vcc
	v_cndmask_b32_e32 v37, v39, v37, vcc
	v_add_f32_e32 v37, v38, v37
	v_cndmask_b32_e32 v38, v50, v42, vcc
	v_mov_b32_e32 v40, v38
	v_pk_add_f32 v[44:45], v[44:45], v[44:45] op_sel:[0,1] op_sel_hi:[1,0]
	s_nop 0
	v_permlane32_swap_b32_e32 v38, v40
	v_pk_add_f32 v[52:53], v[52:53], v[52:53] op_sel:[0,1] op_sel_hi:[1,0]
	v_cndmask_b32_e32 v39, v42, v50, vcc
	v_cndmask_b32_e32 v38, v40, v38, vcc
	v_add_f32_e32 v50, v39, v38
	v_cndmask_b32_e32 v38, v52, v44, vcc
	v_mov_b32_e32 v40, v38
	v_pk_add_f32 v[46:47], v[46:47], v[46:47] op_sel:[0,1] op_sel_hi:[1,0]
	s_nop 0
	v_permlane32_swap_b32_e32 v38, v40
	v_cndmask_b32_e32 v39, v44, v52, vcc
	v_cndmask_b32_e32 v38, v40, v38, vcc
	v_add_f32_e32 v38, v39, v38
	v_cndmask_b32_e32 v39, v36, v46, vcc
	v_mov_b32_e32 v40, v39
	v_cndmask_b32_e32 v36, v46, v36, vcc
	s_nop 0
	v_permlane32_swap_b32_e32 v39, v40
	v_cndmask_b32_e32 v39, v40, v39, vcc
	v_add_f32_e32 v51, v36, v39
	v_cndmask_b32_e64 v52, v37, v38, s[2:3]
	v_cndmask_b32_e64 v53, v38, v37, s[2:3]
	s_waitcnt vmcnt(8)
	v_pk_mul_f32 v[36:37], v[34:35], v[92:93]
	v_pk_mul_f32 v[38:39], v[34:35], v[96:97]
	v_pk_mul_f32 v[40:41], v[34:35], v[100:101]
	v_pk_mul_f32 v[42:43], v[34:35], v[104:105]
	v_pk_mul_f32 v[44:45], v[34:35], v[108:109]
	v_pk_mul_f32 v[46:47], v[34:35], v[110:111]
	v_pk_mul_f32 v[48:49], v[34:35], v[112:113]
	v_pk_mul_f32 v[34:35], v[34:35], v[114:115]
	v_pk_fma_f32 v[36:37], v[32:33], v[84:85], v[36:37]
	v_pk_fma_f32 v[38:39], v[32:33], v[86:87], v[38:39]
	v_pk_fma_f32 v[40:41], v[32:33], v[88:89], v[40:41]
	v_pk_fma_f32 v[42:43], v[32:33], v[90:91], v[42:43]
	v_pk_fma_f32 v[44:45], v[32:33], v[94:95], v[44:45]
	v_pk_fma_f32 v[46:47], v[32:33], v[98:99], v[46:47]
	v_pk_fma_f32 v[48:49], v[32:33], v[102:103], v[48:49]
	v_pk_fma_f32 v[32:33], v[32:33], v[106:107], v[34:35]
	v_pk_add_f32 v[36:37], v[36:37], v[36:37] op_sel:[0,1] op_sel_hi:[1,0]
	v_pk_add_f32 v[44:45], v[44:45], v[44:45] op_sel:[0,1] op_sel_hi:[1,0]
	v_pk_add_f32 v[32:33], v[32:33], v[32:33] op_sel:[0,1] op_sel_hi:[1,0]
	v_cndmask_b32_e64 v55, v50, v51, s[2:3]
	v_cndmask_b32_e32 v33, v44, v36, vcc
	v_mov_b32_e32 v54, v52
	v_mov_b32_e32 v60, v55
	v_mov_b32_e32 v35, v33
	v_pk_add_f32 v[38:39], v[38:39], v[38:39] op_sel:[0,1] op_sel_hi:[1,0]
	s_nop 0
	v_permlane32_swap_b32_e32 v33, v35
	v_pk_add_f32 v[46:47], v[46:47], v[46:47] op_sel:[0,1] op_sel_hi:[1,0]
	v_cndmask_b32_e32 v34, v36, v44, vcc
	v_cndmask_b32_e32 v33, v35, v33, vcc
	v_add_f32_e32 v33, v34, v33
	v_cndmask_b32_e32 v34, v46, v38, vcc
	v_mov_b32_e32 v36, v34
	v_pk_add_f32 v[40:41], v[40:41], v[40:41] op_sel:[0,1] op_sel_hi:[1,0]
	s_nop 0
	v_permlane32_swap_b32_e32 v34, v36
	v_pk_add_f32 v[48:49], v[48:49], v[48:49] op_sel:[0,1] op_sel_hi:[1,0]
	v_cndmask_b32_e32 v35, v38, v46, vcc
	v_cndmask_b32_e32 v34, v36, v34, vcc
	v_add_f32_e32 v34, v35, v34
	v_cndmask_b32_e32 v35, v48, v40, vcc
	v_mov_b32_e32 v37, v35
	v_pk_add_f32 v[42:43], v[42:43], v[42:43] op_sel:[0,1] op_sel_hi:[1,0]
	s_nop 0
	v_permlane32_swap_b32_e32 v35, v37
	v_cndmask_b32_e32 v36, v40, v48, vcc
	v_cndmask_b32_e32 v35, v37, v35, vcc
	v_add_f32_e32 v35, v36, v35
	v_cndmask_b32_e32 v36, v32, v42, vcc
	v_mov_b32_e32 v37, v36
	v_cndmask_b32_e32 v32, v42, v32, vcc
	s_nop 0
	v_permlane32_swap_b32_e32 v36, v37
	v_cndmask_b32_e32 v36, v37, v36, vcc
	v_add_f32_e32 v32, v32, v36
	v_cndmask_b32_e64 v36, v33, v35, s[2:3]
	v_cndmask_b32_e64 v38, v34, v32, s[2:3]
	v_mov_b32_e32 v37, v36
	v_mov_b32_e32 v39, v38
	global_load_dwordx4 v[150:153], v[58:59], off nt
	v_permlane16_swap_b32_e32 v36, v37
	v_permlane16_swap_b32_e32 v38, v39
	v_cndmask_b32_e64 v33, v35, v33, s[2:3]
	v_cndmask_b32_e64 v35, v36, v37, s[2:3]
	v_cndmask_b32_e64 v32, v32, v34, s[2:3]
	v_cndmask_b32_e64 v34, v38, v39, s[2:3]
	v_add_f32_e32 v33, v33, v35
	v_add_f32_e32 v32, v32, v34
	v_cndmask_b32_e64 v34, v33, v32, s[4:5]
	v_cndmask_b32_e64 v32, v32, v33, s[4:5]
	v_permlane16_swap_b32_e32 v52, v54
	s_nop 0
	v_add_f32_dpp v32, v34, v32 row_ror:8 row_mask:0xf bank_mask:0xf bound_ctrl:1
	v_cndmask_b32_e64 v40, v52, v54, s[2:3]
	v_permlane16_swap_b32_e32 v55, v60
	v_add_f32_dpp v32, v32, v32 quad_perm:[1,0,3,2] row_mask:0xf bank_mask:0xf bound_ctrl:1
	v_add_f32_e32 v40, v53, v40
	v_cndmask_b32_e64 v41, v51, v50, s[2:3]
	v_add_f32_dpp v32, v32, v32 quad_perm:[2,3,0,1] row_mask:0xf bank_mask:0xf bound_ctrl:1
	v_cndmask_b32_e64 v42, v55, v60, s[2:3]
	v_add_f32_e32 v41, v41, v42
	v_add_f32_dpp v146, v32, v32 row_half_mirror row_mask:0xf bank_mask:0xf bound_ctrl:1
	v_add_co_u32_e64 v32, s[6:7], s43, v116
	v_cndmask_b32_e64 v42, v40, v41, s[4:5]
	s_nop 0
	v_addc_co_u32_e64 v33, s[6:7], 0, v117, s[6:7]
	global_load_dwordx4 v[158:161], v[32:33], off offset:-4096 nt
	global_load_dwordx4 v[162:165], v[32:33], off nt
	v_add_co_u32_e64 v32, s[6:7], s38, v116
	v_cndmask_b32_e64 v40, v41, v40, s[4:5]
	s_nop 0
	v_addc_co_u32_e64 v33, s[6:7], 0, v117, s[6:7]
	global_load_dwordx4 v[80:83], v[32:33], off offset:-4096 nt
	global_load_dwordx4 v[76:79], v[32:33], off nt
	v_add_co_u32_e64 v32, s[6:7], s44, v116
	v_add_f32_dpp v40, v42, v40 row_ror:8 row_mask:0xf bank_mask:0xf bound_ctrl:1
	s_nop 0
	v_addc_co_u32_e64 v33, s[6:7], 0, v117, s[6:7]
	v_add_co_u32_e64 v120, s[6:7], s39, v116
	global_load_dwordx4 v[72:75], v[32:33], off offset:-4096 nt
	global_load_dwordx4 v[68:71], v[32:33], off nt
	v_addc_co_u32_e64 v121, s[6:7], 0, v117, s[6:7]
	v_add_co_u32_e64 v32, s[6:7], s43, v124
	global_load_dwordx4 v[64:67], v[120:121], off offset:-4096 nt
	global_load_dwordx4 v[60:63], v[56:57], off nt
	v_addc_co_u32_e64 v33, s[6:7], 0, v125, s[6:7]
	global_load_dwordx4 v[56:59], v[32:33], off offset:-4096 nt
	global_load_dwordx4 v[52:55], v[32:33], off nt
	v_add_co_u32_e64 v32, s[6:7], s38, v124
	v_add_f32_dpp v40, v40, v40 quad_perm:[1,0,3,2] row_mask:0xf bank_mask:0xf bound_ctrl:1
	s_nop 0
	v_addc_co_u32_e64 v33, s[6:7], 0, v125, s[6:7]
	global_load_dwordx4 v[48:51], v[32:33], off offset:-4096 nt
	global_load_dwordx4 v[44:47], v[32:33], off nt
	v_add_co_u32_e64 v32, s[6:7], s44, v124
	v_add_f32_dpp v40, v40, v40 quad_perm:[2,3,0,1] row_mask:0xf bank_mask:0xf bound_ctrl:1
	s_nop 0
	v_addc_co_u32_e64 v33, s[6:7], 0, v125, s[6:7]
	v_add_co_u32_e64 v126, s[6:7], s39, v124
	v_add_f32_dpp v145, v40, v40 row_half_mirror row_mask:0xf bank_mask:0xf bound_ctrl:1
	s_nop 0
	v_addc_co_u32_e64 v127, s[6:7], 0, v125, s[6:7]
	global_load_dwordx4 v[40:43], v[32:33], off offset:-4096 nt
	global_load_dwordx4 v[36:39], v[32:33], off nt
	v_mul_f32_e32 v134, 0x3d800000, v133
	global_load_dwordx4 v[32:35], v[126:127], off offset:-4096 nt
	v_mul_f32_e32 v136, 0x3d800000, v135
	v_mul_f32_e32 v138, 0x3d800000, v137
	v_mul_f32_e32 v140, 0x3d800000, v139
	v_max_f32_e32 v134, v134, v136
	v_mul_f32_e32 v142, 0x3d800000, v141
	v_mul_f32_e32 v144, 0x3d800000, v143
	v_max3_f32 v134, v134, v138, v140
	s_waitcnt vmcnt(15)
	v_pk_mul_f32 v[118:119], v[152:153], v[92:93]
	v_pk_mul_f32 v[168:169], v[152:153], v[108:109]
	v_pk_fma_f32 v[118:119], v[150:151], v[84:85], v[118:119]
	v_pk_mul_f32 v[122:123], v[152:153], v[96:97]
	v_pk_fma_f32 v[168:169], v[150:151], v[94:95], v[168:169]
	v_pk_add_f32 v[118:119], v[118:119], v[118:119] op_sel:[0,1] op_sel_hi:[1,0]
	v_pk_fma_f32 v[122:123], v[150:151], v[86:87], v[122:123]
	v_pk_add_f32 v[168:169], v[168:169], v[168:169] op_sel:[0,1] op_sel_hi:[1,0]
	v_pk_add_f32 v[122:123], v[122:123], v[122:123] op_sel:[0,1] op_sel_hi:[1,0]
	v_cndmask_b32_e32 v119, v168, v118, vcc
	v_mov_b32_e32 v123, v119
	v_pk_mul_f32 v[170:171], v[152:153], v[110:111]
	v_cndmask_b32_e32 v118, v118, v168, vcc
	v_pk_fma_f32 v[170:171], v[150:151], v[98:99], v[170:171]
	v_permlane32_swap_b32_e32 v119, v123
	v_pk_add_f32 v[170:171], v[170:171], v[170:171] op_sel:[0,1] op_sel_hi:[1,0]
	v_cndmask_b32_e32 v119, v123, v119, vcc
	v_add_f32_e32 v118, v118, v119
	v_cndmask_b32_e32 v119, v170, v122, vcc
	v_mov_b32_e32 v123, v119
	v_pk_mul_f32 v[154:155], v[152:153], v[100:101]
	v_pk_mul_f32 v[172:173], v[152:153], v[112:113]
	v_pk_fma_f32 v[154:155], v[150:151], v[88:89], v[154:155]
	v_pk_fma_f32 v[172:173], v[150:151], v[102:103], v[172:173]
	v_permlane32_swap_b32_e32 v119, v123
	v_pk_add_f32 v[154:155], v[154:155], v[154:155] op_sel:[0,1] op_sel_hi:[1,0]
	v_pk_add_f32 v[172:173], v[172:173], v[172:173] op_sel:[0,1] op_sel_hi:[1,0]
	v_cndmask_b32_e32 v122, v122, v170, vcc
	v_cndmask_b32_e32 v119, v123, v119, vcc
	v_add_f32_e32 v119, v122, v119
	v_cndmask_b32_e32 v122, v172, v154, vcc
	v_mov_b32_e32 v149, v122
	v_pk_mul_f32 v[166:167], v[152:153], v[104:105]
	v_pk_mul_f32 v[152:153], v[152:153], v[114:115]
	v_pk_fma_f32 v[166:167], v[150:151], v[90:91], v[166:167]
	v_pk_fma_f32 v[150:151], v[150:151], v[106:107], v[152:153]
	v_permlane32_swap_b32_e32 v122, v149
	v_pk_add_f32 v[166:167], v[166:167], v[166:167] op_sel:[0,1] op_sel_hi:[1,0]
	v_pk_add_f32 v[150:151], v[150:151], v[150:151] op_sel:[0,1] op_sel_hi:[1,0]
	v_cndmask_b32_e32 v123, v154, v172, vcc
	v_cndmask_b32_e32 v122, v149, v122, vcc
	v_add_f32_e32 v122, v123, v122
	v_cndmask_b32_e32 v123, v150, v166, vcc
	v_cndmask_b32_e32 v149, v166, v150, vcc
	v_mov_b32_e32 v150, v123
	s_waitcnt vmcnt(14)
	v_pk_mul_f32 v[166:167], v[160:161], v[108:109]
	v_permlane32_swap_b32_e32 v123, v150
	v_cndmask_b32_e32 v123, v150, v123, vcc
	v_add_f32_e32 v123, v149, v123
	v_cndmask_b32_e64 v149, v118, v122, s[2:3]
	v_cndmask_b32_e64 v118, v122, v118, s[2:3]
	v_mov_b32_e32 v122, v149
	v_pk_fma_f32 v[166:167], v[158:159], v[94:95], v[166:167]
	s_nop 0
	v_permlane16_swap_b32_e32 v149, v122
	v_cndmask_b32_e64 v122, v149, v122, s[2:3]
	v_add_f32_e32 v118, v118, v122
	v_cndmask_b32_e64 v122, v119, v123, s[2:3]
	v_cndmask_b32_e64 v119, v123, v119, s[2:3]
	v_mov_b32_e32 v123, v122
	v_pk_add_f32 v[166:167], v[166:167], v[166:167] op_sel:[0,1] op_sel_hi:[1,0]
	s_nop 0
	v_permlane16_swap_b32_e32 v122, v123
	v_cndmask_b32_e64 v122, v122, v123, s[2:3]
	v_add_f32_e32 v119, v119, v122
	v_cndmask_b32_e64 v122, v118, v119, s[4:5]
	v_cndmask_b32_e64 v118, v119, v118, s[4:5]
	v_pk_mul_f32 v[168:169], v[160:161], v[110:111]
	v_pk_mul_f32 v[152:153], v[160:161], v[100:101]
	v_add_f32_dpp v118, v122, v118 row_ror:8 row_mask:0xf bank_mask:0xf bound_ctrl:1
	v_pk_mul_f32 v[122:123], v[160:161], v[96:97]
	v_pk_fma_f32 v[168:169], v[158:159], v[98:99], v[168:169]
	v_add_f32_dpp v118, v118, v118 quad_perm:[1,0,3,2] row_mask:0xf bank_mask:0xf bound_ctrl:1
	v_pk_fma_f32 v[122:123], v[158:159], v[86:87], v[122:123]
	v_pk_add_f32 v[168:169], v[168:169], v[168:169] op_sel:[0,1] op_sel_hi:[1,0]
	v_add_f32_dpp v118, v118, v118 quad_perm:[2,3,0,1] row_mask:0xf bank_mask:0xf bound_ctrl:1
	v_pk_add_f32 v[122:123], v[122:123], v[122:123] op_sel:[0,1] op_sel_hi:[1,0]
	v_pk_mul_f32 v[170:171], v[160:161], v[112:113]
	v_add_f32_dpp v149, v118, v118 row_half_mirror row_mask:0xf bank_mask:0xf bound_ctrl:1
	v_pk_mul_f32 v[118:119], v[160:161], v[92:93]
	v_pk_fma_f32 v[152:153], v[158:159], v[88:89], v[152:153]
	v_pk_fma_f32 v[118:119], v[158:159], v[84:85], v[118:119]
	v_pk_fma_f32 v[170:171], v[158:159], v[102:103], v[170:171]
	v_pk_add_f32 v[118:119], v[118:119], v[118:119] op_sel:[0,1] op_sel_hi:[1,0]
	v_pk_add_f32 v[152:153], v[152:153], v[152:153] op_sel:[0,1] op_sel_hi:[1,0]
	v_cndmask_b32_e32 v119, v166, v118, vcc
	v_mov_b32_e32 v123, v119
	v_cndmask_b32_e32 v118, v118, v166, vcc
	s_nop 0
	v_permlane32_swap_b32_e32 v119, v123
	v_cndmask_b32_e32 v119, v123, v119, vcc
	v_add_f32_e32 v118, v118, v119
	v_cndmask_b32_e32 v119, v168, v122, vcc
	v_mov_b32_e32 v123, v119
	v_pk_add_f32 v[170:171], v[170:171], v[170:171] op_sel:[0,1] op_sel_hi:[1,0]
	s_nop 0
	v_permlane32_swap_b32_e32 v119, v123
	v_cndmask_b32_e32 v122, v122, v168, vcc
	v_cndmask_b32_e32 v119, v123, v119, vcc
	v_add_f32_e32 v119, v122, v119
	v_cndmask_b32_e32 v122, v170, v152, vcc
	v_mov_b32_e32 v151, v122
	v_pk_mul_f32 v[154:155], v[160:161], v[104:105]
	v_pk_mul_f32 v[160:161], v[160:161], v[114:115]
	v_pk_fma_f32 v[154:155], v[158:159], v[90:91], v[154:155]
	v_pk_fma_f32 v[158:159], v[158:159], v[106:107], v[160:161]
	v_permlane32_swap_b32_e32 v122, v151
	v_pk_add_f32 v[154:155], v[154:155], v[154:155] op_sel:[0,1] op_sel_hi:[1,0]
	v_pk_add_f32 v[158:159], v[158:159], v[158:159] op_sel:[0,1] op_sel_hi:[1,0]
	v_cndmask_b32_e32 v123, v152, v170, vcc
	v_cndmask_b32_e32 v122, v151, v122, vcc
	v_add_f32_e32 v122, v123, v122
	v_cndmask_b32_e32 v123, v158, v154, vcc
	v_mov_b32_e32 v152, v123
	v_cndmask_b32_e32 v151, v154, v158, vcc
	s_nop 0
	v_permlane32_swap_b32_e32 v123, v152
	v_cndmask_b32_e32 v123, v152, v123, vcc
	v_add_f32_e32 v123, v151, v123
	v_cndmask_b32_e64 v151, v118, v122, s[2:3]
	v_cndmask_b32_e64 v118, v122, v118, s[2:3]
	v_mov_b32_e32 v122, v151
	s_waitcnt vmcnt(13)
	v_pk_mul_f32 v[160:161], v[164:165], v[108:109]
	v_permlane16_swap_b32_e32 v151, v122
	v_cndmask_b32_e64 v122, v151, v122, s[2:3]
	v_add_f32_e32 v118, v118, v122
	v_cndmask_b32_e64 v122, v119, v123, s[2:3]
	v_cndmask_b32_e64 v119, v123, v119, s[2:3]
	v_mov_b32_e32 v123, v122
	v_pk_fma_f32 v[160:161], v[162:163], v[94:95], v[160:161]
	s_nop 0
	v_permlane16_swap_b32_e32 v122, v123
	v_cndmask_b32_e64 v122, v122, v123, s[2:3]
	v_add_f32_e32 v119, v119, v122
	v_cndmask_b32_e64 v122, v118, v119, s[4:5]
	v_cndmask_b32_e64 v118, v119, v118, s[4:5]
	v_pk_add_f32 v[160:161], v[160:161], v[160:161] op_sel:[0,1] op_sel_hi:[1,0]
	v_pk_mul_f32 v[166:167], v[164:165], v[110:111]
	v_add_f32_dpp v118, v122, v118 row_ror:8 row_mask:0xf bank_mask:0xf bound_ctrl:1
	v_pk_mul_f32 v[122:123], v[164:165], v[96:97]
	v_pk_fma_f32 v[166:167], v[162:163], v[98:99], v[166:167]
	v_add_f32_dpp v118, v118, v118 quad_perm:[1,0,3,2] row_mask:0xf bank_mask:0xf bound_ctrl:1
	v_pk_fma_f32 v[122:123], v[162:163], v[86:87], v[122:123]
	v_pk_add_f32 v[166:167], v[166:167], v[166:167] op_sel:[0,1] op_sel_hi:[1,0]
	v_add_f32_dpp v118, v118, v118 quad_perm:[2,3,0,1] row_mask:0xf bank_mask:0xf bound_ctrl:1
	v_pk_add_f32 v[122:123], v[122:123], v[122:123] op_sel:[0,1] op_sel_hi:[1,0]
	v_pk_mul_f32 v[154:155], v[164:165], v[100:101]
	v_add_f32_dpp v151, v118, v118 row_half_mirror row_mask:0xf bank_mask:0xf bound_ctrl:1
	v_pk_mul_f32 v[118:119], v[164:165], v[92:93]
	v_pk_mul_f32 v[168:169], v[164:165], v[112:113]
	v_pk_fma_f32 v[118:119], v[162:163], v[84:85], v[118:119]
	v_pk_fma_f32 v[154:155], v[162:163], v[88:89], v[154:155]
	v_pk_add_f32 v[118:119], v[118:119], v[118:119] op_sel:[0,1] op_sel_hi:[1,0]
	v_pk_fma_f32 v[168:169], v[162:163], v[102:103], v[168:169]
	v_cndmask_b32_e32 v119, v160, v118, vcc
	v_mov_b32_e32 v123, v119
	v_cndmask_b32_e32 v118, v118, v160, vcc
	s_nop 0
	v_permlane32_swap_b32_e32 v119, v123
	v_cndmask_b32_e32 v119, v123, v119, vcc
	v_add_f32_e32 v118, v118, v119
	v_cndmask_b32_e32 v119, v166, v122, vcc
	v_mov_b32_e32 v123, v119
	v_pk_add_f32 v[154:155], v[154:155], v[154:155] op_sel:[0,1] op_sel_hi:[1,0]
	s_nop 0
	v_permlane32_swap_b32_e32 v119, v123
	v_pk_add_f32 v[168:169], v[168:169], v[168:169] op_sel:[0,1] op_sel_hi:[1,0]
	v_cndmask_b32_e32 v122, v122, v166, vcc
	v_cndmask_b32_e32 v119, v123, v119, vcc
	v_add_f32_e32 v119, v122, v119
	v_cndmask_b32_e32 v122, v168, v154, vcc
	v_mov_b32_e32 v153, v122
	v_pk_mul_f32 v[158:159], v[164:165], v[104:105]
	v_pk_mul_f32 v[164:165], v[164:165], v[114:115]
	v_pk_fma_f32 v[158:159], v[162:163], v[90:91], v[158:159]
	v_pk_fma_f32 v[162:163], v[162:163], v[106:107], v[164:165]
	v_permlane32_swap_b32_e32 v122, v153
	v_pk_add_f32 v[158:159], v[158:159], v[158:159] op_sel:[0,1] op_sel_hi:[1,0]
	v_pk_add_f32 v[162:163], v[162:163], v[162:163] op_sel:[0,1] op_sel_hi:[1,0]
	v_cndmask_b32_e32 v123, v154, v168, vcc
	v_cndmask_b32_e32 v122, v153, v122, vcc
	v_add_f32_e32 v122, v123, v122
	v_cndmask_b32_e32 v123, v162, v158, vcc
	v_mov_b32_e32 v154, v123
	v_cndmask_b32_e32 v153, v158, v162, vcc
	s_nop 0
	v_permlane32_swap_b32_e32 v123, v154
	v_cndmask_b32_e32 v123, v154, v123, vcc
	v_add_f32_e32 v123, v153, v123
	v_cndmask_b32_e64 v153, v118, v122, s[2:3]
	v_cndmask_b32_e64 v118, v122, v118, s[2:3]
	v_mov_b32_e32 v122, v153
	s_waitcnt vmcnt(12)
	v_pk_mul_f32 v[158:159], v[82:83], v[100:101]
	v_permlane16_swap_b32_e32 v153, v122
	v_cndmask_b32_e64 v122, v153, v122, s[2:3]
	v_add_f32_e32 v118, v118, v122
	v_cndmask_b32_e64 v122, v119, v123, s[2:3]
	v_cndmask_b32_e64 v119, v123, v119, s[2:3]
	v_mov_b32_e32 v123, v122
	v_pk_mul_f32 v[160:161], v[82:83], v[104:105]
	s_nop 0
	v_permlane16_swap_b32_e32 v122, v123
	v_cndmask_b32_e64 v122, v122, v123, s[2:3]
	v_add_f32_e32 v119, v119, v122
	v_cndmask_b32_e64 v122, v118, v119, s[4:5]
	v_cndmask_b32_e64 v118, v119, v118, s[4:5]
	v_pk_mul_f32 v[162:163], v[82:83], v[108:109]
	v_pk_mul_f32 v[164:165], v[82:83], v[110:111]
	v_add_f32_dpp v118, v122, v118 row_ror:8 row_mask:0xf bank_mask:0xf bound_ctrl:1
	v_pk_mul_f32 v[122:123], v[82:83], v[96:97]
	v_pk_mul_f32 v[166:167], v[82:83], v[112:113]
	v_add_f32_dpp v118, v118, v118 quad_perm:[1,0,3,2] row_mask:0xf bank_mask:0xf bound_ctrl:1
	v_pk_fma_f32 v[122:123], v[80:81], v[86:87], v[122:123]
	v_pk_fma_f32 v[158:159], v[80:81], v[88:89], v[158:159]
	v_add_f32_dpp v118, v118, v118 quad_perm:[2,3,0,1] row_mask:0xf bank_mask:0xf bound_ctrl:1
	v_pk_fma_f32 v[160:161], v[80:81], v[90:91], v[160:161]
	v_pk_fma_f32 v[162:163], v[80:81], v[94:95], v[162:163]
	v_add_f32_dpp v153, v118, v118 row_half_mirror row_mask:0xf bank_mask:0xf bound_ctrl:1
	v_pk_mul_f32 v[118:119], v[82:83], v[92:93]
	v_pk_mul_f32 v[82:83], v[82:83], v[114:115]
	v_pk_fma_f32 v[118:119], v[80:81], v[84:85], v[118:119]
	v_pk_fma_f32 v[164:165], v[80:81], v[98:99], v[164:165]
	v_pk_fma_f32 v[166:167], v[80:81], v[102:103], v[166:167]
	v_pk_fma_f32 v[80:81], v[80:81], v[106:107], v[82:83]
	v_pk_add_f32 v[118:119], v[118:119], v[118:119] op_sel:[0,1] op_sel_hi:[1,0]
	v_pk_add_f32 v[162:163], v[162:163], v[162:163] op_sel:[0,1] op_sel_hi:[1,0]
	v_pk_add_f32 v[80:81], v[80:81], v[80:81] op_sel:[0,1] op_sel_hi:[1,0]
	v_pk_add_f32 v[122:123], v[122:123], v[122:123] op_sel:[0,1] op_sel_hi:[1,0]
	v_cndmask_b32_e32 v81, v162, v118, vcc
	v_mov_b32_e32 v83, v81
	v_pk_add_f32 v[164:165], v[164:165], v[164:165] op_sel:[0,1] op_sel_hi:[1,0]
	s_nop 0
	v_permlane32_swap_b32_e32 v81, v83
	v_cndmask_b32_e32 v82, v118, v162, vcc
	v_cndmask_b32_e32 v81, v83, v81, vcc
	v_add_f32_e32 v81, v82, v81
	v_cndmask_b32_e32 v82, v164, v122, vcc
	v_mov_b32_e32 v118, v82
	v_pk_add_f32 v[158:159], v[158:159], v[158:159] op_sel:[0,1] op_sel_hi:[1,0]
	s_nop 0
	v_permlane32_swap_b32_e32 v82, v118
	v_pk_add_f32 v[166:167], v[166:167], v[166:167] op_sel:[0,1] op_sel_hi:[1,0]
	v_cndmask_b32_e32 v83, v122, v164, vcc
	v_cndmask_b32_e32 v82, v118, v82, vcc
	v_add_f32_e32 v82, v83, v82
	v_cndmask_b32_e32 v83, v166, v158, vcc
	v_mov_b32_e32 v119, v83
	v_pk_add_f32 v[160:161], v[160:161], v[160:161] op_sel:[0,1] op_sel_hi:[1,0]
	s_nop 0
	v_permlane32_swap_b32_e32 v83, v119
	v_cndmask_b32_e32 v118, v158, v166, vcc
	v_cndmask_b32_e32 v83, v119, v83, vcc
	v_add_f32_e32 v83, v118, v83
	v_cndmask_b32_e32 v118, v80, v160, vcc
	v_mov_b32_e32 v119, v118
	v_cndmask_b32_e32 v80, v160, v80, vcc
	s_nop 0
	v_permlane32_swap_b32_e32 v118, v119
	v_cndmask_b32_e32 v118, v119, v118, vcc
	v_add_f32_e32 v80, v80, v118
	v_cndmask_b32_e64 v118, v81, v83, s[2:3]
	v_cndmask_b32_e64 v81, v83, v81, s[2:3]
	v_mov_b32_e32 v83, v118
	s_waitcnt vmcnt(11)
	v_pk_mul_f32 v[122:123], v[78:79], v[104:105]
	v_permlane16_swap_b32_e32 v118, v83
	v_cndmask_b32_e64 v83, v118, v83, s[2:3]
	v_add_f32_e32 v81, v81, v83
	v_cndmask_b32_e64 v83, v82, v80, s[2:3]
	v_cndmask_b32_e64 v80, v80, v82, s[2:3]
	v_mov_b32_e32 v82, v83
	v_pk_mul_f32 v[118:119], v[78:79], v[100:101]
	s_nop 0
	v_permlane16_swap_b32_e32 v83, v82
	v_cndmask_b32_e64 v82, v83, v82, s[2:3]
	v_add_f32_e32 v80, v80, v82
	v_cndmask_b32_e64 v82, v81, v80, s[4:5]
	v_cndmask_b32_e64 v80, v80, v81, s[4:5]
	v_pk_mul_f32 v[158:159], v[78:79], v[108:109]
	v_pk_mul_f32 v[160:161], v[78:79], v[110:111]
	v_add_f32_dpp v80, v82, v80 row_ror:8 row_mask:0xf bank_mask:0xf bound_ctrl:1
	v_pk_mul_f32 v[82:83], v[78:79], v[96:97]
	v_pk_mul_f32 v[162:163], v[78:79], v[112:113]
	v_add_f32_dpp v80, v80, v80 quad_perm:[1,0,3,2] row_mask:0xf bank_mask:0xf bound_ctrl:1
	v_pk_fma_f32 v[82:83], v[76:77], v[86:87], v[82:83]
	v_pk_fma_f32 v[118:119], v[76:77], v[88:89], v[118:119]
	v_add_f32_dpp v80, v80, v80 quad_perm:[2,3,0,1] row_mask:0xf bank_mask:0xf bound_ctrl:1
	v_pk_fma_f32 v[122:123], v[76:77], v[90:91], v[122:123]
	v_pk_fma_f32 v[158:159], v[76:77], v[94:95], v[158:159]
	v_add_f32_dpp v155, v80, v80 row_half_mirror row_mask:0xf bank_mask:0xf bound_ctrl:1
	v_pk_mul_f32 v[80:81], v[78:79], v[92:93]
	v_pk_mul_f32 v[78:79], v[78:79], v[114:115]
	v_pk_fma_f32 v[80:81], v[76:77], v[84:85], v[80:81]
	v_pk_fma_f32 v[160:161], v[76:77], v[98:99], v[160:161]
	v_pk_fma_f32 v[162:163], v[76:77], v[102:103], v[162:163]
	v_pk_fma_f32 v[76:77], v[76:77], v[106:107], v[78:79]
	v_pk_add_f32 v[80:81], v[80:81], v[80:81] op_sel:[0,1] op_sel_hi:[1,0]
	v_pk_add_f32 v[158:159], v[158:159], v[158:159] op_sel:[0,1] op_sel_hi:[1,0]
	v_pk_add_f32 v[76:77], v[76:77], v[76:77] op_sel:[0,1] op_sel_hi:[1,0]
	v_pk_add_f32 v[82:83], v[82:83], v[82:83] op_sel:[0,1] op_sel_hi:[1,0]
	v_cndmask_b32_e32 v77, v158, v80, vcc
	v_mov_b32_e32 v79, v77
	v_pk_add_f32 v[160:161], v[160:161], v[160:161] op_sel:[0,1] op_sel_hi:[1,0]
	s_nop 0
	v_permlane32_swap_b32_e32 v77, v79
	v_cndmask_b32_e32 v78, v80, v158, vcc
	v_cndmask_b32_e32 v77, v79, v77, vcc
	v_add_f32_e32 v77, v78, v77
	v_cndmask_b32_e32 v78, v160, v82, vcc
	v_mov_b32_e32 v80, v78
	v_pk_add_f32 v[118:119], v[118:119], v[118:119] op_sel:[0,1] op_sel_hi:[1,0]
	s_nop 0
	v_permlane32_swap_b32_e32 v78, v80
	v_pk_add_f32 v[162:163], v[162:163], v[162:163] op_sel:[0,1] op_sel_hi:[1,0]
	v_cndmask_b32_e32 v79, v82, v160, vcc
	v_cndmask_b32_e32 v78, v80, v78, vcc
	v_add_f32_e32 v78, v79, v78
	v_cndmask_b32_e32 v79, v162, v118, vcc
	v_mov_b32_e32 v81, v79
	v_pk_add_f32 v[122:123], v[122:123], v[122:123] op_sel:[0,1] op_sel_hi:[1,0]
	s_nop 0
	v_permlane32_swap_b32_e32 v79, v81
	v_cndmask_b32_e32 v80, v118, v162, vcc
	v_cndmask_b32_e32 v79, v81, v79, vcc
	v_add_f32_e32 v79, v80, v79
	v_cndmask_b32_e32 v80, v76, v122, vcc
	v_mov_b32_e32 v81, v80
	v_cndmask_b32_e32 v76, v122, v76, vcc
	s_nop 0
	v_permlane32_swap_b32_e32 v80, v81
	v_cndmask_b32_e32 v80, v81, v80, vcc
	v_add_f32_e32 v76, v76, v80
	v_cndmask_b32_e64 v80, v77, v79, s[2:3]
	v_cndmask_b32_e64 v77, v79, v77, s[2:3]
	v_mov_b32_e32 v79, v80
	s_waitcnt vmcnt(10)
	v_pk_mul_f32 v[82:83], v[74:75], v[104:105]
	v_permlane16_swap_b32_e32 v80, v79
	v_cndmask_b32_e64 v79, v80, v79, s[2:3]
	v_add_f32_e32 v77, v77, v79
	v_cndmask_b32_e64 v79, v78, v76, s[2:3]
	v_cndmask_b32_e64 v76, v76, v78, s[2:3]
	v_mov_b32_e32 v78, v79
	v_pk_mul_f32 v[80:81], v[74:75], v[100:101]
	s_nop 0
	v_permlane16_swap_b32_e32 v79, v78
	v_cndmask_b32_e64 v78, v79, v78, s[2:3]
	v_add_f32_e32 v76, v76, v78
	v_cndmask_b32_e64 v78, v77, v76, s[4:5]
	v_cndmask_b32_e64 v76, v76, v77, s[4:5]
	v_pk_mul_f32 v[118:119], v[74:75], v[108:109]
	v_pk_mul_f32 v[122:123], v[74:75], v[110:111]
	v_add_f32_dpp v76, v78, v76 row_ror:8 row_mask:0xf bank_mask:0xf bound_ctrl:1
	v_pk_mul_f32 v[78:79], v[74:75], v[96:97]
	v_pk_mul_f32 v[160:161], v[74:75], v[112:113]
	v_add_f32_dpp v76, v76, v76 quad_perm:[1,0,3,2] row_mask:0xf bank_mask:0xf bound_ctrl:1
	v_pk_fma_f32 v[78:79], v[72:73], v[86:87], v[78:79]
	v_pk_fma_f32 v[80:81], v[72:73], v[88:89], v[80:81]
	v_add_f32_dpp v76, v76, v76 quad_perm:[2,3,0,1] row_mask:0xf bank_mask:0xf bound_ctrl:1
	v_pk_fma_f32 v[82:83], v[72:73], v[90:91], v[82:83]
	v_pk_fma_f32 v[118:119], v[72:73], v[94:95], v[118:119]
	v_add_f32_dpp v158, v76, v76 row_half_mirror row_mask:0xf bank_mask:0xf bound_ctrl:1
	v_pk_mul_f32 v[76:77], v[74:75], v[92:93]
	v_pk_mul_f32 v[74:75], v[74:75], v[114:115]
	v_pk_fma_f32 v[76:77], v[72:73], v[84:85], v[76:77]
	v_pk_fma_f32 v[122:123], v[72:73], v[98:99], v[122:123]
	v_pk_fma_f32 v[160:161], v[72:73], v[102:103], v[160:161]
	v_pk_fma_f32 v[72:73], v[72:73], v[106:107], v[74:75]
	v_pk_add_f32 v[76:77], v[76:77], v[76:77] op_sel:[0,1] op_sel_hi:[1,0]
	v_pk_add_f32 v[118:119], v[118:119], v[118:119] op_sel:[0,1] op_sel_hi:[1,0]
	v_pk_add_f32 v[72:73], v[72:73], v[72:73] op_sel:[0,1] op_sel_hi:[1,0]
	v_pk_add_f32 v[78:79], v[78:79], v[78:79] op_sel:[0,1] op_sel_hi:[1,0]
	v_cndmask_b32_e32 v73, v118, v76, vcc
	v_mov_b32_e32 v75, v73
	v_pk_add_f32 v[122:123], v[122:123], v[122:123] op_sel:[0,1] op_sel_hi:[1,0]
	s_nop 0
	v_permlane32_swap_b32_e32 v73, v75
	v_cndmask_b32_e32 v74, v76, v118, vcc
	v_cndmask_b32_e32 v73, v75, v73, vcc
	v_add_f32_e32 v73, v74, v73
	v_cndmask_b32_e32 v74, v122, v78, vcc
	v_mov_b32_e32 v76, v74
	v_pk_add_f32 v[80:81], v[80:81], v[80:81] op_sel:[0,1] op_sel_hi:[1,0]
	s_nop 0
	v_permlane32_swap_b32_e32 v74, v76
	v_pk_add_f32 v[160:161], v[160:161], v[160:161] op_sel:[0,1] op_sel_hi:[1,0]
	v_cndmask_b32_e32 v75, v78, v122, vcc
	v_cndmask_b32_e32 v74, v76, v74, vcc
	v_add_f32_e32 v161, v75, v74
	v_cndmask_b32_e32 v74, v160, v80, vcc
	v_mov_b32_e32 v76, v74
	v_pk_add_f32 v[82:83], v[82:83], v[82:83] op_sel:[0,1] op_sel_hi:[1,0]
	s_nop 0
	v_permlane32_swap_b32_e32 v74, v76
	v_cndmask_b32_e32 v75, v80, v160, vcc
	v_cndmask_b32_e32 v74, v76, v74, vcc
	v_add_f32_e32 v74, v75, v74
	v_cndmask_b32_e32 v75, v72, v82, vcc
	v_mov_b32_e32 v76, v75
	v_cndmask_b32_e32 v72, v82, v72, vcc
	s_nop 0
	v_permlane32_swap_b32_e32 v75, v76
	v_cndmask_b32_e32 v75, v76, v75, vcc
	v_add_f32_e32 v160, v72, v75
	v_cndmask_b32_e64 v162, v73, v74, s[2:3]
	v_cndmask_b32_e64 v163, v74, v73, s[2:3]
	s_waitcnt vmcnt(9)
	v_pk_mul_f32 v[72:73], v[70:71], v[92:93]
	v_pk_mul_f32 v[74:75], v[70:71], v[96:97]
	v_pk_mul_f32 v[76:77], v[70:71], v[100:101]
	v_pk_mul_f32 v[78:79], v[70:71], v[104:105]
	v_pk_mul_f32 v[80:81], v[70:71], v[108:109]
	v_pk_mul_f32 v[82:83], v[70:71], v[110:111]
	v_pk_mul_f32 v[118:119], v[70:71], v[112:113]
	v_pk_mul_f32 v[70:71], v[70:71], v[114:115]
	v_pk_fma_f32 v[72:73], v[68:69], v[84:85], v[72:73]
	v_pk_fma_f32 v[74:75], v[68:69], v[86:87], v[74:75]
	v_pk_fma_f32 v[76:77], v[68:69], v[88:89], v[76:77]
	v_pk_fma_f32 v[78:79], v[68:69], v[90:91], v[78:79]
	v_pk_fma_f32 v[80:81], v[68:69], v[94:95], v[80:81]
	v_pk_fma_f32 v[82:83], v[68:69], v[98:99], v[82:83]
	v_pk_fma_f32 v[118:119], v[68:69], v[102:103], v[118:119]
	v_pk_fma_f32 v[68:69], v[68:69], v[106:107], v[70:71]
	v_pk_add_f32 v[72:73], v[72:73], v[72:73] op_sel:[0,1] op_sel_hi:[1,0]
	v_pk_add_f32 v[80:81], v[80:81], v[80:81] op_sel:[0,1] op_sel_hi:[1,0]
	v_pk_add_f32 v[68:69], v[68:69], v[68:69] op_sel:[0,1] op_sel_hi:[1,0]
	v_cndmask_b32_e64 v165, v161, v160, s[2:3]
	v_cndmask_b32_e32 v69, v80, v72, vcc
	v_mov_b32_e32 v164, v162
	v_mov_b32_e32 v166, v165
	v_mov_b32_e32 v71, v69
	v_pk_add_f32 v[74:75], v[74:75], v[74:75] op_sel:[0,1] op_sel_hi:[1,0]
	s_nop 0
	v_permlane32_swap_b32_e32 v69, v71
	v_pk_add_f32 v[82:83], v[82:83], v[82:83] op_sel:[0,1] op_sel_hi:[1,0]
	v_cndmask_b32_e32 v70, v72, v80, vcc
	v_cndmask_b32_e32 v69, v71, v69, vcc
	v_add_f32_e32 v83, v70, v69
	v_cndmask_b32_e32 v69, v82, v74, vcc
	v_mov_b32_e32 v71, v69
	v_pk_add_f32 v[76:77], v[76:77], v[76:77] op_sel:[0,1] op_sel_hi:[1,0]
	s_nop 0
	v_permlane32_swap_b32_e32 v69, v71
	v_pk_add_f32 v[118:119], v[118:119], v[118:119] op_sel:[0,1] op_sel_hi:[1,0]
	v_cndmask_b32_e32 v70, v74, v82, vcc
	v_cndmask_b32_e32 v69, v71, v69, vcc
	v_add_f32_e32 v82, v70, v69
	v_cndmask_b32_e32 v69, v118, v76, vcc
	v_mov_b32_e32 v71, v69
	v_pk_add_f32 v[78:79], v[78:79], v[78:79] op_sel:[0,1] op_sel_hi:[1,0]
	s_nop 0
	v_permlane32_swap_b32_e32 v69, v71
	v_cndmask_b32_e32 v70, v76, v118, vcc
	v_cndmask_b32_e32 v69, v71, v69, vcc
	v_add_f32_e32 v167, v70, v69
	v_cndmask_b32_e32 v69, v68, v78, vcc
	v_mov_b32_e32 v70, v69
	v_cndmask_b32_e32 v68, v78, v68, vcc
	s_nop 0
	v_permlane32_swap_b32_e32 v69, v70
	v_cndmask_b32_e32 v69, v70, v69, vcc
	v_add_f32_e32 v168, v68, v69
	s_waitcnt vmcnt(8)
	v_pk_mul_f32 v[68:69], v[66:67], v[92:93]
	v_pk_mul_f32 v[70:71], v[66:67], v[96:97]
	v_pk_mul_f32 v[72:73], v[66:67], v[100:101]
	v_pk_mul_f32 v[74:75], v[66:67], v[104:105]
	v_pk_mul_f32 v[76:77], v[66:67], v[108:109]
	v_pk_mul_f32 v[78:79], v[66:67], v[110:111]
	v_pk_mul_f32 v[80:81], v[66:67], v[112:113]
	v_pk_mul_f32 v[66:67], v[66:67], v[114:115]
	v_pk_fma_f32 v[68:69], v[64:65], v[84:85], v[68:69]
	v_pk_fma_f32 v[70:71], v[64:65], v[86:87], v[70:71]
	v_pk_fma_f32 v[72:73], v[64:65], v[88:89], v[72:73]
	v_pk_fma_f32 v[74:75], v[64:65], v[90:91], v[74:75]
	v_pk_fma_f32 v[76:77], v[64:65], v[94:95], v[76:77]
	v_pk_fma_f32 v[78:79], v[64:65], v[98:99], v[78:79]
	v_pk_fma_f32 v[80:81], v[64:65], v[102:103], v[80:81]
	v_pk_fma_f32 v[64:65], v[64:65], v[106:107], v[66:67]
	v_pk_add_f32 v[68:69], v[68:69], v[68:69] op_sel:[0,1] op_sel_hi:[1,0]
	v_pk_add_f32 v[76:77], v[76:77], v[76:77] op_sel:[0,1] op_sel_hi:[1,0]
	v_pk_add_f32 v[64:65], v[64:65], v[64:65] op_sel:[0,1] op_sel_hi:[1,0]
	v_cndmask_b32_e64 v169, v83, v167, s[2:3]
	v_cndmask_b32_e64 v171, v82, v168, s[2:3]
	v_cndmask_b32_e32 v65, v76, v68, vcc
	v_mov_b32_e32 v170, v169
	v_mov_b32_e32 v172, v171
	v_mov_b32_e32 v67, v65
	v_pk_add_f32 v[70:71], v[70:71], v[70:71] op_sel:[0,1] op_sel_hi:[1,0]
	s_nop 0
	v_permlane32_swap_b32_e32 v65, v67
	v_pk_add_f32 v[78:79], v[78:79], v[78:79] op_sel:[0,1] op_sel_hi:[1,0]
	v_cndmask_b32_e32 v66, v68, v76, vcc
	v_cndmask_b32_e32 v65, v67, v65, vcc
	v_add_f32_e32 v68, v66, v65
	v_cndmask_b32_e32 v65, v78, v70, vcc
	v_mov_b32_e32 v67, v65
	v_pk_add_f32 v[72:73], v[72:73], v[72:73] op_sel:[0,1] op_sel_hi:[1,0]
	s_nop 0
	v_permlane32_swap_b32_e32 v65, v67
	v_pk_add_f32 v[80:81], v[80:81], v[80:81] op_sel:[0,1] op_sel_hi:[1,0]
	v_cndmask_b32_e32 v66, v70, v78, vcc
	v_cndmask_b32_e32 v65, v67, v65, vcc
	v_add_f32_e32 v69, v66, v65
	v_cndmask_b32_e32 v65, v80, v72, vcc
	v_mov_b32_e32 v67, v65
	v_pk_add_f32 v[74:75], v[74:75], v[74:75] op_sel:[0,1] op_sel_hi:[1,0]
	s_nop 0
	v_permlane32_swap_b32_e32 v65, v67
	v_cndmask_b32_e32 v66, v72, v80, vcc
	v_cndmask_b32_e32 v65, v67, v65, vcc
	v_add_f32_e32 v70, v66, v65
	v_cndmask_b32_e32 v65, v64, v74, vcc
	v_mov_b32_e32 v66, v65
	v_cndmask_b32_e32 v64, v74, v64, vcc
	s_nop 0
	v_permlane32_swap_b32_e32 v65, v66
	v_cndmask_b32_e32 v65, v66, v65, vcc
	v_add_f32_e32 v71, v64, v65
	v_cndmask_b32_e64 v72, v68, v70, s[2:3]
	v_cndmask_b32_e64 v74, v69, v71, s[2:3]
	v_add_co_u32_e64 v118, s[6:7], s41, v116
	v_mov_b32_e32 v73, v72
	v_mov_b32_e32 v75, v74
	v_addc_co_u32_e64 v119, s[6:7], 0, v117, s[6:7]
	global_load_dwordx4 v[64:67], v[118:119], off offset:-4096 nt
	s_nop 0
	global_load_dwordx4 v[120:123], v[120:121], off nt
	v_permlane16_swap_b32_e32 v162, v164
	v_permlane16_swap_b32_e32 v165, v166
	v_cndmask_b32_e64 v76, v162, v164, s[2:3]
	v_cndmask_b32_e64 v77, v160, v161, s[2:3]
	v_cndmask_b32_e64 v78, v165, v166, s[2:3]
	v_add_f32_e32 v76, v163, v76
	v_add_f32_e32 v77, v77, v78
	v_permlane16_swap_b32_e32 v72, v73
	v_cndmask_b32_e64 v78, v76, v77, s[4:5]
	v_cndmask_b32_e64 v76, v77, v76, s[4:5]
	v_cndmask_b32_e64 v68, v70, v68, s[2:3]
	v_cndmask_b32_e64 v70, v72, v73, s[2:3]
	v_permlane16_swap_b32_e32 v74, v75
	v_add_f32_dpp v76, v78, v76 row_ror:8 row_mask:0xf bank_mask:0xf bound_ctrl:1
	v_add_f32_e32 v68, v68, v70
	v_cndmask_b32_e64 v69, v71, v69, s[2:3]
	v_cndmask_b32_e64 v70, v74, v75, s[2:3]
	v_add_f32_dpp v76, v76, v76 quad_perm:[1,0,3,2] row_mask:0xf bank_mask:0xf bound_ctrl:1
	v_add_f32_e32 v69, v69, v70
	v_permlane16_swap_b32_e32 v169, v170
	v_add_f32_dpp v76, v76, v76 quad_perm:[2,3,0,1] row_mask:0xf bank_mask:0xf bound_ctrl:1
	v_cndmask_b32_e64 v70, v68, v69, s[4:5]
	v_cndmask_b32_e64 v68, v69, v68, s[4:5]
	v_add_f32_dpp v160, v76, v76 row_half_mirror row_mask:0xf bank_mask:0xf bound_ctrl:1
	v_cndmask_b32_e64 v76, v167, v83, s[2:3]
	v_cndmask_b32_e64 v77, v169, v170, s[2:3]
	v_permlane16_swap_b32_e32 v171, v172
	v_add_f32_dpp v68, v70, v68 row_ror:8 row_mask:0xf bank_mask:0xf bound_ctrl:1
	v_add_f32_e32 v76, v76, v77
	v_cndmask_b32_e64 v77, v168, v82, s[2:3]
	v_cndmask_b32_e64 v78, v171, v172, s[2:3]
	v_add_f32_dpp v68, v68, v68 quad_perm:[1,0,3,2] row_mask:0xf bank_mask:0xf bound_ctrl:1
	v_add_f32_e32 v77, v77, v78
	v_cndmask_b32_e64 v78, v76, v77, s[4:5]
	v_add_f32_dpp v68, v68, v68 quad_perm:[2,3,0,1] row_mask:0xf bank_mask:0xf bound_ctrl:1
	v_cndmask_b32_e64 v76, v77, v76, s[4:5]
	v_mul_f32_e32 v147, 0x3d800000, v145
	v_add_f32_dpp v162, v68, v68 row_half_mirror row_mask:0xf bank_mask:0xf bound_ctrl:1
	v_add_co_u32_e64 v68, s[6:7], s46, v116
	v_add_f32_dpp v76, v78, v76 row_ror:8 row_mask:0xf bank_mask:0xf bound_ctrl:1
	s_nop 0
	v_addc_co_u32_e64 v69, s[6:7], 0, v117, s[6:7]
	v_add_f32_dpp v76, v76, v76 quad_perm:[1,0,3,2] row_mask:0xf bank_mask:0xf bound_ctrl:1
	v_add_co_u32_e64 v72, s[6:7], s0, v116
	s_nop 0
	v_add_f32_dpp v76, v76, v76 quad_perm:[2,3,0,1] row_mask:0xf bank_mask:0xf bound_ctrl:1
	v_addc_co_u32_e64 v73, s[6:7], 0, v117, s[6:7]
	s_nop 0
	v_add_f32_dpp v161, v76, v76 row_half_mirror row_mask:0xf bank_mask:0xf bound_ctrl:1
	v_add_co_u32_e64 v76, s[6:7], s40, v116
	s_mov_b32 s0, 0x13000
	s_nop 0
	v_addc_co_u32_e64 v77, s[6:7], 0, v117, s[6:7]
	v_add_co_u32_e64 v80, s[6:7], s0, v116
	s_mov_b32 s0, 0x11000
	s_nop 0
	v_addc_co_u32_e64 v81, s[6:7], 0, v117, s[6:7]
	v_add_co_u32_e64 v78, s[6:7], s47, v116
	global_load_dwordx4 v[68:71], v[68:69], off nt
	s_nop 0
	global_load_dwordx4 v[72:75], v[72:73], off nt
	v_addc_co_u32_e64 v79, s[6:7], 0, v117, s[6:7]
	v_add_co_u32_e64 v82, s[6:7], s0, v116
	s_mov_b32 s0, 0x19000
	s_nop 0
	v_addc_co_u32_e64 v83, s[6:7], 0, v117, s[6:7]
	global_load_dwordx4 v[166:169], v[78:79], off nt
	global_load_dwordx4 v[170:173], v[82:83], off nt
	s_nop 0
	global_load_dwordx4 v[76:79], v[76:77], off nt
	s_nop 0
	global_load_dwordx4 v[80:83], v[80:81], off nt
	v_mul_f32_e32 v148, 0x3d800000, v146
	v_max3_f32 v134, v134, v142, v144
	s_waitcnt vmcnt(6)
	v_pk_mul_f32 v[174:175], v[122:123], v[92:93]
	v_pk_mul_f32 v[176:177], v[122:123], v[96:97]
	v_pk_mul_f32 v[178:179], v[122:123], v[100:101]
	v_pk_mul_f32 v[180:181], v[122:123], v[104:105]
	v_pk_mul_f32 v[182:183], v[122:123], v[108:109]
	v_pk_mul_f32 v[184:185], v[122:123], v[110:111]
	v_pk_mul_f32 v[186:187], v[122:123], v[112:113]
	v_pk_mul_f32 v[122:123], v[122:123], v[114:115]
	v_pk_fma_f32 v[174:175], v[120:121], v[84:85], v[174:175]
	v_pk_fma_f32 v[176:177], v[120:121], v[86:87], v[176:177]
	v_pk_fma_f32 v[178:179], v[120:121], v[88:89], v[178:179]
	v_pk_fma_f32 v[180:181], v[120:121], v[90:91], v[180:181]
	v_pk_fma_f32 v[182:183], v[120:121], v[94:95], v[182:183]
	v_pk_fma_f32 v[184:185], v[120:121], v[98:99], v[184:185]
	v_pk_fma_f32 v[186:187], v[120:121], v[102:103], v[186:187]
	v_pk_fma_f32 v[120:121], v[120:121], v[106:107], v[122:123]
	v_pk_add_f32 v[174:175], v[174:175], v[174:175] op_sel:[0,1] op_sel_hi:[1,0]
	v_pk_add_f32 v[182:183], v[182:183], v[182:183] op_sel:[0,1] op_sel_hi:[1,0]
	v_pk_add_f32 v[120:121], v[120:121], v[120:121] op_sel:[0,1] op_sel_hi:[1,0]
	v_pk_add_f32 v[176:177], v[176:177], v[176:177] op_sel:[0,1] op_sel_hi:[1,0]
	v_cndmask_b32_e32 v121, v182, v174, vcc
	v_mov_b32_e32 v123, v121
	v_pk_add_f32 v[184:185], v[184:185], v[184:185] op_sel:[0,1] op_sel_hi:[1,0]
	s_nop 0
	v_permlane32_swap_b32_e32 v121, v123
	v_cndmask_b32_e32 v122, v174, v182, vcc
	v_cndmask_b32_e32 v121, v123, v121, vcc
	v_add_f32_e32 v121, v121, v122
	v_cndmask_b32_e32 v122, v184, v176, vcc
	v_mov_b32_e32 v174, v122
	v_pk_add_f32 v[178:179], v[178:179], v[178:179] op_sel:[0,1] op_sel_hi:[1,0]
	s_nop 0
	v_permlane32_swap_b32_e32 v122, v174
	v_pk_add_f32 v[186:187], v[186:187], v[186:187] op_sel:[0,1] op_sel_hi:[1,0]
	v_cndmask_b32_e32 v123, v176, v184, vcc
	v_cndmask_b32_e32 v122, v174, v122, vcc
	v_add_f32_e32 v122, v122, v123
	v_cndmask_b32_e32 v123, v186, v178, vcc
	v_mov_b32_e32 v175, v123
	v_pk_add_f32 v[180:181], v[180:181], v[180:181] op_sel:[0,1] op_sel_hi:[1,0]
	s_nop 0
	v_permlane32_swap_b32_e32 v123, v175
	v_cndmask_b32_e32 v174, v178, v186, vcc
	v_cndmask_b32_e32 v123, v175, v123, vcc
	v_add_f32_e32 v123, v174, v123
	v_cndmask_b32_e32 v174, v120, v180, vcc
	v_mov_b32_e32 v175, v174
	v_cndmask_b32_e32 v120, v180, v120, vcc
	s_nop 0
	v_permlane32_swap_b32_e32 v174, v175
	v_cndmask_b32_e32 v174, v175, v174, vcc
	v_add_f32_e32 v120, v120, v174
	v_cndmask_b32_e64 v174, v121, v123, s[2:3]
	v_cndmask_b32_e64 v121, v123, v121, s[2:3]
	v_mov_b32_e32 v123, v174
	v_mul_f32_e32 v150, 0x3d800000, v149
	s_nop 0
	v_permlane16_swap_b32_e32 v174, v123
	v_cndmask_b32_e64 v123, v174, v123, s[2:3]
	v_add_f32_e32 v121, v121, v123
	v_cndmask_b32_e64 v123, v122, v120, s[2:3]
	v_cndmask_b32_e64 v120, v120, v122, s[2:3]
	v_mov_b32_e32 v122, v123
	v_mul_f32_e32 v152, 0x3d800000, v151
	s_nop 0
	v_permlane16_swap_b32_e32 v123, v122
	v_cndmask_b32_e64 v122, v123, v122, s[2:3]
	v_add_f32_e32 v120, v120, v122
	v_cndmask_b32_e64 v122, v121, v120, s[4:5]
	v_cndmask_b32_e64 v120, v120, v121, s[4:5]
	s_waitcnt vmcnt(2)
	v_pk_mul_f32 v[180:181], v[172:173], v[108:109]
	v_pk_mul_f32 v[174:175], v[172:173], v[96:97]
	v_add_f32_dpp v120, v122, v120 row_ror:8 row_mask:0xf bank_mask:0xf bound_ctrl:1
	v_pk_mul_f32 v[122:123], v[172:173], v[92:93]
	v_pk_mul_f32 v[176:177], v[172:173], v[100:101]
	v_pk_fma_f32 v[122:123], v[170:171], v[84:85], v[122:123]
	v_pk_mul_f32 v[178:179], v[172:173], v[104:105]
	v_pk_fma_f32 v[180:181], v[170:171], v[94:95], v[180:181]
	v_pk_mul_f32 v[182:183], v[172:173], v[110:111]
	v_pk_mul_f32 v[184:185], v[172:173], v[112:113]
	v_pk_mul_f32 v[172:173], v[172:173], v[114:115]
	v_pk_add_f32 v[122:123], v[122:123], v[122:123] op_sel:[0,1] op_sel_hi:[1,0]
	v_pk_fma_f32 v[174:175], v[170:171], v[86:87], v[174:175]
	v_pk_fma_f32 v[176:177], v[170:171], v[88:89], v[176:177]
	v_pk_fma_f32 v[178:179], v[170:171], v[90:91], v[178:179]
	v_pk_add_f32 v[180:181], v[180:181], v[180:181] op_sel:[0,1] op_sel_hi:[1,0]
	v_pk_fma_f32 v[182:183], v[170:171], v[98:99], v[182:183]
	v_pk_fma_f32 v[184:185], v[170:171], v[102:103], v[184:185]
	v_pk_fma_f32 v[170:171], v[170:171], v[106:107], v[172:173]
	v_cndmask_b32_e32 v123, v180, v122, vcc
	v_pk_add_f32 v[170:171], v[170:171], v[170:171] op_sel:[0,1] op_sel_hi:[1,0]
	v_pk_add_f32 v[174:175], v[174:175], v[174:175] op_sel:[0,1] op_sel_hi:[1,0]
	v_mov_b32_e32 v171, v123
	v_pk_add_f32 v[182:183], v[182:183], v[182:183] op_sel:[0,1] op_sel_hi:[1,0]
	s_nop 0
	v_permlane32_swap_b32_e32 v123, v171
	v_cndmask_b32_e32 v122, v122, v180, vcc
	v_cndmask_b32_e32 v123, v171, v123, vcc
	v_add_f32_e32 v122, v122, v123
	v_cndmask_b32_e32 v123, v182, v174, vcc
	v_mov_b32_e32 v172, v123
	v_pk_add_f32 v[176:177], v[176:177], v[176:177] op_sel:[0,1] op_sel_hi:[1,0]
	s_nop 0
	v_permlane32_swap_b32_e32 v123, v172
	v_pk_add_f32 v[184:185], v[184:185], v[184:185] op_sel:[0,1] op_sel_hi:[1,0]
	v_cndmask_b32_e32 v171, v174, v182, vcc
	v_cndmask_b32_e32 v123, v172, v123, vcc
	v_add_f32_e32 v123, v171, v123
	v_cndmask_b32_e32 v171, v184, v176, vcc
	v_mov_b32_e32 v173, v171
	v_pk_add_f32 v[178:179], v[178:179], v[178:179] op_sel:[0,1] op_sel_hi:[1,0]
	s_nop 0
	v_permlane32_swap_b32_e32 v171, v173
	v_cndmask_b32_e32 v172, v176, v184, vcc
	v_cndmask_b32_e32 v171, v173, v171, vcc
	v_add_f32_e32 v171, v172, v171
	v_cndmask_b32_e32 v172, v170, v178, vcc
	v_mov_b32_e32 v173, v172
	v_cndmask_b32_e32 v170, v178, v170, vcc
	s_nop 0
	v_permlane32_swap_b32_e32 v172, v173
	v_cndmask_b32_e32 v172, v173, v172, vcc
	v_add_f32_e32 v170, v170, v172
	v_cndmask_b32_e64 v172, v122, v171, s[2:3]
	v_cndmask_b32_e64 v122, v171, v122, s[2:3]
	v_mov_b32_e32 v171, v172
	v_pk_mul_f32 v[174:175], v[168:169], v[100:101]
	s_nop 0
	v_permlane16_swap_b32_e32 v172, v171
	v_cndmask_b32_e64 v171, v172, v171, s[2:3]
	v_add_f32_e32 v122, v122, v171
	v_cndmask_b32_e64 v171, v123, v170, s[2:3]
	v_cndmask_b32_e64 v123, v170, v123, s[2:3]
	v_mov_b32_e32 v170, v171
	v_pk_mul_f32 v[172:173], v[168:169], v[96:97]
	s_nop 0
	v_permlane16_swap_b32_e32 v171, v170
	v_cndmask_b32_e64 v170, v171, v170, s[2:3]
	v_add_f32_e32 v123, v123, v170
	v_cndmask_b32_e64 v170, v122, v123, s[4:5]
	v_cndmask_b32_e64 v122, v123, v122, s[4:5]
	v_pk_mul_f32 v[176:177], v[168:169], v[104:105]
	v_pk_mul_f32 v[178:179], v[168:169], v[108:109]
	v_add_f32_dpp v122, v170, v122 row_ror:8 row_mask:0xf bank_mask:0xf bound_ctrl:1
	v_pk_mul_f32 v[170:171], v[168:169], v[92:93]
	v_pk_mul_f32 v[180:181], v[168:169], v[110:111]
	v_pk_mul_f32 v[182:183], v[168:169], v[112:113]
	v_pk_mul_f32 v[168:169], v[168:169], v[114:115]
	v_pk_fma_f32 v[170:171], v[166:167], v[84:85], v[170:171]
	v_pk_fma_f32 v[172:173], v[166:167], v[86:87], v[172:173]
	v_pk_fma_f32 v[174:175], v[166:167], v[88:89], v[174:175]
	v_pk_fma_f32 v[176:177], v[166:167], v[90:91], v[176:177]
	v_pk_fma_f32 v[178:179], v[166:167], v[94:95], v[178:179]
	v_pk_fma_f32 v[180:181], v[166:167], v[98:99], v[180:181]
	v_pk_fma_f32 v[182:183], v[166:167], v[102:103], v[182:183]
	v_pk_fma_f32 v[166:167], v[166:167], v[106:107], v[168:169]
	v_pk_add_f32 v[170:171], v[170:171], v[170:171] op_sel:[0,1] op_sel_hi:[1,0]
	v_pk_add_f32 v[178:179], v[178:179], v[178:179] op_sel:[0,1] op_sel_hi:[1,0]
	v_pk_add_f32 v[166:167], v[166:167], v[166:167] op_sel:[0,1] op_sel_hi:[1,0]
	v_pk_add_f32 v[172:173], v[172:173], v[172:173] op_sel:[0,1] op_sel_hi:[1,0]
	v_cndmask_b32_e32 v167, v178, v170, vcc
	v_mov_b32_e32 v169, v167
	v_pk_add_f32 v[180:181], v[180:181], v[180:181] op_sel:[0,1] op_sel_hi:[1,0]
	s_nop 0
	v_permlane32_swap_b32_e32 v167, v169
	v_cndmask_b32_e32 v168, v170, v178, vcc
	v_cndmask_b32_e32 v167, v169, v167, vcc
	v_add_f32_e32 v167, v168, v167
	v_cndmask_b32_e32 v168, v180, v172, vcc
	v_mov_b32_e32 v170, v168
	v_pk_add_f32 v[174:175], v[174:175], v[174:175] op_sel:[0,1] op_sel_hi:[1,0]
	s_nop 0
	v_permlane32_swap_b32_e32 v168, v170
	v_pk_add_f32 v[182:183], v[182:183], v[182:183] op_sel:[0,1] op_sel_hi:[1,0]
	v_cndmask_b32_e32 v169, v172, v180, vcc
	v_cndmask_b32_e32 v168, v170, v168, vcc
	v_add_f32_e32 v168, v169, v168
	v_cndmask_b32_e32 v169, v182, v174, vcc
	v_mov_b32_e32 v171, v169
	v_pk_add_f32 v[176:177], v[176:177], v[176:177] op_sel:[0,1] op_sel_hi:[1,0]
	s_nop 0
	v_permlane32_swap_b32_e32 v169, v171
	v_cndmask_b32_e32 v170, v174, v182, vcc
	v_cndmask_b32_e32 v169, v171, v169, vcc
	v_add_f32_e32 v169, v170, v169
	v_cndmask_b32_e32 v170, v166, v176, vcc
	v_mov_b32_e32 v171, v170
	v_cndmask_b32_e32 v166, v176, v166, vcc
	s_nop 0
	v_permlane32_swap_b32_e32 v170, v171
	v_cndmask_b32_e32 v170, v171, v170, vcc
	v_add_f32_e32 v166, v166, v170
	v_cndmask_b32_e64 v170, v167, v169, s[2:3]
	v_cndmask_b32_e64 v167, v169, v167, s[2:3]
	v_mov_b32_e32 v169, v170
	s_waitcnt vmcnt(0)
	v_pk_mul_f32 v[174:175], v[82:83], v[100:101]
	v_permlane16_swap_b32_e32 v170, v169
	v_cndmask_b32_e64 v169, v170, v169, s[2:3]
	v_add_f32_e32 v167, v167, v169
	v_cndmask_b32_e64 v169, v168, v166, s[2:3]
	v_cndmask_b32_e64 v166, v166, v168, s[2:3]
	v_mov_b32_e32 v168, v169
	v_pk_mul_f32 v[176:177], v[82:83], v[104:105]
	s_nop 0
	v_permlane16_swap_b32_e32 v169, v168
	v_cndmask_b32_e64 v168, v169, v168, s[2:3]
	v_add_f32_e32 v166, v166, v168
	v_cndmask_b32_e64 v168, v167, v166, s[4:5]
	v_cndmask_b32_e64 v166, v166, v167, s[4:5]
	v_pk_mul_f32 v[178:179], v[82:83], v[108:109]
	v_pk_mul_f32 v[180:181], v[82:83], v[110:111]
	v_add_f32_dpp v166, v168, v166 row_ror:8 row_mask:0xf bank_mask:0xf bound_ctrl:1
	v_pk_mul_f32 v[168:169], v[82:83], v[96:97]
	v_pk_mul_f32 v[182:183], v[82:83], v[112:113]
	v_add_f32_dpp v166, v166, v166 quad_perm:[1,0,3,2] row_mask:0xf bank_mask:0xf bound_ctrl:1
	v_pk_fma_f32 v[168:169], v[80:81], v[86:87], v[168:169]
	v_pk_fma_f32 v[174:175], v[80:81], v[88:89], v[174:175]
	v_add_f32_dpp v171, v166, v166 quad_perm:[2,3,0,1] row_mask:0xf bank_mask:0xf bound_ctrl:1
	v_pk_mul_f32 v[166:167], v[82:83], v[92:93]
	v_pk_mul_f32 v[82:83], v[82:83], v[114:115]
	v_pk_fma_f32 v[166:167], v[80:81], v[84:85], v[166:167]
	v_pk_fma_f32 v[176:177], v[80:81], v[90:91], v[176:177]
	v_pk_fma_f32 v[178:179], v[80:81], v[94:95], v[178:179]
	v_pk_fma_f32 v[180:181], v[80:81], v[98:99], v[180:181]
	v_pk_fma_f32 v[182:183], v[80:81], v[102:103], v[182:183]
	v_pk_fma_f32 v[80:81], v[80:81], v[106:107], v[82:83]
	v_pk_add_f32 v[166:167], v[166:167], v[166:167] op_sel:[0,1] op_sel_hi:[1,0]
	v_pk_add_f32 v[178:179], v[178:179], v[178:179] op_sel:[0,1] op_sel_hi:[1,0]
	v_pk_add_f32 v[80:81], v[80:81], v[80:81] op_sel:[0,1] op_sel_hi:[1,0]
	v_pk_add_f32 v[168:169], v[168:169], v[168:169] op_sel:[0,1] op_sel_hi:[1,0]
	v_cndmask_b32_e32 v81, v178, v166, vcc
	v_mov_b32_e32 v83, v81
	v_pk_add_f32 v[180:181], v[180:181], v[180:181] op_sel:[0,1] op_sel_hi:[1,0]
	s_nop 0
	v_permlane32_swap_b32_e32 v81, v83
	v_cndmask_b32_e32 v82, v166, v178, vcc
	v_cndmask_b32_e32 v81, v83, v81, vcc
	v_add_f32_e32 v81, v82, v81
	v_cndmask_b32_e32 v82, v180, v168, vcc
	v_mov_b32_e32 v166, v82
	v_pk_add_f32 v[174:175], v[174:175], v[174:175] op_sel:[0,1] op_sel_hi:[1,0]
	s_nop 0
	v_permlane32_swap_b32_e32 v82, v166
	v_pk_add_f32 v[182:183], v[182:183], v[182:183] op_sel:[0,1] op_sel_hi:[1,0]
	v_cndmask_b32_e32 v83, v168, v180, vcc
	v_cndmask_b32_e32 v82, v166, v82, vcc
	v_add_f32_e32 v82, v83, v82
	v_cndmask_b32_e32 v83, v182, v174, vcc
	v_mov_b32_e32 v167, v83
	v_pk_add_f32 v[176:177], v[176:177], v[176:177] op_sel:[0,1] op_sel_hi:[1,0]
	s_nop 0
	v_permlane32_swap_b32_e32 v83, v167
	v_cndmask_b32_e32 v166, v174, v182, vcc
	v_cndmask_b32_e32 v83, v167, v83, vcc
	v_add_f32_e32 v83, v166, v83
	v_cndmask_b32_e32 v166, v80, v176, vcc
	v_mov_b32_e32 v167, v166
	v_cndmask_b32_e32 v80, v176, v80, vcc
	s_nop 0
	v_permlane32_swap_b32_e32 v166, v167
	v_cndmask_b32_e32 v166, v167, v166, vcc
	v_add_f32_e32 v80, v80, v166
	v_cndmask_b32_e64 v166, v81, v83, s[2:3]
	v_cndmask_b32_e64 v81, v83, v81, s[2:3]
	v_mov_b32_e32 v83, v166
	v_pk_mul_f32 v[168:169], v[78:79], v[104:105]
	s_nop 0
	v_permlane16_swap_b32_e32 v166, v83
	v_cndmask_b32_e64 v83, v166, v83, s[2:3]
	v_add_f32_e32 v81, v81, v83
	v_cndmask_b32_e64 v83, v82, v80, s[2:3]
	v_cndmask_b32_e64 v80, v80, v82, s[2:3]
	v_mov_b32_e32 v82, v83
	v_pk_mul_f32 v[166:167], v[78:79], v[100:101]
	s_nop 0
	v_permlane16_swap_b32_e32 v83, v82
	v_cndmask_b32_e64 v82, v83, v82, s[2:3]
	v_add_f32_e32 v80, v80, v82
	v_cndmask_b32_e64 v82, v81, v80, s[4:5]
	v_cndmask_b32_e64 v80, v80, v81, s[4:5]
	v_pk_mul_f32 v[174:175], v[78:79], v[108:109]
	v_pk_mul_f32 v[176:177], v[78:79], v[110:111]
	v_add_f32_dpp v80, v82, v80 row_ror:8 row_mask:0xf bank_mask:0xf bound_ctrl:1
	v_pk_mul_f32 v[82:83], v[78:79], v[96:97]
	v_pk_mul_f32 v[178:179], v[78:79], v[112:113]
	v_add_f32_dpp v80, v80, v80 quad_perm:[1,0,3,2] row_mask:0xf bank_mask:0xf bound_ctrl:1
	v_pk_fma_f32 v[82:83], v[76:77], v[86:87], v[82:83]
	v_pk_fma_f32 v[166:167], v[76:77], v[88:89], v[166:167]
	v_add_f32_dpp v170, v80, v80 quad_perm:[2,3,0,1] row_mask:0xf bank_mask:0xf bound_ctrl:1
	v_pk_mul_f32 v[80:81], v[78:79], v[92:93]
	v_pk_mul_f32 v[78:79], v[78:79], v[114:115]
	v_pk_fma_f32 v[80:81], v[76:77], v[84:85], v[80:81]
	v_pk_fma_f32 v[168:169], v[76:77], v[90:91], v[168:169]
	v_pk_fma_f32 v[174:175], v[76:77], v[94:95], v[174:175]
	v_pk_fma_f32 v[176:177], v[76:77], v[98:99], v[176:177]
	v_pk_fma_f32 v[178:179], v[76:77], v[102:103], v[178:179]
	v_pk_fma_f32 v[76:77], v[76:77], v[106:107], v[78:79]
	v_pk_add_f32 v[80:81], v[80:81], v[80:81] op_sel:[0,1] op_sel_hi:[1,0]
	v_pk_add_f32 v[174:175], v[174:175], v[174:175] op_sel:[0,1] op_sel_hi:[1,0]
	v_pk_add_f32 v[76:77], v[76:77], v[76:77] op_sel:[0,1] op_sel_hi:[1,0]
	v_pk_add_f32 v[82:83], v[82:83], v[82:83] op_sel:[0,1] op_sel_hi:[1,0]
	v_cndmask_b32_e32 v77, v174, v80, vcc
	v_mov_b32_e32 v79, v77
	v_pk_add_f32 v[176:177], v[176:177], v[176:177] op_sel:[0,1] op_sel_hi:[1,0]
	s_nop 0
	v_permlane32_swap_b32_e32 v77, v79
	v_cndmask_b32_e32 v78, v80, v174, vcc
	v_cndmask_b32_e32 v77, v79, v77, vcc
	v_add_f32_e32 v77, v78, v77
	v_cndmask_b32_e32 v78, v176, v82, vcc
	v_mov_b32_e32 v80, v78
	v_pk_add_f32 v[166:167], v[166:167], v[166:167] op_sel:[0,1] op_sel_hi:[1,0]
	s_nop 0
	v_permlane32_swap_b32_e32 v78, v80
	v_pk_add_f32 v[178:179], v[178:179], v[178:179] op_sel:[0,1] op_sel_hi:[1,0]
	v_cndmask_b32_e32 v79, v82, v176, vcc
	v_cndmask_b32_e32 v78, v80, v78, vcc
	v_add_f32_e32 v78, v79, v78
	v_cndmask_b32_e32 v79, v178, v166, vcc
	v_mov_b32_e32 v81, v79
	v_pk_add_f32 v[168:169], v[168:169], v[168:169] op_sel:[0,1] op_sel_hi:[1,0]
	s_nop 0
	v_permlane32_swap_b32_e32 v79, v81
	v_cndmask_b32_e32 v80, v166, v178, vcc
	v_cndmask_b32_e32 v79, v81, v79, vcc
	v_add_f32_e32 v79, v80, v79
	v_cndmask_b32_e32 v80, v76, v168, vcc
	v_mov_b32_e32 v81, v80
	v_cndmask_b32_e32 v76, v168, v76, vcc
	s_nop 0
	v_permlane32_swap_b32_e32 v80, v81
	v_cndmask_b32_e32 v80, v81, v80, vcc
	v_add_f32_e32 v76, v76, v80
	v_cndmask_b32_e64 v80, v77, v79, s[2:3]
	v_cndmask_b32_e64 v77, v79, v77, s[2:3]
	v_mov_b32_e32 v79, v80
	v_pk_mul_f32 v[82:83], v[74:75], v[104:105]
	s_nop 0
	v_permlane16_swap_b32_e32 v80, v79
	v_cndmask_b32_e64 v79, v80, v79, s[2:3]
	v_add_f32_e32 v77, v77, v79
	v_cndmask_b32_e64 v79, v78, v76, s[2:3]
	v_cndmask_b32_e64 v76, v76, v78, s[2:3]
	v_mov_b32_e32 v78, v79
	v_pk_mul_f32 v[80:81], v[74:75], v[100:101]
	s_nop 0
	v_permlane16_swap_b32_e32 v79, v78
	v_cndmask_b32_e64 v78, v79, v78, s[2:3]
	v_add_f32_e32 v76, v76, v78
	v_cndmask_b32_e64 v78, v77, v76, s[4:5]
	v_cndmask_b32_e64 v76, v76, v77, s[4:5]
	v_pk_mul_f32 v[166:167], v[74:75], v[108:109]
	v_pk_mul_f32 v[168:169], v[74:75], v[110:111]
	v_add_f32_dpp v76, v78, v76 row_ror:8 row_mask:0xf bank_mask:0xf bound_ctrl:1
	v_pk_mul_f32 v[78:79], v[74:75], v[96:97]
	v_pk_mul_f32 v[174:175], v[74:75], v[112:113]
	v_add_f32_dpp v76, v76, v76 quad_perm:[1,0,3,2] row_mask:0xf bank_mask:0xf bound_ctrl:1
	v_pk_fma_f32 v[78:79], v[72:73], v[86:87], v[78:79]
	v_pk_fma_f32 v[80:81], v[72:73], v[88:89], v[80:81]
	v_add_f32_dpp v177, v76, v76 quad_perm:[2,3,0,1] row_mask:0xf bank_mask:0xf bound_ctrl:1
	v_pk_mul_f32 v[76:77], v[74:75], v[92:93]
	v_pk_mul_f32 v[74:75], v[74:75], v[114:115]
	v_pk_fma_f32 v[76:77], v[72:73], v[84:85], v[76:77]
	v_pk_fma_f32 v[82:83], v[72:73], v[90:91], v[82:83]
	v_pk_fma_f32 v[166:167], v[72:73], v[94:95], v[166:167]
	v_pk_fma_f32 v[168:169], v[72:73], v[98:99], v[168:169]
	v_pk_fma_f32 v[174:175], v[72:73], v[102:103], v[174:175]
	v_pk_fma_f32 v[72:73], v[72:73], v[106:107], v[74:75]
	v_pk_add_f32 v[76:77], v[76:77], v[76:77] op_sel:[0,1] op_sel_hi:[1,0]
	v_pk_add_f32 v[166:167], v[166:167], v[166:167] op_sel:[0,1] op_sel_hi:[1,0]
	v_pk_add_f32 v[72:73], v[72:73], v[72:73] op_sel:[0,1] op_sel_hi:[1,0]
	v_pk_add_f32 v[78:79], v[78:79], v[78:79] op_sel:[0,1] op_sel_hi:[1,0]
	v_cndmask_b32_e32 v73, v166, v76, vcc
	v_mov_b32_e32 v75, v73
	v_pk_add_f32 v[168:169], v[168:169], v[168:169] op_sel:[0,1] op_sel_hi:[1,0]
	s_nop 0
	v_permlane32_swap_b32_e32 v73, v75
	v_cndmask_b32_e32 v74, v76, v166, vcc
	v_cndmask_b32_e32 v73, v75, v73, vcc
	v_add_f32_e32 v73, v74, v73
	v_cndmask_b32_e32 v74, v168, v78, vcc
	v_mov_b32_e32 v76, v74
	v_pk_add_f32 v[80:81], v[80:81], v[80:81] op_sel:[0,1] op_sel_hi:[1,0]
	s_nop 0
	v_permlane32_swap_b32_e32 v74, v76
	v_pk_add_f32 v[174:175], v[174:175], v[174:175] op_sel:[0,1] op_sel_hi:[1,0]
	v_cndmask_b32_e32 v75, v78, v168, vcc
	v_cndmask_b32_e32 v74, v76, v74, vcc
	v_add_f32_e32 v74, v75, v74
	v_cndmask_b32_e32 v75, v174, v80, vcc
	v_mov_b32_e32 v77, v75
	v_pk_add_f32 v[82:83], v[82:83], v[82:83] op_sel:[0,1] op_sel_hi:[1,0]
	s_nop 0
	v_permlane32_swap_b32_e32 v75, v77
	v_cndmask_b32_e32 v76, v80, v174, vcc
	v_cndmask_b32_e32 v75, v77, v75, vcc
	v_add_f32_e32 v75, v76, v75
	v_cndmask_b32_e32 v76, v72, v82, vcc
	v_mov_b32_e32 v77, v76
	v_cndmask_b32_e32 v72, v82, v72, vcc
	s_nop 0
	v_permlane32_swap_b32_e32 v76, v77
	v_cndmask_b32_e32 v76, v77, v76, vcc
	v_add_f32_e32 v72, v72, v76
	v_cndmask_b32_e64 v76, v73, v75, s[2:3]
	v_cndmask_b32_e64 v73, v75, v73, s[2:3]
	v_mov_b32_e32 v75, v76
	v_pk_mul_f32 v[78:79], v[70:71], v[104:105]
	s_nop 0
	v_permlane16_swap_b32_e32 v76, v75
	v_cndmask_b32_e64 v75, v76, v75, s[2:3]
	v_add_f32_e32 v73, v73, v75
	v_cndmask_b32_e64 v75, v74, v72, s[2:3]
	v_cndmask_b32_e64 v72, v72, v74, s[2:3]
	v_mov_b32_e32 v74, v75
	v_pk_mul_f32 v[76:77], v[70:71], v[100:101]
	s_nop 0
	v_permlane16_swap_b32_e32 v75, v74
	v_cndmask_b32_e64 v74, v75, v74, s[2:3]
	v_add_f32_e32 v72, v72, v74
	v_cndmask_b32_e64 v74, v73, v72, s[4:5]
	v_cndmask_b32_e64 v72, v72, v73, s[4:5]
	v_pk_mul_f32 v[80:81], v[70:71], v[108:109]
	v_pk_mul_f32 v[82:83], v[70:71], v[110:111]
	v_add_f32_dpp v72, v74, v72 row_ror:8 row_mask:0xf bank_mask:0xf bound_ctrl:1
	v_pk_mul_f32 v[74:75], v[70:71], v[96:97]
	v_pk_mul_f32 v[166:167], v[70:71], v[112:113]
	v_add_f32_dpp v72, v72, v72 quad_perm:[1,0,3,2] row_mask:0xf bank_mask:0xf bound_ctrl:1
	v_pk_fma_f32 v[74:75], v[68:69], v[86:87], v[74:75]
	v_pk_fma_f32 v[76:77], v[68:69], v[88:89], v[76:77]
	v_add_f32_dpp v168, v72, v72 quad_perm:[2,3,0,1] row_mask:0xf bank_mask:0xf bound_ctrl:1
	v_pk_mul_f32 v[72:73], v[70:71], v[92:93]
	v_pk_mul_f32 v[70:71], v[70:71], v[114:115]
	v_pk_fma_f32 v[72:73], v[68:69], v[84:85], v[72:73]
	v_pk_fma_f32 v[78:79], v[68:69], v[90:91], v[78:79]
	v_pk_fma_f32 v[80:81], v[68:69], v[94:95], v[80:81]
	v_pk_fma_f32 v[82:83], v[68:69], v[98:99], v[82:83]
	v_pk_fma_f32 v[166:167], v[68:69], v[102:103], v[166:167]
	v_pk_fma_f32 v[68:69], v[68:69], v[106:107], v[70:71]
	v_pk_add_f32 v[72:73], v[72:73], v[72:73] op_sel:[0,1] op_sel_hi:[1,0]
	v_pk_add_f32 v[80:81], v[80:81], v[80:81] op_sel:[0,1] op_sel_hi:[1,0]
	v_pk_add_f32 v[68:69], v[68:69], v[68:69] op_sel:[0,1] op_sel_hi:[1,0]
	v_pk_add_f32 v[74:75], v[74:75], v[74:75] op_sel:[0,1] op_sel_hi:[1,0]
	v_cndmask_b32_e32 v69, v80, v72, vcc
	v_mov_b32_e32 v71, v69
	v_pk_add_f32 v[82:83], v[82:83], v[82:83] op_sel:[0,1] op_sel_hi:[1,0]
	s_nop 0
	v_permlane32_swap_b32_e32 v69, v71
	v_cndmask_b32_e32 v70, v72, v80, vcc
	v_cndmask_b32_e32 v69, v71, v69, vcc
	v_add_f32_e32 v83, v70, v69
	v_cndmask_b32_e32 v69, v82, v74, vcc
	v_mov_b32_e32 v71, v69
	v_pk_add_f32 v[76:77], v[76:77], v[76:77] op_sel:[0,1] op_sel_hi:[1,0]
	s_nop 0
	v_permlane32_swap_b32_e32 v69, v71
	v_pk_add_f32 v[166:167], v[166:167], v[166:167] op_sel:[0,1] op_sel_hi:[1,0]
	v_cndmask_b32_e32 v70, v74, v82, vcc
	v_cndmask_b32_e32 v69, v71, v69, vcc
	v_add_f32_e32 v82, v70, v69
	v_cndmask_b32_e32 v69, v166, v76, vcc
	v_mov_b32_e32 v71, v69
	v_pk_add_f32 v[78:79], v[78:79], v[78:79] op_sel:[0,1] op_sel_hi:[1,0]
	s_nop 0
	v_permlane32_swap_b32_e32 v69, v71
	v_cndmask_b32_e32 v70, v76, v166, vcc
	v_cndmask_b32_e32 v69, v71, v69, vcc
	v_add_f32_e32 v166, v70, v69
	v_cndmask_b32_e32 v69, v68, v78, vcc
	v_mov_b32_e32 v70, v69
	v_cndmask_b32_e32 v68, v78, v68, vcc
	s_nop 0
	v_permlane32_swap_b32_e32 v69, v70
	v_cndmask_b32_e32 v69, v70, v69, vcc
	v_add_f32_e32 v167, v68, v69
	v_pk_mul_f32 v[68:69], v[66:67], v[92:93]
	v_pk_mul_f32 v[70:71], v[66:67], v[96:97]
	v_pk_mul_f32 v[72:73], v[66:67], v[100:101]
	v_pk_mul_f32 v[74:75], v[66:67], v[104:105]
	v_pk_mul_f32 v[76:77], v[66:67], v[108:109]
	v_pk_mul_f32 v[78:79], v[66:67], v[110:111]
	v_pk_mul_f32 v[80:81], v[66:67], v[112:113]
	v_pk_mul_f32 v[66:67], v[66:67], v[114:115]
	v_pk_fma_f32 v[68:69], v[64:65], v[84:85], v[68:69]
	v_pk_fma_f32 v[70:71], v[64:65], v[86:87], v[70:71]
	v_pk_fma_f32 v[72:73], v[64:65], v[88:89], v[72:73]
	v_pk_fma_f32 v[74:75], v[64:65], v[90:91], v[74:75]
	v_pk_fma_f32 v[76:77], v[64:65], v[94:95], v[76:77]
	v_pk_fma_f32 v[78:79], v[64:65], v[98:99], v[78:79]
	v_pk_fma_f32 v[80:81], v[64:65], v[102:103], v[80:81]
	v_pk_fma_f32 v[64:65], v[64:65], v[106:107], v[66:67]
	v_pk_add_f32 v[68:69], v[68:69], v[68:69] op_sel:[0,1] op_sel_hi:[1,0]
	v_pk_add_f32 v[76:77], v[76:77], v[76:77] op_sel:[0,1] op_sel_hi:[1,0]
	v_pk_add_f32 v[64:65], v[64:65], v[64:65] op_sel:[0,1] op_sel_hi:[1,0]
	v_cndmask_b32_e64 v169, v83, v166, s[2:3]
	v_cndmask_b32_e64 v175, v82, v167, s[2:3]
	v_cndmask_b32_e32 v65, v76, v68, vcc
	v_mov_b32_e32 v174, v169
	v_mov_b32_e32 v176, v175
	v_mov_b32_e32 v67, v65
	v_pk_add_f32 v[70:71], v[70:71], v[70:71] op_sel:[0,1] op_sel_hi:[1,0]
	s_nop 0
	v_permlane32_swap_b32_e32 v65, v67
	v_pk_add_f32 v[78:79], v[78:79], v[78:79] op_sel:[0,1] op_sel_hi:[1,0]
	v_cndmask_b32_e32 v66, v68, v76, vcc
	v_cndmask_b32_e32 v65, v67, v65, vcc
	v_add_f32_e32 v66, v66, v65
	v_cndmask_b32_e32 v65, v78, v70, vcc
	v_mov_b32_e32 v68, v65
	v_pk_add_f32 v[72:73], v[72:73], v[72:73] op_sel:[0,1] op_sel_hi:[1,0]
	s_nop 0
	v_permlane32_swap_b32_e32 v65, v68
	v_pk_add_f32 v[80:81], v[80:81], v[80:81] op_sel:[0,1] op_sel_hi:[1,0]
	v_cndmask_b32_e32 v67, v70, v78, vcc
	v_cndmask_b32_e32 v65, v68, v65, vcc
	v_add_f32_e32 v67, v67, v65
	v_cndmask_b32_e32 v65, v80, v72, vcc
	v_mov_b32_e32 v69, v65
	v_pk_add_f32 v[74:75], v[74:75], v[74:75] op_sel:[0,1] op_sel_hi:[1,0]
	s_nop 0
	v_permlane32_swap_b32_e32 v65, v69
	v_cndmask_b32_e32 v68, v72, v80, vcc
	v_cndmask_b32_e32 v65, v69, v65, vcc
	v_add_f32_e32 v68, v68, v65
	v_cndmask_b32_e32 v65, v64, v74, vcc
	v_mov_b32_e32 v69, v65
	v_cndmask_b32_e32 v64, v74, v64, vcc
	s_nop 0
	v_permlane32_swap_b32_e32 v65, v69
	v_cndmask_b32_e32 v65, v69, v65, vcc
	v_add_f32_e32 v69, v64, v65
	v_cndmask_b32_e64 v70, v66, v68, s[2:3]
	v_cndmask_b32_e64 v72, v67, v69, s[2:3]
	v_add_co_u32_e64 v64, s[6:7], s0, v116
	v_mov_b32_e32 v71, v70
	v_mov_b32_e32 v73, v72
	v_addc_co_u32_e64 v65, s[6:7], 0, v117, s[6:7]
	global_load_dwordx4 v[184:187], v[64:65], off nt
	global_load_dwordx4 v[188:191], v[118:119], off nt
	v_permlane16_swap_b32_e32 v169, v174
	v_cndmask_b32_e64 v64, v166, v83, s[2:3]
	v_cndmask_b32_e64 v65, v169, v174, s[2:3]
	v_permlane16_swap_b32_e32 v175, v176
	v_add_f32_e32 v64, v64, v65
	v_cndmask_b32_e64 v65, v167, v82, s[2:3]
	v_cndmask_b32_e64 v74, v175, v176, s[2:3]
	v_add_f32_e32 v65, v65, v74
	v_cndmask_b32_e64 v74, v64, v65, s[4:5]
	v_cndmask_b32_e64 v64, v65, v64, s[4:5]
	v_permlane16_swap_b32_e32 v70, v71
	s_nop 0
	v_add_f32_dpp v64, v74, v64 row_ror:8 row_mask:0xf bank_mask:0xf bound_ctrl:1
	v_cndmask_b32_e64 v65, v70, v71, s[2:3]
	v_permlane16_swap_b32_e32 v72, v73
	v_add_f32_dpp v64, v64, v64 quad_perm:[1,0,3,2] row_mask:0xf bank_mask:0xf bound_ctrl:1
	s_mov_b32 s0, 0x1d000
	v_add_f32_dpp v120, v120, v120 quad_perm:[1,0,3,2] row_mask:0xf bank_mask:0xf bound_ctrl:1
	v_add_f32_dpp v167, v64, v64 quad_perm:[2,3,0,1] row_mask:0xf bank_mask:0xf bound_ctrl:1
	v_cndmask_b32_e64 v64, v68, v66, s[2:3]
	v_add_f32_e32 v64, v64, v65
	v_cndmask_b32_e64 v65, v69, v67, s[2:3]
	v_cndmask_b32_e64 v66, v72, v73, s[2:3]
	v_add_f32_e32 v65, v65, v66
	v_cndmask_b32_e64 v66, v64, v65, s[4:5]
	v_cndmask_b32_e64 v64, v65, v64, s[4:5]
	v_add_f32_dpp v120, v120, v120 quad_perm:[2,3,0,1] row_mask:0xf bank_mask:0xf bound_ctrl:1
	v_add_f32_dpp v122, v122, v122 quad_perm:[1,0,3,2] row_mask:0xf bank_mask:0xf bound_ctrl:1
	v_add_f32_dpp v64, v66, v64 row_ror:8 row_mask:0xf bank_mask:0xf bound_ctrl:1
	v_mov_b32_dpp v121, v120 row_half_mirror row_mask:0xf bank_mask:0xf bound_ctrl:1
	v_add_f32_dpp v122, v122, v122 quad_perm:[2,3,0,1] row_mask:0xf bank_mask:0xf bound_ctrl:1
	v_add_f32_dpp v64, v64, v64 quad_perm:[1,0,3,2] row_mask:0xf bank_mask:0xf bound_ctrl:1
	v_mov_b32_dpp v173, v170 row_half_mirror row_mask:0xf bank_mask:0xf bound_ctrl:1
	v_mov_b32_dpp v123, v122 row_half_mirror row_mask:0xf bank_mask:0xf bound_ctrl:1
	v_add_f32_dpp v166, v64, v64 quad_perm:[2,3,0,1] row_mask:0xf bank_mask:0xf bound_ctrl:1
	v_add_co_u32_e64 v64, s[6:7], s48, v116
	v_mov_b32_dpp v172, v171 row_half_mirror row_mask:0xf bank_mask:0xf bound_ctrl:1
	s_nop 0
	v_addc_co_u32_e64 v65, s[6:7], 0, v117, s[6:7]
	v_add_co_u32_e64 v68, s[6:7], s49, v116
	v_add_f32_e32 v170, v170, v173
	s_nop 0
	v_addc_co_u32_e64 v69, s[6:7], 0, v117, s[6:7]
	v_add_co_u32_e64 v72, s[6:7], s0, v116
	s_mov_b32 s0, 0x1b000
	s_nop 0
	v_addc_co_u32_e64 v73, s[6:7], 0, v117, s[6:7]
	v_add_co_u32_e64 v76, s[6:7], s42, v116
	global_load_dwordx4 v[64:67], v[64:65], off nt
	s_nop 0
	global_load_dwordx4 v[68:71], v[68:69], off nt
	v_addc_co_u32_e64 v77, s[6:7], 0, v117, s[6:7]
	v_add_co_u32_e64 v80, s[6:7], s0, v116
	global_load_dwordx4 v[72:75], v[72:73], off nt
	s_nop 0
	global_load_dwordx4 v[76:79], v[76:77], off nt
	v_addc_co_u32_e64 v81, s[6:7], 0, v117, s[6:7]
	v_add_co_u32_e64 v116, s[6:7], s50, v116
	v_add_f32_e32 v173, v120, v121
	s_nop 0
	v_addc_co_u32_e64 v117, s[6:7], 0, v117, s[6:7]
	global_load_dwordx4 v[80:83], v[80:81], off nt
	s_nop 0
	global_load_dwordx4 v[116:119], v[116:117], off nt
	v_add_f32_e32 v171, v171, v172
	v_add_f32_e32 v172, v122, v123
	v_max3_f32 v134, v134, v147, v148
	v_mul_f32_e32 v154, 0x3d800000, v153
	v_mul_f32_e32 v156, 0x3d800000, v155
	v_max3_f32 v134, v134, v150, v152
	v_mul_f32_e32 v159, 0x3d800000, v158
	v_mul_f32_e32 v163, 0x3d800000, v160
	v_max3_f32 v134, v134, v154, v156
	v_mul_f32_e32 v164, 0x3d800000, v161
	s_waitcnt vmcnt(6)
	v_pk_mul_f32 v[120:121], v[190:191], v[92:93]
	v_pk_mul_f32 v[216:217], v[190:191], v[108:109]
	v_pk_fma_f32 v[120:121], v[188:189], v[84:85], v[120:121]
	v_pk_mul_f32 v[122:123], v[190:191], v[96:97]
	v_pk_fma_f32 v[216:217], v[188:189], v[94:95], v[216:217]
	v_pk_add_f32 v[120:121], v[120:121], v[120:121] op_sel:[0,1] op_sel_hi:[1,0]
	v_pk_fma_f32 v[122:123], v[188:189], v[86:87], v[122:123]
	v_pk_add_f32 v[216:217], v[216:217], v[216:217] op_sel:[0,1] op_sel_hi:[1,0]
	v_pk_add_f32 v[122:123], v[122:123], v[122:123] op_sel:[0,1] op_sel_hi:[1,0]
	v_cndmask_b32_e32 v121, v216, v120, vcc
	v_mov_b32_e32 v123, v121
	v_pk_mul_f32 v[218:219], v[190:191], v[110:111]
	v_cndmask_b32_e32 v120, v120, v216, vcc
	v_pk_fma_f32 v[218:219], v[188:189], v[98:99], v[218:219]
	v_permlane32_swap_b32_e32 v121, v123
	v_pk_add_f32 v[218:219], v[218:219], v[218:219] op_sel:[0,1] op_sel_hi:[1,0]
	v_cndmask_b32_e32 v121, v123, v121, vcc
	v_add_f32_e32 v120, v121, v120
	v_cndmask_b32_e32 v121, v218, v122, vcc
	v_mov_b32_e32 v123, v121
	v_pk_mul_f32 v[182:183], v[190:191], v[100:101]
	v_pk_mul_f32 v[220:221], v[190:191], v[112:113]
	v_pk_fma_f32 v[182:183], v[188:189], v[88:89], v[182:183]
	v_pk_fma_f32 v[220:221], v[188:189], v[102:103], v[220:221]
	v_permlane32_swap_b32_e32 v121, v123
	v_pk_add_f32 v[182:183], v[182:183], v[182:183] op_sel:[0,1] op_sel_hi:[1,0]
	v_pk_add_f32 v[220:221], v[220:221], v[220:221] op_sel:[0,1] op_sel_hi:[1,0]
	v_cndmask_b32_e32 v122, v122, v218, vcc
	v_cndmask_b32_e32 v121, v123, v121, vcc
	v_add_f32_e32 v121, v121, v122
	v_cndmask_b32_e32 v122, v220, v182, vcc
	v_cndmask_b32_e32 v123, v182, v220, vcc
	v_mov_b32_e32 v182, v122
	v_pk_mul_f32 v[192:193], v[190:191], v[104:105]
	v_pk_mul_f32 v[190:191], v[190:191], v[114:115]
	v_pk_fma_f32 v[192:193], v[188:189], v[90:91], v[192:193]
	v_pk_fma_f32 v[188:189], v[188:189], v[106:107], v[190:191]
	v_permlane32_swap_b32_e32 v122, v182
	v_pk_add_f32 v[192:193], v[192:193], v[192:193] op_sel:[0,1] op_sel_hi:[1,0]
	v_pk_add_f32 v[188:189], v[188:189], v[188:189] op_sel:[0,1] op_sel_hi:[1,0]
	v_cndmask_b32_e32 v122, v182, v122, vcc
	v_add_f32_e32 v122, v123, v122
	v_cndmask_b32_e32 v123, v188, v192, vcc
	v_mov_b32_e32 v183, v123
	v_cndmask_b32_e32 v182, v192, v188, vcc
	s_nop 0
	v_permlane32_swap_b32_e32 v123, v183
	v_cndmask_b32_e32 v123, v183, v123, vcc
	v_add_f32_e32 v123, v182, v123
	v_cndmask_b32_e64 v182, v120, v122, s[2:3]
	v_cndmask_b32_e64 v120, v122, v120, s[2:3]
	v_mov_b32_e32 v122, v182
	v_pk_mul_f32 v[192:193], v[186:187], v[108:109]
	s_nop 0
	v_permlane16_swap_b32_e32 v182, v122
	v_cndmask_b32_e64 v122, v182, v122, s[2:3]
	v_add_f32_e32 v120, v120, v122
	v_cndmask_b32_e64 v122, v121, v123, s[2:3]
	v_cndmask_b32_e64 v121, v123, v121, s[2:3]
	v_mov_b32_e32 v123, v122
	v_pk_fma_f32 v[192:193], v[184:185], v[94:95], v[192:193]
	s_nop 0
	v_permlane16_swap_b32_e32 v122, v123
	v_cndmask_b32_e64 v122, v122, v123, s[2:3]
	v_add_f32_e32 v121, v121, v122
	v_cndmask_b32_e64 v122, v120, v121, s[4:5]
	v_cndmask_b32_e64 v120, v121, v120, s[4:5]
	v_pk_add_f32 v[192:193], v[192:193], v[192:193] op_sel:[0,1] op_sel_hi:[1,0]
	v_pk_mul_f32 v[216:217], v[186:187], v[110:111]
	v_add_f32_dpp v120, v122, v120 row_ror:8 row_mask:0xf bank_mask:0xf bound_ctrl:1
	v_pk_mul_f32 v[122:123], v[186:187], v[96:97]
	v_pk_fma_f32 v[216:217], v[184:185], v[98:99], v[216:217]
	v_add_f32_dpp v120, v120, v120 quad_perm:[1,0,3,2] row_mask:0xf bank_mask:0xf bound_ctrl:1
	v_pk_fma_f32 v[122:123], v[184:185], v[86:87], v[122:123]
	v_pk_add_f32 v[216:217], v[216:217], v[216:217] op_sel:[0,1] op_sel_hi:[1,0]
	v_add_f32_dpp v120, v120, v120 quad_perm:[2,3,0,1] row_mask:0xf bank_mask:0xf bound_ctrl:1
	v_pk_add_f32 v[122:123], v[122:123], v[122:123] op_sel:[0,1] op_sel_hi:[1,0]
	v_pk_mul_f32 v[188:189], v[186:187], v[100:101]
	v_add_f32_dpp v182, v120, v120 row_half_mirror row_mask:0xf bank_mask:0xf bound_ctrl:1
	v_pk_mul_f32 v[120:121], v[186:187], v[92:93]
	v_pk_mul_f32 v[218:219], v[186:187], v[112:113]
	v_pk_fma_f32 v[120:121], v[184:185], v[84:85], v[120:121]
	v_pk_fma_f32 v[188:189], v[184:185], v[88:89], v[188:189]
	v_pk_add_f32 v[120:121], v[120:121], v[120:121] op_sel:[0,1] op_sel_hi:[1,0]
	v_pk_mul_f32 v[190:191], v[186:187], v[104:105]
	v_cndmask_b32_e32 v121, v192, v120, vcc
	v_mov_b32_e32 v123, v121
	v_cndmask_b32_e32 v120, v120, v192, vcc
	s_nop 0
	v_permlane32_swap_b32_e32 v121, v123
	v_cndmask_b32_e32 v121, v123, v121, vcc
	v_add_f32_e32 v120, v120, v121
	v_cndmask_b32_e32 v121, v216, v122, vcc
	v_mov_b32_e32 v123, v121
	v_pk_fma_f32 v[218:219], v[184:185], v[102:103], v[218:219]
	v_pk_mul_f32 v[186:187], v[186:187], v[114:115]
	v_permlane32_swap_b32_e32 v121, v123
	v_pk_add_f32 v[188:189], v[188:189], v[188:189] op_sel:[0,1] op_sel_hi:[1,0]
	v_pk_fma_f32 v[190:191], v[184:185], v[90:91], v[190:191]
	v_pk_add_f32 v[218:219], v[218:219], v[218:219] op_sel:[0,1] op_sel_hi:[1,0]
	v_pk_fma_f32 v[184:185], v[184:185], v[106:107], v[186:187]
	v_cndmask_b32_e32 v122, v122, v216, vcc
	v_cndmask_b32_e32 v121, v123, v121, vcc
	v_pk_add_f32 v[184:185], v[184:185], v[184:185] op_sel:[0,1] op_sel_hi:[1,0]
	v_add_f32_e32 v121, v122, v121
	v_cndmask_b32_e32 v122, v218, v188, vcc
	v_mov_b32_e32 v185, v122
	v_pk_add_f32 v[190:191], v[190:191], v[190:191] op_sel:[0,1] op_sel_hi:[1,0]
	s_nop 0
	v_permlane32_swap_b32_e32 v122, v185
	v_cndmask_b32_e32 v123, v188, v218, vcc
	v_cndmask_b32_e32 v122, v185, v122, vcc
	v_add_f32_e32 v122, v123, v122
	v_cndmask_b32_e32 v123, v184, v190, vcc
	v_mov_b32_e32 v185, v123
	v_cndmask_b32_e32 v184, v190, v184, vcc
	s_nop 0
	v_permlane32_swap_b32_e32 v123, v185
	v_cndmask_b32_e32 v123, v185, v123, vcc
	v_add_f32_e32 v123, v184, v123
	v_cndmask_b32_e64 v184, v120, v122, s[2:3]
	v_cndmask_b32_e64 v120, v122, v120, s[2:3]
	v_mov_b32_e32 v122, v184
	s_waitcnt vmcnt(0)
	v_pk_mul_f32 v[186:187], v[118:119], v[100:101]
	v_permlane16_swap_b32_e32 v184, v122
	v_cndmask_b32_e64 v122, v184, v122, s[2:3]
	v_add_f32_e32 v120, v120, v122
	v_cndmask_b32_e64 v122, v121, v123, s[2:3]
	v_cndmask_b32_e64 v121, v123, v121, s[2:3]
	v_mov_b32_e32 v123, v122
	v_pk_mul_f32 v[188:189], v[118:119], v[104:105]
	s_nop 0
	v_permlane16_swap_b32_e32 v122, v123
	v_cndmask_b32_e64 v122, v122, v123, s[2:3]
	v_add_f32_e32 v121, v121, v122
	v_cndmask_b32_e64 v122, v120, v121, s[4:5]
	v_cndmask_b32_e64 v120, v121, v120, s[4:5]
	v_pk_mul_f32 v[190:191], v[118:119], v[108:109]
	v_pk_mul_f32 v[192:193], v[118:119], v[110:111]
	v_add_f32_dpp v120, v122, v120 row_ror:8 row_mask:0xf bank_mask:0xf bound_ctrl:1
	v_pk_mul_f32 v[122:123], v[118:119], v[96:97]
	v_pk_mul_f32 v[216:217], v[118:119], v[112:113]
	v_add_f32_dpp v120, v120, v120 quad_perm:[1,0,3,2] row_mask:0xf bank_mask:0xf bound_ctrl:1
	v_pk_fma_f32 v[122:123], v[116:117], v[86:87], v[122:123]
	v_pk_fma_f32 v[186:187], v[116:117], v[88:89], v[186:187]
	v_add_f32_dpp v120, v120, v120 quad_perm:[2,3,0,1] row_mask:0xf bank_mask:0xf bound_ctrl:1
	v_pk_fma_f32 v[188:189], v[116:117], v[90:91], v[188:189]
	v_pk_fma_f32 v[190:191], v[116:117], v[94:95], v[190:191]
	v_add_f32_dpp v184, v120, v120 row_half_mirror row_mask:0xf bank_mask:0xf bound_ctrl:1
	v_pk_mul_f32 v[120:121], v[118:119], v[92:93]
	v_pk_mul_f32 v[118:119], v[118:119], v[114:115]
	v_pk_fma_f32 v[120:121], v[116:117], v[84:85], v[120:121]
	v_pk_fma_f32 v[192:193], v[116:117], v[98:99], v[192:193]
	v_pk_fma_f32 v[216:217], v[116:117], v[102:103], v[216:217]
	v_pk_fma_f32 v[116:117], v[116:117], v[106:107], v[118:119]
	v_pk_add_f32 v[120:121], v[120:121], v[120:121] op_sel:[0,1] op_sel_hi:[1,0]
	v_pk_add_f32 v[190:191], v[190:191], v[190:191] op_sel:[0,1] op_sel_hi:[1,0]
	v_pk_add_f32 v[116:117], v[116:117], v[116:117] op_sel:[0,1] op_sel_hi:[1,0]
	v_pk_add_f32 v[122:123], v[122:123], v[122:123] op_sel:[0,1] op_sel_hi:[1,0]
	v_cndmask_b32_e32 v117, v190, v120, vcc
	v_mov_b32_e32 v119, v117
	v_pk_add_f32 v[192:193], v[192:193], v[192:193] op_sel:[0,1] op_sel_hi:[1,0]
	s_nop 0
	v_permlane32_swap_b32_e32 v117, v119
	v_cndmask_b32_e32 v118, v120, v190, vcc
	v_cndmask_b32_e32 v117, v119, v117, vcc
	v_add_f32_e32 v117, v118, v117
	v_cndmask_b32_e32 v118, v192, v122, vcc
	v_mov_b32_e32 v120, v118
	v_pk_add_f32 v[186:187], v[186:187], v[186:187] op_sel:[0,1] op_sel_hi:[1,0]
	s_nop 0
	v_permlane32_swap_b32_e32 v118, v120
	v_pk_add_f32 v[216:217], v[216:217], v[216:217] op_sel:[0,1] op_sel_hi:[1,0]
	v_cndmask_b32_e32 v119, v122, v192, vcc
	v_cndmask_b32_e32 v118, v120, v118, vcc
	v_add_f32_e32 v118, v119, v118
	v_cndmask_b32_e32 v119, v216, v186, vcc
	v_mov_b32_e32 v121, v119
	v_pk_add_f32 v[188:189], v[188:189], v[188:189] op_sel:[0,1] op_sel_hi:[1,0]
	s_nop 0
	v_permlane32_swap_b32_e32 v119, v121
	v_cndmask_b32_e32 v120, v186, v216, vcc
	v_cndmask_b32_e32 v119, v121, v119, vcc
	v_add_f32_e32 v119, v120, v119
	v_cndmask_b32_e32 v120, v116, v188, vcc
	v_mov_b32_e32 v121, v120
	v_cndmask_b32_e32 v116, v188, v116, vcc
	s_nop 0
	v_permlane32_swap_b32_e32 v120, v121
	v_cndmask_b32_e32 v120, v121, v120, vcc
	v_add_f32_e32 v116, v116, v120
	v_cndmask_b32_e64 v120, v117, v119, s[2:3]
	v_cndmask_b32_e64 v117, v119, v117, s[2:3]
	v_mov_b32_e32 v119, v120
	v_pk_mul_f32 v[122:123], v[82:83], v[104:105]
	s_nop 0
	v_permlane16_swap_b32_e32 v120, v119
	v_cndmask_b32_e64 v119, v120, v119, s[2:3]
	v_add_f32_e32 v117, v117, v119
	v_cndmask_b32_e64 v119, v118, v116, s[2:3]
	v_cndmask_b32_e64 v116, v116, v118, s[2:3]
	v_mov_b32_e32 v118, v119
	v_pk_mul_f32 v[120:121], v[82:83], v[100:101]
	s_nop 0
	v_permlane16_swap_b32_e32 v119, v118
	v_cndmask_b32_e64 v118, v119, v118, s[2:3]
	v_add_f32_e32 v116, v116, v118
	v_cndmask_b32_e64 v118, v117, v116, s[4:5]
	v_cndmask_b32_e64 v116, v116, v117, s[4:5]
	v_pk_mul_f32 v[188:189], v[82:83], v[108:109]
	v_pk_mul_f32 v[190:191], v[82:83], v[110:111]
	v_add_f32_dpp v116, v118, v116 row_ror:8 row_mask:0xf bank_mask:0xf bound_ctrl:1
	v_pk_mul_f32 v[118:119], v[82:83], v[96:97]
	v_pk_mul_f32 v[192:193], v[82:83], v[112:113]
	v_add_f32_dpp v116, v116, v116 quad_perm:[1,0,3,2] row_mask:0xf bank_mask:0xf bound_ctrl:1
	v_pk_fma_f32 v[118:119], v[80:81], v[86:87], v[118:119]
	v_pk_fma_f32 v[120:121], v[80:81], v[88:89], v[120:121]
	v_add_f32_dpp v116, v116, v116 quad_perm:[2,3,0,1] row_mask:0xf bank_mask:0xf bound_ctrl:1
	v_pk_fma_f32 v[122:123], v[80:81], v[90:91], v[122:123]
	v_pk_fma_f32 v[188:189], v[80:81], v[94:95], v[188:189]
	v_add_f32_dpp v186, v116, v116 row_half_mirror row_mask:0xf bank_mask:0xf bound_ctrl:1
	v_pk_mul_f32 v[116:117], v[82:83], v[92:93]
	v_pk_mul_f32 v[82:83], v[82:83], v[114:115]
	v_pk_fma_f32 v[116:117], v[80:81], v[84:85], v[116:117]
	v_pk_fma_f32 v[190:191], v[80:81], v[98:99], v[190:191]
	v_pk_fma_f32 v[192:193], v[80:81], v[102:103], v[192:193]
	v_pk_fma_f32 v[80:81], v[80:81], v[106:107], v[82:83]
	v_pk_add_f32 v[116:117], v[116:117], v[116:117] op_sel:[0,1] op_sel_hi:[1,0]
	v_pk_add_f32 v[188:189], v[188:189], v[188:189] op_sel:[0,1] op_sel_hi:[1,0]
	v_pk_add_f32 v[80:81], v[80:81], v[80:81] op_sel:[0,1] op_sel_hi:[1,0]
	v_pk_add_f32 v[118:119], v[118:119], v[118:119] op_sel:[0,1] op_sel_hi:[1,0]
	v_cndmask_b32_e32 v81, v188, v116, vcc
	v_mov_b32_e32 v83, v81
	v_pk_add_f32 v[190:191], v[190:191], v[190:191] op_sel:[0,1] op_sel_hi:[1,0]
	s_nop 0
	v_permlane32_swap_b32_e32 v81, v83
	v_cndmask_b32_e32 v82, v116, v188, vcc
	v_cndmask_b32_e32 v81, v83, v81, vcc
	v_add_f32_e32 v81, v82, v81
	v_cndmask_b32_e32 v82, v190, v118, vcc
	v_mov_b32_e32 v116, v82
	v_pk_add_f32 v[120:121], v[120:121], v[120:121] op_sel:[0,1] op_sel_hi:[1,0]
	s_nop 0
	v_permlane32_swap_b32_e32 v82, v116
	v_pk_add_f32 v[192:193], v[192:193], v[192:193] op_sel:[0,1] op_sel_hi:[1,0]
	v_cndmask_b32_e32 v83, v118, v190, vcc
	v_cndmask_b32_e32 v82, v116, v82, vcc
	v_add_f32_e32 v82, v83, v82
	v_cndmask_b32_e32 v83, v192, v120, vcc
	v_mov_b32_e32 v117, v83
	v_pk_add_f32 v[122:123], v[122:123], v[122:123] op_sel:[0,1] op_sel_hi:[1,0]
	s_nop 0
	v_permlane32_swap_b32_e32 v83, v117
	v_cndmask_b32_e32 v116, v120, v192, vcc
	v_cndmask_b32_e32 v83, v117, v83, vcc
	v_add_f32_e32 v83, v116, v83
	v_cndmask_b32_e32 v116, v80, v122, vcc
	v_mov_b32_e32 v117, v116
	v_cndmask_b32_e32 v80, v122, v80, vcc
	s_nop 0
	v_permlane32_swap_b32_e32 v116, v117
	v_cndmask_b32_e32 v116, v117, v116, vcc
	v_add_f32_e32 v80, v80, v116
	v_cndmask_b32_e64 v116, v81, v83, s[2:3]
	v_cndmask_b32_e64 v81, v83, v81, s[2:3]
	v_mov_b32_e32 v83, v116
	v_pk_mul_f32 v[118:119], v[78:79], v[104:105]
	s_nop 0
	v_permlane16_swap_b32_e32 v116, v83
	v_cndmask_b32_e64 v83, v116, v83, s[2:3]
	v_add_f32_e32 v81, v81, v83
	v_cndmask_b32_e64 v83, v82, v80, s[2:3]
	v_cndmask_b32_e64 v80, v80, v82, s[2:3]
	v_mov_b32_e32 v82, v83
	v_pk_mul_f32 v[116:117], v[78:79], v[100:101]
	s_nop 0
	v_permlane16_swap_b32_e32 v83, v82
	v_cndmask_b32_e64 v82, v83, v82, s[2:3]
	v_add_f32_e32 v80, v80, v82
	v_cndmask_b32_e64 v82, v81, v80, s[4:5]
	v_cndmask_b32_e64 v80, v80, v81, s[4:5]
	v_pk_mul_f32 v[120:121], v[78:79], v[108:109]
	v_pk_mul_f32 v[122:123], v[78:79], v[110:111]
	v_add_f32_dpp v80, v82, v80 row_ror:8 row_mask:0xf bank_mask:0xf bound_ctrl:1
	v_pk_mul_f32 v[82:83], v[78:79], v[96:97]
	v_pk_mul_f32 v[188:189], v[78:79], v[112:113]
	v_add_f32_dpp v80, v80, v80 quad_perm:[1,0,3,2] row_mask:0xf bank_mask:0xf bound_ctrl:1
	v_pk_fma_f32 v[82:83], v[76:77], v[86:87], v[82:83]
	v_pk_fma_f32 v[116:117], v[76:77], v[88:89], v[116:117]
	v_add_f32_dpp v80, v80, v80 quad_perm:[2,3,0,1] row_mask:0xf bank_mask:0xf bound_ctrl:1
	v_pk_fma_f32 v[118:119], v[76:77], v[90:91], v[118:119]
	v_pk_fma_f32 v[120:121], v[76:77], v[94:95], v[120:121]
	v_add_f32_dpp v190, v80, v80 row_half_mirror row_mask:0xf bank_mask:0xf bound_ctrl:1
	v_pk_mul_f32 v[80:81], v[78:79], v[92:93]
	v_pk_mul_f32 v[78:79], v[78:79], v[114:115]
	v_pk_fma_f32 v[80:81], v[76:77], v[84:85], v[80:81]
	v_pk_fma_f32 v[122:123], v[76:77], v[98:99], v[122:123]
	v_pk_fma_f32 v[188:189], v[76:77], v[102:103], v[188:189]
	v_pk_fma_f32 v[76:77], v[76:77], v[106:107], v[78:79]
	v_pk_add_f32 v[80:81], v[80:81], v[80:81] op_sel:[0,1] op_sel_hi:[1,0]
	v_pk_add_f32 v[120:121], v[120:121], v[120:121] op_sel:[0,1] op_sel_hi:[1,0]
	v_pk_add_f32 v[76:77], v[76:77], v[76:77] op_sel:[0,1] op_sel_hi:[1,0]
	v_pk_add_f32 v[82:83], v[82:83], v[82:83] op_sel:[0,1] op_sel_hi:[1,0]
	v_cndmask_b32_e32 v77, v120, v80, vcc
	v_mov_b32_e32 v79, v77
	v_pk_add_f32 v[122:123], v[122:123], v[122:123] op_sel:[0,1] op_sel_hi:[1,0]
	s_nop 0
	v_permlane32_swap_b32_e32 v77, v79
	v_cndmask_b32_e32 v78, v80, v120, vcc
	v_cndmask_b32_e32 v77, v79, v77, vcc
	v_add_f32_e32 v77, v78, v77
	v_cndmask_b32_e32 v78, v122, v82, vcc
	v_mov_b32_e32 v80, v78
	v_pk_add_f32 v[116:117], v[116:117], v[116:117] op_sel:[0,1] op_sel_hi:[1,0]
	s_nop 0
	v_permlane32_swap_b32_e32 v78, v80
	v_pk_add_f32 v[188:189], v[188:189], v[188:189] op_sel:[0,1] op_sel_hi:[1,0]
	v_cndmask_b32_e32 v79, v82, v122, vcc
	v_cndmask_b32_e32 v78, v80, v78, vcc
	v_add_f32_e32 v78, v79, v78
	v_cndmask_b32_e32 v79, v188, v116, vcc
	v_mov_b32_e32 v81, v79
	v_pk_add_f32 v[118:119], v[118:119], v[118:119] op_sel:[0,1] op_sel_hi:[1,0]
	s_nop 0
	v_permlane32_swap_b32_e32 v79, v81
	v_cndmask_b32_e32 v80, v116, v188, vcc
	v_cndmask_b32_e32 v79, v81, v79, vcc
	v_add_f32_e32 v79, v80, v79
	v_cndmask_b32_e32 v80, v76, v118, vcc
	v_mov_b32_e32 v81, v80
	v_cndmask_b32_e32 v76, v118, v76, vcc
	s_nop 0
	v_permlane32_swap_b32_e32 v80, v81
	v_cndmask_b32_e32 v80, v81, v80, vcc
	v_add_f32_e32 v76, v76, v80
	v_cndmask_b32_e64 v80, v77, v79, s[2:3]
	v_cndmask_b32_e64 v77, v79, v77, s[2:3]
	v_mov_b32_e32 v79, v80
	v_pk_mul_f32 v[82:83], v[74:75], v[104:105]
	s_nop 0
	v_permlane16_swap_b32_e32 v80, v79
	v_cndmask_b32_e64 v79, v80, v79, s[2:3]
	v_add_f32_e32 v77, v77, v79
	v_cndmask_b32_e64 v79, v78, v76, s[2:3]
	v_cndmask_b32_e64 v76, v76, v78, s[2:3]
	v_mov_b32_e32 v78, v79
	v_pk_mul_f32 v[80:81], v[74:75], v[100:101]
	s_nop 0
	v_permlane16_swap_b32_e32 v79, v78
	v_cndmask_b32_e64 v78, v79, v78, s[2:3]
	v_add_f32_e32 v76, v76, v78
	v_cndmask_b32_e64 v78, v77, v76, s[4:5]
	v_cndmask_b32_e64 v76, v76, v77, s[4:5]
	v_pk_mul_f32 v[116:117], v[74:75], v[108:109]
	v_pk_mul_f32 v[118:119], v[74:75], v[110:111]
	v_add_f32_dpp v76, v78, v76 row_ror:8 row_mask:0xf bank_mask:0xf bound_ctrl:1
	v_pk_mul_f32 v[78:79], v[74:75], v[96:97]
	v_pk_mul_f32 v[120:121], v[74:75], v[112:113]
	v_add_f32_dpp v76, v76, v76 quad_perm:[1,0,3,2] row_mask:0xf bank_mask:0xf bound_ctrl:1
	v_pk_fma_f32 v[78:79], v[72:73], v[86:87], v[78:79]
	v_pk_fma_f32 v[80:81], v[72:73], v[88:89], v[80:81]
	v_add_f32_dpp v76, v76, v76 quad_perm:[2,3,0,1] row_mask:0xf bank_mask:0xf bound_ctrl:1
	v_pk_fma_f32 v[82:83], v[72:73], v[90:91], v[82:83]
	v_pk_fma_f32 v[116:117], v[72:73], v[94:95], v[116:117]
	v_add_f32_dpp v188, v76, v76 row_half_mirror row_mask:0xf bank_mask:0xf bound_ctrl:1
	v_pk_mul_f32 v[76:77], v[74:75], v[92:93]
	v_pk_mul_f32 v[74:75], v[74:75], v[114:115]
	v_pk_fma_f32 v[76:77], v[72:73], v[84:85], v[76:77]
	v_pk_fma_f32 v[118:119], v[72:73], v[98:99], v[118:119]
	v_pk_fma_f32 v[120:121], v[72:73], v[102:103], v[120:121]
	v_pk_fma_f32 v[72:73], v[72:73], v[106:107], v[74:75]
	v_pk_add_f32 v[76:77], v[76:77], v[76:77] op_sel:[0,1] op_sel_hi:[1,0]
	v_pk_add_f32 v[116:117], v[116:117], v[116:117] op_sel:[0,1] op_sel_hi:[1,0]
	v_pk_add_f32 v[72:73], v[72:73], v[72:73] op_sel:[0,1] op_sel_hi:[1,0]
	v_pk_add_f32 v[78:79], v[78:79], v[78:79] op_sel:[0,1] op_sel_hi:[1,0]
	v_cndmask_b32_e32 v73, v116, v76, vcc
	v_mov_b32_e32 v75, v73
	v_pk_add_f32 v[118:119], v[118:119], v[118:119] op_sel:[0,1] op_sel_hi:[1,0]
	s_nop 0
	v_permlane32_swap_b32_e32 v73, v75
	v_cndmask_b32_e32 v74, v76, v116, vcc
	v_cndmask_b32_e32 v73, v75, v73, vcc
	v_add_f32_e32 v73, v74, v73
	v_cndmask_b32_e32 v74, v118, v78, vcc
	v_mov_b32_e32 v76, v74
	v_pk_add_f32 v[80:81], v[80:81], v[80:81] op_sel:[0,1] op_sel_hi:[1,0]
	s_nop 0
	v_permlane32_swap_b32_e32 v74, v76
	v_pk_add_f32 v[120:121], v[120:121], v[120:121] op_sel:[0,1] op_sel_hi:[1,0]
	v_cndmask_b32_e32 v75, v78, v118, vcc
	v_cndmask_b32_e32 v74, v76, v74, vcc
	v_add_f32_e32 v74, v75, v74
	v_cndmask_b32_e32 v75, v120, v80, vcc
	v_mov_b32_e32 v77, v75
	v_pk_add_f32 v[82:83], v[82:83], v[82:83] op_sel:[0,1] op_sel_hi:[1,0]
	s_nop 0
	v_permlane32_swap_b32_e32 v75, v77
	v_cndmask_b32_e32 v76, v80, v120, vcc
	v_cndmask_b32_e32 v75, v77, v75, vcc
	v_add_f32_e32 v75, v76, v75
	v_cndmask_b32_e32 v76, v72, v82, vcc
	v_mov_b32_e32 v77, v76
	v_cndmask_b32_e32 v72, v82, v72, vcc
	s_nop 0
	v_permlane32_swap_b32_e32 v76, v77
	v_cndmask_b32_e32 v76, v77, v76, vcc
	v_add_f32_e32 v72, v72, v76
	v_cndmask_b32_e64 v76, v73, v75, s[2:3]
	v_cndmask_b32_e64 v73, v75, v73, s[2:3]
	v_mov_b32_e32 v75, v76
	v_pk_mul_f32 v[78:79], v[70:71], v[104:105]
	s_nop 0
	v_permlane16_swap_b32_e32 v76, v75
	v_cndmask_b32_e64 v75, v76, v75, s[2:3]
	v_add_f32_e32 v73, v73, v75
	v_cndmask_b32_e64 v75, v74, v72, s[2:3]
	v_cndmask_b32_e64 v72, v72, v74, s[2:3]
	v_mov_b32_e32 v74, v75
	v_pk_mul_f32 v[76:77], v[70:71], v[100:101]
	s_nop 0
	v_permlane16_swap_b32_e32 v75, v74
	v_cndmask_b32_e64 v74, v75, v74, s[2:3]
	v_add_f32_e32 v72, v72, v74
	v_cndmask_b32_e64 v74, v73, v72, s[4:5]
	v_cndmask_b32_e64 v72, v72, v73, s[4:5]
	v_pk_mul_f32 v[80:81], v[70:71], v[108:109]
	v_pk_mul_f32 v[82:83], v[70:71], v[110:111]
	v_add_f32_dpp v72, v74, v72 row_ror:8 row_mask:0xf bank_mask:0xf bound_ctrl:1
	v_pk_mul_f32 v[74:75], v[70:71], v[96:97]
	v_pk_mul_f32 v[116:117], v[70:71], v[112:113]
	v_add_f32_dpp v72, v72, v72 quad_perm:[1,0,3,2] row_mask:0xf bank_mask:0xf bound_ctrl:1
	v_pk_fma_f32 v[74:75], v[68:69], v[86:87], v[74:75]
	v_pk_fma_f32 v[76:77], v[68:69], v[88:89], v[76:77]
	v_add_f32_dpp v72, v72, v72 quad_perm:[2,3,0,1] row_mask:0xf bank_mask:0xf bound_ctrl:1
	v_pk_fma_f32 v[78:79], v[68:69], v[90:91], v[78:79]
	v_pk_fma_f32 v[80:81], v[68:69], v[94:95], v[80:81]
	v_add_f32_dpp v192, v72, v72 row_half_mirror row_mask:0xf bank_mask:0xf bound_ctrl:1
	v_pk_mul_f32 v[72:73], v[70:71], v[92:93]
	v_pk_mul_f32 v[70:71], v[70:71], v[114:115]
	v_pk_fma_f32 v[72:73], v[68:69], v[84:85], v[72:73]
	v_pk_fma_f32 v[82:83], v[68:69], v[98:99], v[82:83]
	v_pk_fma_f32 v[116:117], v[68:69], v[102:103], v[116:117]
	v_pk_fma_f32 v[68:69], v[68:69], v[106:107], v[70:71]
	v_pk_add_f32 v[72:73], v[72:73], v[72:73] op_sel:[0,1] op_sel_hi:[1,0]
	v_pk_add_f32 v[80:81], v[80:81], v[80:81] op_sel:[0,1] op_sel_hi:[1,0]
	v_pk_add_f32 v[68:69], v[68:69], v[68:69] op_sel:[0,1] op_sel_hi:[1,0]
	v_pk_add_f32 v[74:75], v[74:75], v[74:75] op_sel:[0,1] op_sel_hi:[1,0]
	v_cndmask_b32_e32 v69, v80, v72, vcc
	v_mov_b32_e32 v71, v69
	v_pk_add_f32 v[82:83], v[82:83], v[82:83] op_sel:[0,1] op_sel_hi:[1,0]
	s_nop 0
	v_permlane32_swap_b32_e32 v69, v71
	v_cndmask_b32_e32 v70, v72, v80, vcc
	v_cndmask_b32_e32 v69, v71, v69, vcc
	v_add_f32_e32 v69, v70, v69
	v_cndmask_b32_e32 v70, v82, v74, vcc
	v_mov_b32_e32 v72, v70
	v_pk_add_f32 v[76:77], v[76:77], v[76:77] op_sel:[0,1] op_sel_hi:[1,0]
	s_nop 0
	v_permlane32_swap_b32_e32 v70, v72
	v_pk_add_f32 v[116:117], v[116:117], v[116:117] op_sel:[0,1] op_sel_hi:[1,0]
	v_cndmask_b32_e32 v71, v74, v82, vcc
	v_cndmask_b32_e32 v70, v72, v70, vcc
	v_add_f32_e32 v70, v71, v70
	v_cndmask_b32_e32 v71, v116, v76, vcc
	v_mov_b32_e32 v73, v71
	v_pk_add_f32 v[78:79], v[78:79], v[78:79] op_sel:[0,1] op_sel_hi:[1,0]
	s_nop 0
	v_permlane32_swap_b32_e32 v71, v73
	v_cndmask_b32_e32 v72, v76, v116, vcc
	v_cndmask_b32_e32 v71, v73, v71, vcc
	v_add_f32_e32 v71, v72, v71
	v_cndmask_b32_e32 v72, v68, v78, vcc
	v_mov_b32_e32 v73, v72
	v_cndmask_b32_e32 v68, v78, v68, vcc
	s_nop 0
	v_permlane32_swap_b32_e32 v72, v73
	v_cndmask_b32_e32 v72, v73, v72, vcc
	v_add_f32_e32 v68, v68, v72
	v_cndmask_b32_e64 v72, v69, v71, s[2:3]
	v_cndmask_b32_e64 v69, v71, v69, s[2:3]
	v_mov_b32_e32 v71, v72
	v_pk_mul_f32 v[74:75], v[66:67], v[104:105]
	s_nop 0
	v_permlane16_swap_b32_e32 v72, v71
	v_cndmask_b32_e64 v71, v72, v71, s[2:3]
	v_add_f32_e32 v69, v69, v71
	v_cndmask_b32_e64 v71, v70, v68, s[2:3]
	v_cndmask_b32_e64 v68, v68, v70, s[2:3]
	v_mov_b32_e32 v70, v71
	v_pk_mul_f32 v[72:73], v[66:67], v[100:101]
	s_nop 0
	v_permlane16_swap_b32_e32 v71, v70
	v_cndmask_b32_e64 v70, v71, v70, s[2:3]
	v_add_f32_e32 v68, v68, v70
	v_cndmask_b32_e64 v70, v69, v68, s[4:5]
	v_cndmask_b32_e64 v68, v68, v69, s[4:5]
	v_pk_mul_f32 v[76:77], v[66:67], v[108:109]
	v_pk_mul_f32 v[78:79], v[66:67], v[110:111]
	v_add_f32_dpp v68, v70, v68 row_ror:8 row_mask:0xf bank_mask:0xf bound_ctrl:1
	v_pk_mul_f32 v[70:71], v[66:67], v[96:97]
	v_pk_mul_f32 v[80:81], v[66:67], v[112:113]
	v_add_f32_dpp v68, v68, v68 quad_perm:[1,0,3,2] row_mask:0xf bank_mask:0xf bound_ctrl:1
	v_pk_fma_f32 v[70:71], v[64:65], v[86:87], v[70:71]
	v_pk_fma_f32 v[72:73], v[64:65], v[88:89], v[72:73]
	v_add_f32_dpp v68, v68, v68 quad_perm:[2,3,0,1] row_mask:0xf bank_mask:0xf bound_ctrl:1
	v_pk_fma_f32 v[74:75], v[64:65], v[90:91], v[74:75]
	v_pk_fma_f32 v[76:77], v[64:65], v[94:95], v[76:77]
	v_add_f32_dpp v215, v68, v68 row_half_mirror row_mask:0xf bank_mask:0xf bound_ctrl:1
	v_pk_mul_f32 v[68:69], v[66:67], v[92:93]
	v_pk_mul_f32 v[66:67], v[66:67], v[114:115]
	v_pk_fma_f32 v[68:69], v[64:65], v[84:85], v[68:69]
	v_pk_fma_f32 v[78:79], v[64:65], v[98:99], v[78:79]
	v_pk_fma_f32 v[80:81], v[64:65], v[102:103], v[80:81]
	v_pk_fma_f32 v[64:65], v[64:65], v[106:107], v[66:67]
	v_pk_add_f32 v[68:69], v[68:69], v[68:69] op_sel:[0,1] op_sel_hi:[1,0]
	v_pk_add_f32 v[76:77], v[76:77], v[76:77] op_sel:[0,1] op_sel_hi:[1,0]
	v_pk_add_f32 v[64:65], v[64:65], v[64:65] op_sel:[0,1] op_sel_hi:[1,0]
	v_pk_add_f32 v[70:71], v[70:71], v[70:71] op_sel:[0,1] op_sel_hi:[1,0]
	v_cndmask_b32_e32 v65, v76, v68, vcc
	v_mov_b32_e32 v67, v65
	v_pk_add_f32 v[78:79], v[78:79], v[78:79] op_sel:[0,1] op_sel_hi:[1,0]
	s_nop 0
	v_permlane32_swap_b32_e32 v65, v67
	v_cndmask_b32_e32 v66, v68, v76, vcc
	v_cndmask_b32_e32 v65, v67, v65, vcc
	v_add_f32_e32 v65, v66, v65
	v_cndmask_b32_e32 v66, v78, v70, vcc
	v_mov_b32_e32 v68, v66
	v_pk_add_f32 v[72:73], v[72:73], v[72:73] op_sel:[0,1] op_sel_hi:[1,0]
	s_nop 0
	v_permlane32_swap_b32_e32 v66, v68
	v_pk_add_f32 v[80:81], v[80:81], v[80:81] op_sel:[0,1] op_sel_hi:[1,0]
	v_cndmask_b32_e32 v67, v70, v78, vcc
	v_cndmask_b32_e32 v66, v68, v66, vcc
	v_add_f32_e32 v66, v67, v66
	v_cndmask_b32_e32 v67, v80, v72, vcc
	v_mov_b32_e32 v69, v67
	v_pk_add_f32 v[74:75], v[74:75], v[74:75] op_sel:[0,1] op_sel_hi:[1,0]
	s_nop 0
	v_permlane32_swap_b32_e32 v67, v69
	v_cndmask_b32_e32 v68, v72, v80, vcc
	v_cndmask_b32_e32 v67, v69, v67, vcc
	v_add_f32_e32 v67, v68, v67
	v_cndmask_b32_e32 v68, v64, v74, vcc
	v_mov_b32_e32 v69, v68
	v_cndmask_b32_e32 v64, v74, v64, vcc
	s_nop 0
	v_permlane32_swap_b32_e32 v68, v69
	v_cndmask_b32_e32 v68, v69, v68, vcc
	v_add_f32_e32 v64, v64, v68
	v_cndmask_b32_e64 v68, v65, v67, s[2:3]
	v_cndmask_b32_e64 v65, v67, v65, s[2:3]
	v_mov_b32_e32 v67, v68
	v_mul_f32_e32 v165, 0x3d800000, v162
	s_nop 0
	v_permlane16_swap_b32_e32 v68, v67
	v_cndmask_b32_e64 v67, v68, v67, s[2:3]
	v_add_f32_e32 v65, v65, v67
	v_cndmask_b32_e64 v67, v66, v64, s[2:3]
	v_cndmask_b32_e64 v64, v64, v66, s[2:3]
	v_mov_b32_e32 v66, v67
	v_max3_f32 v134, v134, v159, v163
	s_nop 0
	v_permlane16_swap_b32_e32 v67, v66
	v_mov_b32_dpp v178, v177 row_half_mirror row_mask:0xf bank_mask:0xf bound_ctrl:1
	v_mov_b32_dpp v179, v168 row_half_mirror row_mask:0xf bank_mask:0xf bound_ctrl:1
	v_mov_b32_dpp v169, v167 row_half_mirror row_mask:0xf bank_mask:0xf bound_ctrl:1
	v_mul_f32_e32 v180, 0x3d800000, v172
	v_mul_f32_e32 v181, 0x3d800000, v173
	v_cndmask_b32_e64 v66, v67, v66, s[2:3]
	v_max3_f32 v134, v134, v164, v165
	v_mov_b32_dpp v174, v166 row_half_mirror row_mask:0xf bank_mask:0xf bound_ctrl:1
	v_add_f32_e32 v167, v167, v169
	v_add_f32_e32 v168, v168, v179
	v_add_f32_e32 v169, v177, v178
	v_mul_f32_e32 v178, 0x3d800000, v170
	v_mul_f32_e32 v179, 0x3d800000, v171
	v_add_f32_e32 v64, v64, v66
	v_max3_f32 v134, v134, v181, v180
	v_add_f32_e32 v166, v166, v174
	v_mul_f32_e32 v176, 0x3d800000, v168
	v_mul_f32_e32 v177, 0x3d800000, v169
	v_cndmask_b32_e64 v66, v65, v64, s[4:5]
	v_cndmask_b32_e64 v64, v64, v65, s[4:5]
	v_max3_f32 v134, v134, v179, v178
	v_mul_f32_e32 v174, 0x3d800000, v166
	v_mul_f32_e32 v175, 0x3d800000, v167
	v_add_f32_dpp v64, v66, v64 row_ror:8 row_mask:0xf bank_mask:0xf bound_ctrl:1
	v_max3_f32 v134, v134, v177, v176
	v_mul_f32_e32 v183, 0x3d800000, v182
	v_mul_f32_e32 v185, 0x3d800000, v184
	v_add_f32_dpp v64, v64, v64 quad_perm:[1,0,3,2] row_mask:0xf bank_mask:0xf bound_ctrl:1
	v_max3_f32 v134, v134, v175, v174
	v_mul_f32_e32 v187, 0x3d800000, v186
	v_mul_f32_e32 v191, 0x3d800000, v190
	v_add_f32_dpp v64, v64, v64 quad_perm:[2,3,0,1] row_mask:0xf bank_mask:0xf bound_ctrl:1
	v_max3_f32 v134, v134, v183, v185
	v_mul_f32_e32 v189, 0x3d800000, v188
	v_mul_f32_e32 v193, 0x3d800000, v192
	v_add_f32_dpp v217, v64, v64 row_half_mirror row_mask:0xf bank_mask:0xf bound_ctrl:1
	v_max3_f32 v134, v134, v187, v191
	v_mul_f32_e32 v216, 0x3d800000, v215
	v_mul_f32_e32 v218, 0x3d800000, v217
	v_max3_f32 v134, v134, v189, v193
	v_max3_f32 v134, v134, v216, v218
	v_fma_f32 v133, v133, s28, -v134
	v_mul_f32_e32 v133, 0x3fb8aa3b, v133
	v_exp_f32_e32 v133, v133
	v_fma_f32 v140, v145, s28, -v134
	v_fma_f32 v144, v153, s28, -v134
	v_fma_f32 v145, v155, s28, -v134
	v_readlane_b32 s0, v133, 0
	v_fma_f32 v152, v171, s28, -v134
	v_fma_f32 v153, v170, s28, -v134
	v_fma_f32 v154, v169, s28, -v134
	v_fma_f32 v155, v168, s28, -v134
	v_pk_fma_f32 v[168:169], v[28:29], s[0:1], 0 op_sel_hi:[1,0,0]
	v_pk_fma_f32 v[170:171], v[30:31], s[0:1], 0 op_sel_hi:[1,0,0]
	v_readlane_b32 s0, v133, 8
	v_fma_f32 v135, v135, s28, -v134
	v_fma_f32 v136, v137, s28, -v134
	v_fma_f32 v137, v139, s28, -v134
	v_fma_f32 v139, v143, s28, -v134
	v_fma_f32 v143, v151, s28, -v134
	v_fma_f32 v150, v173, s28, -v134
	v_fma_f32 v151, v172, s28, -v134
	v_pk_fma_f32 v[172:173], v[28:29], s[0:1], 0 op_sel_hi:[1,0,0]
	v_pk_fma_f32 v[174:175], v[30:31], s[0:1], 0 op_sel_hi:[1,0,0]
	v_readlane_b32 s0, v133, 16
	v_mul_f32_e32 v135, 0x3fb8aa3b, v135
	v_exp_f32_e32 v135, v135
	v_pk_fma_f32 v[176:177], v[28:29], s[0:1], 0 op_sel_hi:[1,0,0]
	v_pk_fma_f32 v[178:179], v[30:31], s[0:1], 0 op_sel_hi:[1,0,0]
	v_readlane_b32 s0, v133, 24
	v_fma_f32 v159, v182, s28, -v134
	v_fma_f32 v147, v160, s28, -v134
	v_pk_fma_f32 v[180:181], v[28:29], s[0:1], 0 op_sel_hi:[1,0,0]
	v_pk_fma_f32 v[182:183], v[30:31], s[0:1], 0 op_sel_hi:[1,0,0]
	v_readlane_b32 s0, v133, 32
	v_fma_f32 v148, v161, s28, -v134
	v_fma_f32 v160, v184, s28, -v134
	v_fma_f32 v161, v186, s28, -v134
	v_pk_fma_f32 v[184:185], v[28:29], s[0:1], 0 op_sel_hi:[1,0,0]
	v_pk_fma_f32 v[186:187], v[30:31], s[0:1], 0 op_sel_hi:[1,0,0]
	v_readlane_b32 s0, v133, 40
	v_fma_f32 v142, v149, s28, -v134
	v_fma_f32 v149, v162, s28, -v134
	v_fma_f32 v162, v190, s28, -v134
	v_fma_f32 v163, v188, s28, -v134
	v_pk_fma_f32 v[188:189], v[28:29], s[0:1], 0 op_sel_hi:[1,0,0]
	v_pk_fma_f32 v[190:191], v[30:31], s[0:1], 0 op_sel_hi:[1,0,0]
	v_readlane_b32 s0, v133, 48
	v_fma_f32 v138, v141, s28, -v134
	v_fma_f32 v141, v146, s28, -v134
	v_fma_f32 v146, v158, s28, -v134
	v_fma_f32 v158, v166, s28, -v134
	v_fma_f32 v164, v192, s28, -v134
	v_fma_f32 v166, v217, s28, -v134
	v_pk_fma_f32 v[192:193], v[28:29], s[0:1], 0 op_sel_hi:[1,0,0]
	v_pk_fma_f32 v[216:217], v[30:31], s[0:1], 0 op_sel_hi:[1,0,0]
	v_readlane_b32 s0, v133, 56
	v_mul_f32_e32 v136, 0x3fb8aa3b, v136
	v_exp_f32_e32 v136, v136
	v_pk_fma_f32 v[28:29], v[28:29], s[0:1], 0 op_sel_hi:[1,0,0]
	v_pk_fma_f32 v[30:31], v[30:31], s[0:1], 0 op_sel_hi:[1,0,0]
	v_readlane_b32 s0, v135, 0
	v_mul_f32_e32 v137, 0x3fb8aa3b, v137
	v_exp_f32_e32 v137, v137
	v_pk_fma_f32 v[170:171], v[26:27], s[0:1], v[170:171] op_sel_hi:[1,0,1]
	v_pk_fma_f32 v[168:169], v[24:25], s[0:1], v[168:169] op_sel_hi:[1,0,1]
	v_readlane_b32 s0, v135, 8
	v_mul_f32_e32 v138, 0x3fb8aa3b, v138
	v_exp_f32_e32 v138, v138
	v_pk_fma_f32 v[174:175], v[26:27], s[0:1], v[174:175] op_sel_hi:[1,0,1]
	v_pk_fma_f32 v[172:173], v[24:25], s[0:1], v[172:173] op_sel_hi:[1,0,1]
	v_readlane_b32 s0, v135, 16
	v_add_co_u32_e32 v64, vcc, s47, v124
	s_nop 0
	v_pk_fma_f32 v[178:179], v[26:27], s[0:1], v[178:179] op_sel_hi:[1,0,1]
	v_pk_fma_f32 v[176:177], v[24:25], s[0:1], v[176:177] op_sel_hi:[1,0,1]
	v_readlane_b32 s0, v135, 24
	v_addc_co_u32_e32 v65, vcc, 0, v125, vcc
	s_nop 0
	v_pk_fma_f32 v[182:183], v[26:27], s[0:1], v[182:183] op_sel_hi:[1,0,1]
	v_pk_fma_f32 v[180:181], v[24:25], s[0:1], v[180:181] op_sel_hi:[1,0,1]
	v_readlane_b32 s0, v135, 32
	v_mul_f32_e32 v139, 0x3fb8aa3b, v139
	global_load_dwordx4 v[120:123], v[64:65], off offset:-4096 nt
	global_load_dwordx4 v[116:119], v[64:65], off nt
	v_pk_fma_f32 v[186:187], v[26:27], s[0:1], v[186:187] op_sel_hi:[1,0,1]
	v_pk_fma_f32 v[184:185], v[24:25], s[0:1], v[184:185] op_sel_hi:[1,0,1]
	v_readlane_b32 s0, v135, 40
	v_add_co_u32_e32 v64, vcc, s40, v124
	s_nop 0
	v_pk_fma_f32 v[190:191], v[26:27], s[0:1], v[190:191] op_sel_hi:[1,0,1]
	v_pk_fma_f32 v[188:189], v[24:25], s[0:1], v[188:189] op_sel_hi:[1,0,1]
	v_readlane_b32 s0, v135, 48
	v_exp_f32_e32 v139, v139
	v_addc_co_u32_e32 v65, vcc, 0, v125, vcc
	v_pk_fma_f32 v[216:217], v[26:27], s[0:1], v[216:217] op_sel_hi:[1,0,1]
	v_pk_fma_f32 v[192:193], v[24:25], s[0:1], v[192:193] op_sel_hi:[1,0,1]
	v_readlane_b32 s0, v135, 56
	global_load_dwordx4 v[112:115], v[64:65], off offset:-4096 nt
	global_load_dwordx4 v[108:111], v[64:65], off nt
	v_pk_fma_f32 v[26:27], v[26:27], s[0:1], v[30:31] op_sel_hi:[1,0,1]
	v_pk_fma_f32 v[24:25], v[24:25], s[0:1], v[28:29] op_sel_hi:[1,0,1]
	v_readlane_b32 s0, v136, 0
	v_add_co_u32_e32 v64, vcc, s46, v124
	s_nop 0
	v_pk_fma_f32 v[28:29], v[20:21], s[0:1], v[168:169] op_sel_hi:[1,0,1]
	v_pk_fma_f32 v[30:31], v[22:23], s[0:1], v[170:171] op_sel_hi:[1,0,1]
	v_readlane_b32 s0, v136, 8
	v_addc_co_u32_e32 v65, vcc, 0, v125, vcc
	s_nop 0
	v_pk_fma_f32 v[168:169], v[20:21], s[0:1], v[172:173] op_sel_hi:[1,0,1]
	v_pk_fma_f32 v[170:171], v[22:23], s[0:1], v[174:175] op_sel_hi:[1,0,1]
	v_readlane_b32 s0, v136, 16
	global_load_dwordx4 v[104:107], v[64:65], off offset:-4096 nt
	global_load_dwordx4 v[100:103], v[64:65], off nt
	v_pk_fma_f32 v[172:173], v[20:21], s[0:1], v[176:177] op_sel_hi:[1,0,1]
	v_pk_fma_f32 v[174:175], v[22:23], s[0:1], v[178:179] op_sel_hi:[1,0,1]
	v_readlane_b32 s0, v136, 24
	v_add_co_u32_e32 v64, vcc, s41, v124
	s_nop 0
	v_pk_fma_f32 v[176:177], v[20:21], s[0:1], v[180:181] op_sel_hi:[1,0,1]
	v_pk_fma_f32 v[178:179], v[22:23], s[0:1], v[182:183] op_sel_hi:[1,0,1]
	v_readlane_b32 s0, v136, 32
	v_addc_co_u32_e32 v65, vcc, 0, v125, vcc
	s_nop 0
	v_pk_fma_f32 v[180:181], v[20:21], s[0:1], v[184:185] op_sel_hi:[1,0,1]
	v_pk_fma_f32 v[182:183], v[22:23], s[0:1], v[186:187] op_sel_hi:[1,0,1]
	v_readlane_b32 s0, v136, 40
	global_load_dwordx4 v[96:99], v[64:65], off offset:-4096 nt
	global_load_dwordx4 v[92:95], v[64:65], off nt
	v_pk_fma_f32 v[184:185], v[20:21], s[0:1], v[188:189] op_sel_hi:[1,0,1]
	v_pk_fma_f32 v[186:187], v[22:23], s[0:1], v[190:191] op_sel_hi:[1,0,1]
	v_readlane_b32 s0, v136, 48
	v_add_co_u32_e32 v64, vcc, s50, v124
	s_nop 0
	v_pk_fma_f32 v[188:189], v[20:21], s[0:1], v[192:193] op_sel_hi:[1,0,1]
	v_pk_fma_f32 v[190:191], v[22:23], s[0:1], v[216:217] op_sel_hi:[1,0,1]
	v_readlane_b32 s0, v136, 56
	v_addc_co_u32_e32 v65, vcc, 0, v125, vcc
	s_nop 0
	v_pk_fma_f32 v[20:21], v[20:21], s[0:1], v[24:25] op_sel_hi:[1,0,1]
	v_pk_fma_f32 v[22:23], v[22:23], s[0:1], v[26:27] op_sel_hi:[1,0,1]
	v_readlane_b32 s0, v137, 0
	v_mul_f32_e32 v140, 0x3fb8aa3b, v140
	global_load_dwordx4 v[88:91], v[64:65], off offset:-4096 nt
	global_load_dwordx4 v[84:87], v[64:65], off nt
	v_pk_fma_f32 v[24:25], v[18:19], s[0:1], v[30:31] op_sel_hi:[1,0,1]
	v_pk_fma_f32 v[26:27], v[16:17], s[0:1], v[28:29] op_sel_hi:[1,0,1]
	v_readlane_b32 s0, v137, 8
	v_add_co_u32_e32 v64, vcc, s42, v124
	s_nop 0
	v_pk_fma_f32 v[28:29], v[18:19], s[0:1], v[170:171] op_sel_hi:[1,0,1]
	v_pk_fma_f32 v[30:31], v[16:17], s[0:1], v[168:169] op_sel_hi:[1,0,1]
	v_readlane_b32 s0, v137, 16
	v_exp_f32_e32 v140, v140
	v_addc_co_u32_e32 v65, vcc, 0, v125, vcc
	v_pk_fma_f32 v[168:169], v[18:19], s[0:1], v[174:175] op_sel_hi:[1,0,1]
	v_pk_fma_f32 v[170:171], v[16:17], s[0:1], v[172:173] op_sel_hi:[1,0,1]
	v_readlane_b32 s0, v137, 24
	global_load_dwordx4 v[80:83], v[64:65], off offset:-4096 nt
	global_load_dwordx4 v[76:79], v[64:65], off nt
	v_pk_fma_f32 v[172:173], v[18:19], s[0:1], v[178:179] op_sel_hi:[1,0,1]
	v_pk_fma_f32 v[174:175], v[16:17], s[0:1], v[176:177] op_sel_hi:[1,0,1]
	v_readlane_b32 s0, v137, 32
	v_add_co_u32_e32 v64, vcc, s49, v124
	s_nop 0
	v_pk_fma_f32 v[176:177], v[18:19], s[0:1], v[182:183] op_sel_hi:[1,0,1]
	v_pk_fma_f32 v[178:179], v[16:17], s[0:1], v[180:181] op_sel_hi:[1,0,1]
	v_readlane_b32 s0, v137, 40
	v_addc_co_u32_e32 v65, vcc, 0, v125, vcc
	s_nop 0
	v_pk_fma_f32 v[180:181], v[18:19], s[0:1], v[186:187] op_sel_hi:[1,0,1]
	v_pk_fma_f32 v[182:183], v[16:17], s[0:1], v[184:185] op_sel_hi:[1,0,1]
	v_readlane_b32 s0, v137, 48
	global_load_dwordx4 v[72:75], v[64:65], off offset:-4096 nt
	global_load_dwordx4 v[68:71], v[64:65], off nt
	v_pk_fma_f32 v[184:185], v[18:19], s[0:1], v[190:191] op_sel_hi:[1,0,1]
	v_pk_fma_f32 v[186:187], v[16:17], s[0:1], v[188:189] op_sel_hi:[1,0,1]
	v_readlane_b32 s0, v137, 56
	v_add_co_u32_e32 v64, vcc, s48, v124
	s_nop 0
	v_pk_fma_f32 v[18:19], v[18:19], s[0:1], v[22:23] op_sel_hi:[1,0,1]
	v_pk_fma_f32 v[16:17], v[16:17], s[0:1], v[20:21] op_sel_hi:[1,0,1]
	v_readlane_b32 s0, v138, 0
	v_addc_co_u32_e32 v65, vcc, 0, v125, vcc
	s_nop 0
	v_pk_fma_f32 v[20:21], v[12:13], s[0:1], v[26:27] op_sel_hi:[1,0,1]
	v_pk_fma_f32 v[22:23], v[14:15], s[0:1], v[24:25] op_sel_hi:[1,0,1]
	v_readlane_b32 s0, v138, 8
	global_load_dwordx4 v[124:127], v[126:127], off nt
	s_nop 0
	global_load_dwordx4 v[64:67], v[64:65], off nt
	v_pk_fma_f32 v[24:25], v[12:13], s[0:1], v[30:31] op_sel_hi:[1,0,1]
	v_pk_fma_f32 v[26:27], v[14:15], s[0:1], v[28:29] op_sel_hi:[1,0,1]
	v_readlane_b32 s0, v138, 16
	v_mul_f32_e32 v141, 0x3fb8aa3b, v141
	v_exp_f32_e32 v141, v141
	v_pk_fma_f32 v[28:29], v[12:13], s[0:1], v[170:171] op_sel_hi:[1,0,1]
	v_pk_fma_f32 v[30:31], v[14:15], s[0:1], v[168:169] op_sel_hi:[1,0,1]
	v_readlane_b32 s0, v138, 24
	v_mul_f32_e32 v142, 0x3fb8aa3b, v142
	v_exp_f32_e32 v142, v142
	v_pk_fma_f32 v[168:169], v[12:13], s[0:1], v[174:175] op_sel_hi:[1,0,1]
	v_pk_fma_f32 v[170:171], v[14:15], s[0:1], v[172:173] op_sel_hi:[1,0,1]
	v_readlane_b32 s0, v138, 32
	v_mul_f32_e32 v143, 0x3fb8aa3b, v143
	v_exp_f32_e32 v143, v143
	v_pk_fma_f32 v[172:173], v[12:13], s[0:1], v[178:179] op_sel_hi:[1,0,1]
	v_pk_fma_f32 v[174:175], v[14:15], s[0:1], v[176:177] op_sel_hi:[1,0,1]
	v_readlane_b32 s0, v138, 40
	v_mul_f32_e32 v144, 0x3fb8aa3b, v144
	v_exp_f32_e32 v144, v144
	v_pk_fma_f32 v[176:177], v[12:13], s[0:1], v[182:183] op_sel_hi:[1,0,1]
	v_pk_fma_f32 v[178:179], v[14:15], s[0:1], v[180:181] op_sel_hi:[1,0,1]
	v_readlane_b32 s0, v138, 48
	v_mul_f32_e32 v145, 0x3fb8aa3b, v145
	v_exp_f32_e32 v145, v145
	v_pk_fma_f32 v[180:181], v[12:13], s[0:1], v[186:187] op_sel_hi:[1,0,1]
	v_pk_fma_f32 v[182:183], v[14:15], s[0:1], v[184:185] op_sel_hi:[1,0,1]
	v_readlane_b32 s0, v138, 56
	v_mul_f32_e32 v146, 0x3fb8aa3b, v146
	v_exp_f32_e32 v146, v146
	v_pk_fma_f32 v[12:13], v[12:13], s[0:1], v[16:17] op_sel_hi:[1,0,1]
	v_pk_fma_f32 v[14:15], v[14:15], s[0:1], v[18:19] op_sel_hi:[1,0,1]
	v_readlane_b32 s0, v139, 0
	v_mul_f32_e32 v147, 0x3fb8aa3b, v147
	v_exp_f32_e32 v147, v147
	v_pk_fma_f32 v[16:17], v[10:11], s[0:1], v[22:23] op_sel_hi:[1,0,1]
	v_pk_fma_f32 v[18:19], v[8:9], s[0:1], v[20:21] op_sel_hi:[1,0,1]
	v_readlane_b32 s0, v139, 8
	v_mul_f32_e32 v148, 0x3fb8aa3b, v148
	v_exp_f32_e32 v148, v148
	v_pk_fma_f32 v[20:21], v[10:11], s[0:1], v[26:27] op_sel_hi:[1,0,1]
	v_pk_fma_f32 v[22:23], v[8:9], s[0:1], v[24:25] op_sel_hi:[1,0,1]
	v_readlane_b32 s0, v139, 16
	v_mul_f32_e32 v149, 0x3fb8aa3b, v149
	v_exp_f32_e32 v149, v149
	v_pk_fma_f32 v[24:25], v[10:11], s[0:1], v[30:31] op_sel_hi:[1,0,1]
	v_pk_fma_f32 v[26:27], v[8:9], s[0:1], v[28:29] op_sel_hi:[1,0,1]
	v_readlane_b32 s0, v139, 24
	v_mul_f32_e32 v150, 0x3fb8aa3b, v150
	v_exp_f32_e32 v150, v150
	v_pk_fma_f32 v[28:29], v[10:11], s[0:1], v[170:171] op_sel_hi:[1,0,1]
	v_pk_fma_f32 v[30:31], v[8:9], s[0:1], v[168:169] op_sel_hi:[1,0,1]
	v_readlane_b32 s0, v139, 32
	v_mul_f32_e32 v151, 0x3fb8aa3b, v151
	v_exp_f32_e32 v151, v151
	v_pk_fma_f32 v[168:169], v[10:11], s[0:1], v[174:175] op_sel_hi:[1,0,1]
	v_pk_fma_f32 v[170:171], v[8:9], s[0:1], v[172:173] op_sel_hi:[1,0,1]
	v_readlane_b32 s0, v139, 40
	v_mul_f32_e32 v152, 0x3fb8aa3b, v152
	v_exp_f32_e32 v152, v152
	v_pk_fma_f32 v[172:173], v[10:11], s[0:1], v[178:179] op_sel_hi:[1,0,1]
	v_pk_fma_f32 v[174:175], v[8:9], s[0:1], v[176:177] op_sel_hi:[1,0,1]
	v_readlane_b32 s0, v139, 48
	v_mul_f32_e32 v153, 0x3fb8aa3b, v153
	v_exp_f32_e32 v153, v153
	v_pk_fma_f32 v[176:177], v[10:11], s[0:1], v[182:183] op_sel_hi:[1,0,1]
	v_pk_fma_f32 v[178:179], v[8:9], s[0:1], v[180:181] op_sel_hi:[1,0,1]
	v_readlane_b32 s0, v139, 56
	v_mul_f32_e32 v154, 0x3fb8aa3b, v154
	v_exp_f32_e32 v154, v154
	v_pk_fma_f32 v[10:11], v[10:11], s[0:1], v[14:15] op_sel_hi:[1,0,1]
	v_pk_fma_f32 v[8:9], v[8:9], s[0:1], v[12:13] op_sel_hi:[1,0,1]
	v_readlane_b32 s0, v140, 0
	v_mul_f32_e32 v155, 0x3fb8aa3b, v155
	v_exp_f32_e32 v155, v155
	v_pk_fma_f32 v[12:13], v[4:5], s[0:1], v[18:19] op_sel_hi:[1,0,1]
	v_pk_fma_f32 v[14:15], v[6:7], s[0:1], v[16:17] op_sel_hi:[1,0,1]
	v_readlane_b32 s0, v140, 8
	v_fma_f32 v156, v167, s28, -v134
	v_mul_f32_e32 v156, 0x3fb8aa3b, v156
	v_pk_fma_f32 v[16:17], v[4:5], s[0:1], v[22:23] op_sel_hi:[1,0,1]
	v_pk_fma_f32 v[18:19], v[6:7], s[0:1], v[20:21] op_sel_hi:[1,0,1]
	v_readlane_b32 s0, v140, 16
	v_exp_f32_e32 v156, v156
	v_mul_f32_e32 v158, 0x3fb8aa3b, v158
	v_pk_fma_f32 v[20:21], v[4:5], s[0:1], v[26:27] op_sel_hi:[1,0,1]
	v_pk_fma_f32 v[22:23], v[6:7], s[0:1], v[24:25] op_sel_hi:[1,0,1]
	v_readlane_b32 s0, v140, 24
	v_exp_f32_e32 v158, v158
	v_mul_f32_e32 v159, 0x3fb8aa3b, v159
	v_pk_fma_f32 v[24:25], v[4:5], s[0:1], v[30:31] op_sel_hi:[1,0,1]
	v_pk_fma_f32 v[26:27], v[6:7], s[0:1], v[28:29] op_sel_hi:[1,0,1]
	v_readlane_b32 s0, v140, 32
	v_exp_f32_e32 v159, v159
	v_mul_f32_e32 v160, 0x3fb8aa3b, v160
	v_pk_fma_f32 v[28:29], v[4:5], s[0:1], v[170:171] op_sel_hi:[1,0,1]
	v_pk_fma_f32 v[30:31], v[6:7], s[0:1], v[168:169] op_sel_hi:[1,0,1]
	v_readlane_b32 s0, v140, 40
	v_exp_f32_e32 v160, v160
	v_mul_f32_e32 v161, 0x3fb8aa3b, v161
	v_pk_fma_f32 v[168:169], v[4:5], s[0:1], v[174:175] op_sel_hi:[1,0,1]
	v_pk_fma_f32 v[170:171], v[6:7], s[0:1], v[172:173] op_sel_hi:[1,0,1]
	v_readlane_b32 s0, v140, 48
	v_exp_f32_e32 v161, v161
	v_mul_f32_e32 v162, 0x3fb8aa3b, v162
	v_pk_fma_f32 v[172:173], v[4:5], s[0:1], v[178:179] op_sel_hi:[1,0,1]
	v_pk_fma_f32 v[174:175], v[6:7], s[0:1], v[176:177] op_sel_hi:[1,0,1]
	v_readlane_b32 s0, v140, 56
	v_exp_f32_e32 v162, v162
	v_mul_f32_e32 v163, 0x3fb8aa3b, v163
	v_pk_fma_f32 v[4:5], v[4:5], s[0:1], v[8:9] op_sel_hi:[1,0,1]
	v_pk_fma_f32 v[6:7], v[6:7], s[0:1], v[10:11] op_sel_hi:[1,0,1]
	v_readlane_b32 s0, v141, 0
	v_exp_f32_e32 v163, v163
	v_mul_f32_e32 v164, 0x3fb8aa3b, v164
	v_pk_fma_f32 v[8:9], v[2:3], s[0:1], v[14:15] op_sel_hi:[1,0,1]
	v_pk_fma_f32 v[10:11], v[0:1], s[0:1], v[12:13] op_sel_hi:[1,0,1]
	v_readlane_b32 s0, v141, 8
	v_exp_f32_e32 v164, v164
	v_fma_f32 v165, v215, s28, -v134
	v_pk_fma_f32 v[12:13], v[2:3], s[0:1], v[18:19] op_sel_hi:[1,0,1]
	v_pk_fma_f32 v[14:15], v[0:1], s[0:1], v[16:17] op_sel_hi:[1,0,1]
	v_readlane_b32 s0, v141, 16
	v_mul_f32_e32 v165, 0x3fb8aa3b, v165
	v_exp_f32_e32 v165, v165
	v_pk_fma_f32 v[16:17], v[2:3], s[0:1], v[22:23] op_sel_hi:[1,0,1]
	v_pk_fma_f32 v[18:19], v[0:1], s[0:1], v[20:21] op_sel_hi:[1,0,1]
	v_readlane_b32 s0, v141, 24
	v_mul_f32_e32 v166, 0x3fb8aa3b, v166
	v_exp_f32_e32 v166, v166
	v_pk_fma_f32 v[20:21], v[2:3], s[0:1], v[26:27] op_sel_hi:[1,0,1]
	v_pk_fma_f32 v[22:23], v[0:1], s[0:1], v[24:25] op_sel_hi:[1,0,1]
	v_readlane_b32 s0, v141, 32
	s_nop 1
	v_pk_fma_f32 v[24:25], v[2:3], s[0:1], v[30:31] op_sel_hi:[1,0,1]
	v_pk_fma_f32 v[26:27], v[0:1], s[0:1], v[28:29] op_sel_hi:[1,0,1]
	v_readlane_b32 s0, v141, 40
	s_nop 1
	v_pk_fma_f32 v[28:29], v[2:3], s[0:1], v[170:171] op_sel_hi:[1,0,1]
	v_pk_fma_f32 v[30:31], v[0:1], s[0:1], v[168:169] op_sel_hi:[1,0,1]
	v_readlane_b32 s0, v141, 48
	s_nop 1
	v_pk_fma_f32 v[168:169], v[2:3], s[0:1], v[174:175] op_sel_hi:[1,0,1]
	v_pk_fma_f32 v[170:171], v[0:1], s[0:1], v[172:173] op_sel_hi:[1,0,1]
	v_readlane_b32 s0, v141, 56
	s_nop 1
	v_pk_fma_f32 v[2:3], v[2:3], s[0:1], v[6:7] op_sel_hi:[1,0,1]
	v_pk_fma_f32 v[0:1], v[0:1], s[0:1], v[4:5] op_sel_hi:[1,0,1]
	v_readlane_b32 s0, v142, 0
	s_nop 1
	v_pk_fma_f32 v[4:5], v[60:61], s[0:1], v[10:11] op_sel_hi:[1,0,1]
	v_pk_fma_f32 v[6:7], v[62:63], s[0:1], v[8:9] op_sel_hi:[1,0,1]
	v_readlane_b32 s0, v142, 8
	s_nop 1
	v_pk_fma_f32 v[8:9], v[60:61], s[0:1], v[14:15] op_sel_hi:[1,0,1]
	v_pk_fma_f32 v[10:11], v[62:63], s[0:1], v[12:13] op_sel_hi:[1,0,1]
	v_readlane_b32 s0, v142, 16
	s_nop 1
	v_pk_fma_f32 v[12:13], v[60:61], s[0:1], v[18:19] op_sel_hi:[1,0,1]
	v_pk_fma_f32 v[14:15], v[62:63], s[0:1], v[16:17] op_sel_hi:[1,0,1]
	v_readlane_b32 s0, v142, 24
	s_nop 1
	v_pk_fma_f32 v[16:17], v[60:61], s[0:1], v[22:23] op_sel_hi:[1,0,1]
	v_pk_fma_f32 v[18:19], v[62:63], s[0:1], v[20:21] op_sel_hi:[1,0,1]
	v_readlane_b32 s0, v142, 32
	s_nop 1
	v_pk_fma_f32 v[20:21], v[60:61], s[0:1], v[26:27] op_sel_hi:[1,0,1]
	v_pk_fma_f32 v[22:23], v[62:63], s[0:1], v[24:25] op_sel_hi:[1,0,1]
	v_readlane_b32 s0, v142, 40
	s_nop 1
	v_pk_fma_f32 v[24:25], v[60:61], s[0:1], v[30:31] op_sel_hi:[1,0,1]
	v_pk_fma_f32 v[26:27], v[62:63], s[0:1], v[28:29] op_sel_hi:[1,0,1]
	v_readlane_b32 s0, v142, 48
	s_nop 1
	v_pk_fma_f32 v[28:29], v[60:61], s[0:1], v[170:171] op_sel_hi:[1,0,1]
	v_pk_fma_f32 v[30:31], v[62:63], s[0:1], v[168:169] op_sel_hi:[1,0,1]
	v_readlane_b32 s0, v142, 56
	s_nop 1
	v_pk_fma_f32 v[0:1], v[60:61], s[0:1], v[0:1] op_sel_hi:[1,0,1]
	v_pk_fma_f32 v[2:3], v[62:63], s[0:1], v[2:3] op_sel_hi:[1,0,1]
	v_readlane_b32 s0, v143, 0
	s_nop 1
	v_pk_fma_f32 v[6:7], v[58:59], s[0:1], v[6:7] op_sel_hi:[1,0,1]
	v_pk_fma_f32 v[4:5], v[56:57], s[0:1], v[4:5] op_sel_hi:[1,0,1]
	v_readlane_b32 s0, v143, 8
	s_nop 1
	v_pk_fma_f32 v[10:11], v[58:59], s[0:1], v[10:11] op_sel_hi:[1,0,1]
	v_pk_fma_f32 v[8:9], v[56:57], s[0:1], v[8:9] op_sel_hi:[1,0,1]
	v_readlane_b32 s0, v143, 16
	s_nop 1
	v_pk_fma_f32 v[14:15], v[58:59], s[0:1], v[14:15] op_sel_hi:[1,0,1]
	v_pk_fma_f32 v[12:13], v[56:57], s[0:1], v[12:13] op_sel_hi:[1,0,1]
	v_readlane_b32 s0, v143, 24
	s_nop 1
	v_pk_fma_f32 v[18:19], v[58:59], s[0:1], v[18:19] op_sel_hi:[1,0,1]
	v_pk_fma_f32 v[16:17], v[56:57], s[0:1], v[16:17] op_sel_hi:[1,0,1]
	v_readlane_b32 s0, v143, 32
	s_nop 1
	v_pk_fma_f32 v[22:23], v[58:59], s[0:1], v[22:23] op_sel_hi:[1,0,1]
	v_pk_fma_f32 v[20:21], v[56:57], s[0:1], v[20:21] op_sel_hi:[1,0,1]
	v_readlane_b32 s0, v143, 40
	s_nop 1
	v_pk_fma_f32 v[26:27], v[58:59], s[0:1], v[26:27] op_sel_hi:[1,0,1]
	v_pk_fma_f32 v[24:25], v[56:57], s[0:1], v[24:25] op_sel_hi:[1,0,1]
	v_readlane_b32 s0, v143, 48
	s_nop 1
	v_pk_fma_f32 v[30:31], v[58:59], s[0:1], v[30:31] op_sel_hi:[1,0,1]
	v_pk_fma_f32 v[28:29], v[56:57], s[0:1], v[28:29] op_sel_hi:[1,0,1]
	v_readlane_b32 s0, v143, 56
	s_nop 1
	v_pk_fma_f32 v[2:3], v[58:59], s[0:1], v[2:3] op_sel_hi:[1,0,1]
	v_pk_fma_f32 v[0:1], v[56:57], s[0:1], v[0:1] op_sel_hi:[1,0,1]
	v_readlane_b32 s0, v144, 0
	s_nop 1
	v_pk_fma_f32 v[4:5], v[52:53], s[0:1], v[4:5] op_sel_hi:[1,0,1]
	v_pk_fma_f32 v[6:7], v[54:55], s[0:1], v[6:7] op_sel_hi:[1,0,1]
	v_readlane_b32 s0, v144, 8
	s_nop 1
	v_pk_fma_f32 v[8:9], v[52:53], s[0:1], v[8:9] op_sel_hi:[1,0,1]
	v_pk_fma_f32 v[10:11], v[54:55], s[0:1], v[10:11] op_sel_hi:[1,0,1]
	v_readlane_b32 s0, v144, 16
	s_nop 1
	v_pk_fma_f32 v[12:13], v[52:53], s[0:1], v[12:13] op_sel_hi:[1,0,1]
	v_pk_fma_f32 v[14:15], v[54:55], s[0:1], v[14:15] op_sel_hi:[1,0,1]
	v_readlane_b32 s0, v144, 24
	s_nop 1
	v_pk_fma_f32 v[16:17], v[52:53], s[0:1], v[16:17] op_sel_hi:[1,0,1]
	v_pk_fma_f32 v[18:19], v[54:55], s[0:1], v[18:19] op_sel_hi:[1,0,1]
	v_readlane_b32 s0, v144, 32
	s_nop 1
	v_pk_fma_f32 v[20:21], v[52:53], s[0:1], v[20:21] op_sel_hi:[1,0,1]
	v_pk_fma_f32 v[22:23], v[54:55], s[0:1], v[22:23] op_sel_hi:[1,0,1]
	v_readlane_b32 s0, v144, 40
	s_nop 1
	v_pk_fma_f32 v[24:25], v[52:53], s[0:1], v[24:25] op_sel_hi:[1,0,1]
	v_pk_fma_f32 v[26:27], v[54:55], s[0:1], v[26:27] op_sel_hi:[1,0,1]
	v_readlane_b32 s0, v144, 48
	s_nop 1
	v_pk_fma_f32 v[28:29], v[52:53], s[0:1], v[28:29] op_sel_hi:[1,0,1]
	v_pk_fma_f32 v[30:31], v[54:55], s[0:1], v[30:31] op_sel_hi:[1,0,1]
	v_readlane_b32 s0, v144, 56
	s_nop 1
	v_pk_fma_f32 v[0:1], v[52:53], s[0:1], v[0:1] op_sel_hi:[1,0,1]
	v_pk_fma_f32 v[2:3], v[54:55], s[0:1], v[2:3] op_sel_hi:[1,0,1]
	v_readlane_b32 s0, v145, 0
	s_nop 1
	v_pk_fma_f32 v[6:7], v[50:51], s[0:1], v[6:7] op_sel_hi:[1,0,1]
	v_pk_fma_f32 v[4:5], v[48:49], s[0:1], v[4:5] op_sel_hi:[1,0,1]
	v_readlane_b32 s0, v145, 8
	s_nop 1
	v_pk_fma_f32 v[10:11], v[50:51], s[0:1], v[10:11] op_sel_hi:[1,0,1]
	v_pk_fma_f32 v[8:9], v[48:49], s[0:1], v[8:9] op_sel_hi:[1,0,1]
	v_readlane_b32 s0, v145, 16
	s_nop 1
	v_pk_fma_f32 v[14:15], v[50:51], s[0:1], v[14:15] op_sel_hi:[1,0,1]
	v_pk_fma_f32 v[12:13], v[48:49], s[0:1], v[12:13] op_sel_hi:[1,0,1]
	v_readlane_b32 s0, v145, 24
	s_nop 1
	v_pk_fma_f32 v[18:19], v[50:51], s[0:1], v[18:19] op_sel_hi:[1,0,1]
	v_pk_fma_f32 v[16:17], v[48:49], s[0:1], v[16:17] op_sel_hi:[1,0,1]
	v_readlane_b32 s0, v145, 32
	s_nop 1
	v_pk_fma_f32 v[22:23], v[50:51], s[0:1], v[22:23] op_sel_hi:[1,0,1]
	v_pk_fma_f32 v[20:21], v[48:49], s[0:1], v[20:21] op_sel_hi:[1,0,1]
	v_readlane_b32 s0, v145, 40
	s_nop 1
	v_pk_fma_f32 v[26:27], v[50:51], s[0:1], v[26:27] op_sel_hi:[1,0,1]
	v_pk_fma_f32 v[24:25], v[48:49], s[0:1], v[24:25] op_sel_hi:[1,0,1]
	v_readlane_b32 s0, v145, 48
	s_nop 1
	v_pk_fma_f32 v[30:31], v[50:51], s[0:1], v[30:31] op_sel_hi:[1,0,1]
	v_pk_fma_f32 v[28:29], v[48:49], s[0:1], v[28:29] op_sel_hi:[1,0,1]
	v_readlane_b32 s0, v145, 56
	s_nop 1
	v_pk_fma_f32 v[2:3], v[50:51], s[0:1], v[2:3] op_sel_hi:[1,0,1]
	v_pk_fma_f32 v[0:1], v[48:49], s[0:1], v[0:1] op_sel_hi:[1,0,1]
	v_readlane_b32 s0, v146, 0
	s_nop 1
	v_pk_fma_f32 v[4:5], v[44:45], s[0:1], v[4:5] op_sel_hi:[1,0,1]
	v_pk_fma_f32 v[6:7], v[46:47], s[0:1], v[6:7] op_sel_hi:[1,0,1]
	v_readlane_b32 s0, v146, 8
	s_nop 1
	v_pk_fma_f32 v[8:9], v[44:45], s[0:1], v[8:9] op_sel_hi:[1,0,1]
	v_pk_fma_f32 v[10:11], v[46:47], s[0:1], v[10:11] op_sel_hi:[1,0,1]
	v_readlane_b32 s0, v146, 16
	s_nop 1
	v_pk_fma_f32 v[12:13], v[44:45], s[0:1], v[12:13] op_sel_hi:[1,0,1]
	v_pk_fma_f32 v[14:15], v[46:47], s[0:1], v[14:15] op_sel_hi:[1,0,1]
	v_readlane_b32 s0, v146, 24
	s_nop 1
	v_pk_fma_f32 v[16:17], v[44:45], s[0:1], v[16:17] op_sel_hi:[1,0,1]
	v_pk_fma_f32 v[18:19], v[46:47], s[0:1], v[18:19] op_sel_hi:[1,0,1]
	v_readlane_b32 s0, v146, 32
	s_nop 1
	v_pk_fma_f32 v[20:21], v[44:45], s[0:1], v[20:21] op_sel_hi:[1,0,1]
	v_pk_fma_f32 v[22:23], v[46:47], s[0:1], v[22:23] op_sel_hi:[1,0,1]
	v_readlane_b32 s0, v146, 40
	s_nop 1
	v_pk_fma_f32 v[24:25], v[44:45], s[0:1], v[24:25] op_sel_hi:[1,0,1]
	v_pk_fma_f32 v[26:27], v[46:47], s[0:1], v[26:27] op_sel_hi:[1,0,1]
	v_readlane_b32 s0, v146, 48
	s_nop 1
	v_pk_fma_f32 v[28:29], v[44:45], s[0:1], v[28:29] op_sel_hi:[1,0,1]
	v_pk_fma_f32 v[30:31], v[46:47], s[0:1], v[30:31] op_sel_hi:[1,0,1]
	v_readlane_b32 s0, v146, 56
	s_nop 1
	v_pk_fma_f32 v[0:1], v[44:45], s[0:1], v[0:1] op_sel_hi:[1,0,1]
	v_pk_fma_f32 v[2:3], v[46:47], s[0:1], v[2:3] op_sel_hi:[1,0,1]
	v_readlane_b32 s0, v147, 0
	s_nop 1
	v_pk_fma_f32 v[6:7], v[42:43], s[0:1], v[6:7] op_sel_hi:[1,0,1]
	v_pk_fma_f32 v[4:5], v[40:41], s[0:1], v[4:5] op_sel_hi:[1,0,1]
	v_readlane_b32 s0, v147, 8
	s_nop 1
	v_pk_fma_f32 v[10:11], v[42:43], s[0:1], v[10:11] op_sel_hi:[1,0,1]
	v_pk_fma_f32 v[8:9], v[40:41], s[0:1], v[8:9] op_sel_hi:[1,0,1]
	v_readlane_b32 s0, v147, 16
	s_nop 1
	v_pk_fma_f32 v[14:15], v[42:43], s[0:1], v[14:15] op_sel_hi:[1,0,1]
	v_pk_fma_f32 v[12:13], v[40:41], s[0:1], v[12:13] op_sel_hi:[1,0,1]
	v_readlane_b32 s0, v147, 24
	s_nop 1
	v_pk_fma_f32 v[18:19], v[42:43], s[0:1], v[18:19] op_sel_hi:[1,0,1]
	v_pk_fma_f32 v[16:17], v[40:41], s[0:1], v[16:17] op_sel_hi:[1,0,1]
	v_readlane_b32 s0, v147, 32
	s_nop 1
	v_pk_fma_f32 v[22:23], v[42:43], s[0:1], v[22:23] op_sel_hi:[1,0,1]
	v_pk_fma_f32 v[20:21], v[40:41], s[0:1], v[20:21] op_sel_hi:[1,0,1]
	v_readlane_b32 s0, v147, 40
	s_nop 1
	v_pk_fma_f32 v[26:27], v[42:43], s[0:1], v[26:27] op_sel_hi:[1,0,1]
	v_pk_fma_f32 v[24:25], v[40:41], s[0:1], v[24:25] op_sel_hi:[1,0,1]
	v_readlane_b32 s0, v147, 48
	s_nop 1
	v_pk_fma_f32 v[30:31], v[42:43], s[0:1], v[30:31] op_sel_hi:[1,0,1]
	v_pk_fma_f32 v[28:29], v[40:41], s[0:1], v[28:29] op_sel_hi:[1,0,1]
	v_readlane_b32 s0, v147, 56
	s_nop 1
	v_pk_fma_f32 v[2:3], v[42:43], s[0:1], v[2:3] op_sel_hi:[1,0,1]
	v_pk_fma_f32 v[0:1], v[40:41], s[0:1], v[0:1] op_sel_hi:[1,0,1]
	v_readlane_b32 s0, v148, 0
	s_nop 1
	v_pk_fma_f32 v[4:5], v[36:37], s[0:1], v[4:5] op_sel_hi:[1,0,1]
	v_pk_fma_f32 v[6:7], v[38:39], s[0:1], v[6:7] op_sel_hi:[1,0,1]
	v_readlane_b32 s0, v148, 8
	s_nop 1
	v_pk_fma_f32 v[8:9], v[36:37], s[0:1], v[8:9] op_sel_hi:[1,0,1]
	v_pk_fma_f32 v[10:11], v[38:39], s[0:1], v[10:11] op_sel_hi:[1,0,1]
	v_readlane_b32 s0, v148, 16
	s_nop 1
	v_pk_fma_f32 v[12:13], v[36:37], s[0:1], v[12:13] op_sel_hi:[1,0,1]
	v_pk_fma_f32 v[14:15], v[38:39], s[0:1], v[14:15] op_sel_hi:[1,0,1]
	v_readlane_b32 s0, v148, 24
	s_nop 1
	v_pk_fma_f32 v[16:17], v[36:37], s[0:1], v[16:17] op_sel_hi:[1,0,1]
	v_pk_fma_f32 v[18:19], v[38:39], s[0:1], v[18:19] op_sel_hi:[1,0,1]
	v_readlane_b32 s0, v148, 32
	s_nop 1
	v_pk_fma_f32 v[20:21], v[36:37], s[0:1], v[20:21] op_sel_hi:[1,0,1]
	v_pk_fma_f32 v[22:23], v[38:39], s[0:1], v[22:23] op_sel_hi:[1,0,1]
	v_readlane_b32 s0, v148, 40
	s_nop 1
	v_pk_fma_f32 v[24:25], v[36:37], s[0:1], v[24:25] op_sel_hi:[1,0,1]
	v_pk_fma_f32 v[26:27], v[38:39], s[0:1], v[26:27] op_sel_hi:[1,0,1]
	v_readlane_b32 s0, v148, 48
	s_nop 1
	v_pk_fma_f32 v[28:29], v[36:37], s[0:1], v[28:29] op_sel_hi:[1,0,1]
	v_pk_fma_f32 v[30:31], v[38:39], s[0:1], v[30:31] op_sel_hi:[1,0,1]
	v_readlane_b32 s0, v148, 56
	s_nop 1
	v_pk_fma_f32 v[0:1], v[36:37], s[0:1], v[0:1] op_sel_hi:[1,0,1]
	v_pk_fma_f32 v[2:3], v[38:39], s[0:1], v[2:3] op_sel_hi:[1,0,1]
	v_readlane_b32 s0, v149, 0
	s_nop 1
	v_pk_fma_f32 v[6:7], v[34:35], s[0:1], v[6:7] op_sel_hi:[1,0,1]
	v_pk_fma_f32 v[4:5], v[32:33], s[0:1], v[4:5] op_sel_hi:[1,0,1]
	v_readlane_b32 s0, v149, 8
	s_nop 1
	v_pk_fma_f32 v[10:11], v[34:35], s[0:1], v[10:11] op_sel_hi:[1,0,1]
	v_pk_fma_f32 v[8:9], v[32:33], s[0:1], v[8:9] op_sel_hi:[1,0,1]
	v_readlane_b32 s0, v149, 16
	s_nop 1
	v_pk_fma_f32 v[14:15], v[34:35], s[0:1], v[14:15] op_sel_hi:[1,0,1]
	v_pk_fma_f32 v[12:13], v[32:33], s[0:1], v[12:13] op_sel_hi:[1,0,1]
	v_readlane_b32 s0, v149, 24
	s_nop 1
	v_pk_fma_f32 v[18:19], v[34:35], s[0:1], v[18:19] op_sel_hi:[1,0,1]
	v_pk_fma_f32 v[16:17], v[32:33], s[0:1], v[16:17] op_sel_hi:[1,0,1]
	v_readlane_b32 s0, v149, 32
	s_nop 1
	v_pk_fma_f32 v[22:23], v[34:35], s[0:1], v[22:23] op_sel_hi:[1,0,1]
	v_pk_fma_f32 v[20:21], v[32:33], s[0:1], v[20:21] op_sel_hi:[1,0,1]
	v_readlane_b32 s0, v149, 40
	s_nop 1
	v_pk_fma_f32 v[26:27], v[34:35], s[0:1], v[26:27] op_sel_hi:[1,0,1]
	v_pk_fma_f32 v[24:25], v[32:33], s[0:1], v[24:25] op_sel_hi:[1,0,1]
	v_readlane_b32 s0, v149, 48
	s_nop 1
	v_pk_fma_f32 v[30:31], v[34:35], s[0:1], v[30:31] op_sel_hi:[1,0,1]
	v_pk_fma_f32 v[28:29], v[32:33], s[0:1], v[28:29] op_sel_hi:[1,0,1]
	v_readlane_b32 s0, v149, 56
	s_nop 1
	v_pk_fma_f32 v[2:3], v[34:35], s[0:1], v[2:3] op_sel_hi:[1,0,1]
	v_pk_fma_f32 v[0:1], v[32:33], s[0:1], v[0:1] op_sel_hi:[1,0,1]
	v_readlane_b32 s0, v150, 0
	s_waitcnt vmcnt(1)
	s_nop 0
	v_pk_fma_f32 v[4:5], v[124:125], s[0:1], v[4:5] op_sel_hi:[1,0,1]
	v_pk_fma_f32 v[6:7], v[126:127], s[0:1], v[6:7] op_sel_hi:[1,0,1]
	v_readlane_b32 s0, v150, 8
	s_nop 1
	v_pk_fma_f32 v[8:9], v[124:125], s[0:1], v[8:9] op_sel_hi:[1,0,1]
	v_pk_fma_f32 v[10:11], v[126:127], s[0:1], v[10:11] op_sel_hi:[1,0,1]
	v_readlane_b32 s0, v150, 16
	s_nop 1
	v_pk_fma_f32 v[12:13], v[124:125], s[0:1], v[12:13] op_sel_hi:[1,0,1]
	v_pk_fma_f32 v[14:15], v[126:127], s[0:1], v[14:15] op_sel_hi:[1,0,1]
	v_readlane_b32 s0, v150, 24
	s_nop 1
	v_pk_fma_f32 v[16:17], v[124:125], s[0:1], v[16:17] op_sel_hi:[1,0,1]
	v_pk_fma_f32 v[18:19], v[126:127], s[0:1], v[18:19] op_sel_hi:[1,0,1]
	v_readlane_b32 s0, v150, 32
	s_nop 1
	v_pk_fma_f32 v[20:21], v[124:125], s[0:1], v[20:21] op_sel_hi:[1,0,1]
	v_pk_fma_f32 v[22:23], v[126:127], s[0:1], v[22:23] op_sel_hi:[1,0,1]
	v_readlane_b32 s0, v150, 40
	s_nop 1
	v_pk_fma_f32 v[24:25], v[124:125], s[0:1], v[24:25] op_sel_hi:[1,0,1]
	v_pk_fma_f32 v[26:27], v[126:127], s[0:1], v[26:27] op_sel_hi:[1,0,1]
	v_readlane_b32 s0, v150, 48
	s_nop 1
	v_pk_fma_f32 v[28:29], v[124:125], s[0:1], v[28:29] op_sel_hi:[1,0,1]
	v_pk_fma_f32 v[30:31], v[126:127], s[0:1], v[30:31] op_sel_hi:[1,0,1]
	v_readlane_b32 s0, v150, 56
	s_nop 1
	v_pk_fma_f32 v[0:1], v[124:125], s[0:1], v[0:1] op_sel_hi:[1,0,1]
	v_pk_fma_f32 v[2:3], v[126:127], s[0:1], v[2:3] op_sel_hi:[1,0,1]
	v_readlane_b32 s0, v151, 0
	s_nop 1
	v_pk_fma_f32 v[6:7], v[122:123], s[0:1], v[6:7] op_sel_hi:[1,0,1]
	v_pk_fma_f32 v[4:5], v[120:121], s[0:1], v[4:5] op_sel_hi:[1,0,1]
	v_readlane_b32 s0, v151, 8
	s_nop 1
	v_pk_fma_f32 v[10:11], v[122:123], s[0:1], v[10:11] op_sel_hi:[1,0,1]
	v_pk_fma_f32 v[8:9], v[120:121], s[0:1], v[8:9] op_sel_hi:[1,0,1]
	v_readlane_b32 s0, v151, 16
	s_nop 1
	v_pk_fma_f32 v[14:15], v[122:123], s[0:1], v[14:15] op_sel_hi:[1,0,1]
	v_pk_fma_f32 v[12:13], v[120:121], s[0:1], v[12:13] op_sel_hi:[1,0,1]
	v_readlane_b32 s0, v151, 24
	s_nop 1
	v_pk_fma_f32 v[18:19], v[122:123], s[0:1], v[18:19] op_sel_hi:[1,0,1]
	v_pk_fma_f32 v[16:17], v[120:121], s[0:1], v[16:17] op_sel_hi:[1,0,1]
	v_readlane_b32 s0, v151, 32
	s_nop 1
	v_pk_fma_f32 v[22:23], v[122:123], s[0:1], v[22:23] op_sel_hi:[1,0,1]
	v_pk_fma_f32 v[20:21], v[120:121], s[0:1], v[20:21] op_sel_hi:[1,0,1]
	v_readlane_b32 s0, v151, 40
	s_nop 1
	v_pk_fma_f32 v[26:27], v[122:123], s[0:1], v[26:27] op_sel_hi:[1,0,1]
	v_pk_fma_f32 v[24:25], v[120:121], s[0:1], v[24:25] op_sel_hi:[1,0,1]
	v_readlane_b32 s0, v151, 48
	s_nop 1
	v_pk_fma_f32 v[30:31], v[122:123], s[0:1], v[30:31] op_sel_hi:[1,0,1]
	v_pk_fma_f32 v[28:29], v[120:121], s[0:1], v[28:29] op_sel_hi:[1,0,1]
	v_readlane_b32 s0, v151, 56
	s_nop 1
	v_pk_fma_f32 v[2:3], v[122:123], s[0:1], v[2:3] op_sel_hi:[1,0,1]
	v_pk_fma_f32 v[0:1], v[120:121], s[0:1], v[0:1] op_sel_hi:[1,0,1]
	v_readlane_b32 s0, v152, 0
	s_nop 1
	v_pk_fma_f32 v[4:5], v[116:117], s[0:1], v[4:5] op_sel_hi:[1,0,1]
	v_pk_fma_f32 v[6:7], v[118:119], s[0:1], v[6:7] op_sel_hi:[1,0,1]
	v_readlane_b32 s0, v152, 8
	s_nop 1
	v_pk_fma_f32 v[8:9], v[116:117], s[0:1], v[8:9] op_sel_hi:[1,0,1]
	v_pk_fma_f32 v[10:11], v[118:119], s[0:1], v[10:11] op_sel_hi:[1,0,1]
	v_readlane_b32 s0, v152, 16
	s_nop 1
	v_pk_fma_f32 v[12:13], v[116:117], s[0:1], v[12:13] op_sel_hi:[1,0,1]
	v_pk_fma_f32 v[14:15], v[118:119], s[0:1], v[14:15] op_sel_hi:[1,0,1]
	v_readlane_b32 s0, v152, 24
	s_nop 1
	v_pk_fma_f32 v[16:17], v[116:117], s[0:1], v[16:17] op_sel_hi:[1,0,1]
	v_pk_fma_f32 v[18:19], v[118:119], s[0:1], v[18:19] op_sel_hi:[1,0,1]
	v_readlane_b32 s0, v152, 32
	s_nop 1
	v_pk_fma_f32 v[20:21], v[116:117], s[0:1], v[20:21] op_sel_hi:[1,0,1]
	v_pk_fma_f32 v[22:23], v[118:119], s[0:1], v[22:23] op_sel_hi:[1,0,1]
	v_readlane_b32 s0, v152, 40
	s_nop 1
	v_pk_fma_f32 v[24:25], v[116:117], s[0:1], v[24:25] op_sel_hi:[1,0,1]
	v_pk_fma_f32 v[26:27], v[118:119], s[0:1], v[26:27] op_sel_hi:[1,0,1]
	v_readlane_b32 s0, v152, 48
	s_nop 1
	v_pk_fma_f32 v[28:29], v[116:117], s[0:1], v[28:29] op_sel_hi:[1,0,1]
	v_pk_fma_f32 v[30:31], v[118:119], s[0:1], v[30:31] op_sel_hi:[1,0,1]
	v_readlane_b32 s0, v152, 56
	s_nop 1
	v_pk_fma_f32 v[0:1], v[116:117], s[0:1], v[0:1] op_sel_hi:[1,0,1]
	v_pk_fma_f32 v[2:3], v[118:119], s[0:1], v[2:3] op_sel_hi:[1,0,1]
	v_readlane_b32 s0, v153, 0
	s_nop 1
	v_pk_fma_f32 v[6:7], v[114:115], s[0:1], v[6:7] op_sel_hi:[1,0,1]
	v_pk_fma_f32 v[4:5], v[112:113], s[0:1], v[4:5] op_sel_hi:[1,0,1]
	v_readlane_b32 s0, v153, 8
	s_nop 1
	v_pk_fma_f32 v[10:11], v[114:115], s[0:1], v[10:11] op_sel_hi:[1,0,1]
	v_pk_fma_f32 v[8:9], v[112:113], s[0:1], v[8:9] op_sel_hi:[1,0,1]
	v_readlane_b32 s0, v153, 16
	s_nop 1
	v_pk_fma_f32 v[14:15], v[114:115], s[0:1], v[14:15] op_sel_hi:[1,0,1]
	v_pk_fma_f32 v[12:13], v[112:113], s[0:1], v[12:13] op_sel_hi:[1,0,1]
	v_readlane_b32 s0, v153, 24
	s_nop 1
	v_pk_fma_f32 v[18:19], v[114:115], s[0:1], v[18:19] op_sel_hi:[1,0,1]
	v_pk_fma_f32 v[16:17], v[112:113], s[0:1], v[16:17] op_sel_hi:[1,0,1]
	v_readlane_b32 s0, v153, 32
	s_nop 1
	v_pk_fma_f32 v[22:23], v[114:115], s[0:1], v[22:23] op_sel_hi:[1,0,1]
	v_pk_fma_f32 v[20:21], v[112:113], s[0:1], v[20:21] op_sel_hi:[1,0,1]
	v_readlane_b32 s0, v153, 40
	s_nop 1
	v_pk_fma_f32 v[26:27], v[114:115], s[0:1], v[26:27] op_sel_hi:[1,0,1]
	v_pk_fma_f32 v[24:25], v[112:113], s[0:1], v[24:25] op_sel_hi:[1,0,1]
	v_readlane_b32 s0, v153, 48
	s_nop 1
	v_pk_fma_f32 v[30:31], v[114:115], s[0:1], v[30:31] op_sel_hi:[1,0,1]
	v_pk_fma_f32 v[28:29], v[112:113], s[0:1], v[28:29] op_sel_hi:[1,0,1]
	v_readlane_b32 s0, v153, 56
	s_nop 1
	v_pk_fma_f32 v[2:3], v[114:115], s[0:1], v[2:3] op_sel_hi:[1,0,1]
	v_pk_fma_f32 v[0:1], v[112:113], s[0:1], v[0:1] op_sel_hi:[1,0,1]
	v_readlane_b32 s0, v154, 0
	s_nop 1
	v_pk_fma_f32 v[4:5], v[108:109], s[0:1], v[4:5] op_sel_hi:[1,0,1]
	v_pk_fma_f32 v[6:7], v[110:111], s[0:1], v[6:7] op_sel_hi:[1,0,1]
	v_readlane_b32 s0, v154, 8
	s_nop 1
	v_pk_fma_f32 v[8:9], v[108:109], s[0:1], v[8:9] op_sel_hi:[1,0,1]
	v_pk_fma_f32 v[10:11], v[110:111], s[0:1], v[10:11] op_sel_hi:[1,0,1]
	v_readlane_b32 s0, v154, 16
	s_nop 1
	v_pk_fma_f32 v[12:13], v[108:109], s[0:1], v[12:13] op_sel_hi:[1,0,1]
	v_pk_fma_f32 v[14:15], v[110:111], s[0:1], v[14:15] op_sel_hi:[1,0,1]
	v_readlane_b32 s0, v154, 24
	s_nop 1
	v_pk_fma_f32 v[16:17], v[108:109], s[0:1], v[16:17] op_sel_hi:[1,0,1]
	v_pk_fma_f32 v[18:19], v[110:111], s[0:1], v[18:19] op_sel_hi:[1,0,1]
	v_readlane_b32 s0, v154, 32
	s_nop 1
	v_pk_fma_f32 v[20:21], v[108:109], s[0:1], v[20:21] op_sel_hi:[1,0,1]
	v_pk_fma_f32 v[22:23], v[110:111], s[0:1], v[22:23] op_sel_hi:[1,0,1]
	v_readlane_b32 s0, v154, 40
	s_nop 1
	v_pk_fma_f32 v[24:25], v[108:109], s[0:1], v[24:25] op_sel_hi:[1,0,1]
	v_pk_fma_f32 v[26:27], v[110:111], s[0:1], v[26:27] op_sel_hi:[1,0,1]
	v_readlane_b32 s0, v154, 48
	s_nop 1
	v_pk_fma_f32 v[28:29], v[108:109], s[0:1], v[28:29] op_sel_hi:[1,0,1]
	v_pk_fma_f32 v[30:31], v[110:111], s[0:1], v[30:31] op_sel_hi:[1,0,1]
	v_readlane_b32 s0, v154, 56
	s_nop 1
	v_pk_fma_f32 v[0:1], v[108:109], s[0:1], v[0:1] op_sel_hi:[1,0,1]
	v_pk_fma_f32 v[2:3], v[110:111], s[0:1], v[2:3] op_sel_hi:[1,0,1]
	v_readlane_b32 s0, v155, 0
	s_nop 1
	v_pk_fma_f32 v[6:7], v[106:107], s[0:1], v[6:7] op_sel_hi:[1,0,1]
	v_pk_fma_f32 v[4:5], v[104:105], s[0:1], v[4:5] op_sel_hi:[1,0,1]
	v_readlane_b32 s0, v155, 8
	s_nop 1
	v_pk_fma_f32 v[10:11], v[106:107], s[0:1], v[10:11] op_sel_hi:[1,0,1]
	v_pk_fma_f32 v[8:9], v[104:105], s[0:1], v[8:9] op_sel_hi:[1,0,1]
	v_readlane_b32 s0, v155, 16
	s_nop 1
	v_pk_fma_f32 v[14:15], v[106:107], s[0:1], v[14:15] op_sel_hi:[1,0,1]
	v_pk_fma_f32 v[12:13], v[104:105], s[0:1], v[12:13] op_sel_hi:[1,0,1]
	v_readlane_b32 s0, v155, 24
	s_nop 1
	v_pk_fma_f32 v[18:19], v[106:107], s[0:1], v[18:19] op_sel_hi:[1,0,1]
	v_pk_fma_f32 v[16:17], v[104:105], s[0:1], v[16:17] op_sel_hi:[1,0,1]
	v_readlane_b32 s0, v155, 32
	s_nop 1
	v_pk_fma_f32 v[22:23], v[106:107], s[0:1], v[22:23] op_sel_hi:[1,0,1]
	v_pk_fma_f32 v[20:21], v[104:105], s[0:1], v[20:21] op_sel_hi:[1,0,1]
	v_readlane_b32 s0, v155, 40
	s_nop 1
	v_pk_fma_f32 v[26:27], v[106:107], s[0:1], v[26:27] op_sel_hi:[1,0,1]
	v_pk_fma_f32 v[24:25], v[104:105], s[0:1], v[24:25] op_sel_hi:[1,0,1]
	v_readlane_b32 s0, v155, 48
	s_nop 1
	v_pk_fma_f32 v[30:31], v[106:107], s[0:1], v[30:31] op_sel_hi:[1,0,1]
	v_pk_fma_f32 v[28:29], v[104:105], s[0:1], v[28:29] op_sel_hi:[1,0,1]
	v_readlane_b32 s0, v155, 56
	s_nop 1
	v_pk_fma_f32 v[2:3], v[106:107], s[0:1], v[2:3] op_sel_hi:[1,0,1]
	v_pk_fma_f32 v[0:1], v[104:105], s[0:1], v[0:1] op_sel_hi:[1,0,1]
	v_readlane_b32 s0, v156, 0
	s_nop 1
	v_pk_fma_f32 v[4:5], v[100:101], s[0:1], v[4:5] op_sel_hi:[1,0,1]
	v_pk_fma_f32 v[6:7], v[102:103], s[0:1], v[6:7] op_sel_hi:[1,0,1]
	v_readlane_b32 s0, v156, 8
	s_nop 1
	v_pk_fma_f32 v[8:9], v[100:101], s[0:1], v[8:9] op_sel_hi:[1,0,1]
	v_pk_fma_f32 v[10:11], v[102:103], s[0:1], v[10:11] op_sel_hi:[1,0,1]
	v_readlane_b32 s0, v156, 16
	s_nop 1
	v_pk_fma_f32 v[12:13], v[100:101], s[0:1], v[12:13] op_sel_hi:[1,0,1]
	v_pk_fma_f32 v[14:15], v[102:103], s[0:1], v[14:15] op_sel_hi:[1,0,1]
	v_readlane_b32 s0, v156, 24
	s_nop 1
	v_pk_fma_f32 v[16:17], v[100:101], s[0:1], v[16:17] op_sel_hi:[1,0,1]
	v_pk_fma_f32 v[18:19], v[102:103], s[0:1], v[18:19] op_sel_hi:[1,0,1]
	v_readlane_b32 s0, v156, 32
	s_nop 1
	v_pk_fma_f32 v[20:21], v[100:101], s[0:1], v[20:21] op_sel_hi:[1,0,1]
	v_pk_fma_f32 v[22:23], v[102:103], s[0:1], v[22:23] op_sel_hi:[1,0,1]
	v_readlane_b32 s0, v156, 40
	s_nop 1
	v_pk_fma_f32 v[24:25], v[100:101], s[0:1], v[24:25] op_sel_hi:[1,0,1]
	v_pk_fma_f32 v[26:27], v[102:103], s[0:1], v[26:27] op_sel_hi:[1,0,1]
	v_readlane_b32 s0, v156, 48
	s_nop 1
	v_pk_fma_f32 v[28:29], v[100:101], s[0:1], v[28:29] op_sel_hi:[1,0,1]
	v_pk_fma_f32 v[30:31], v[102:103], s[0:1], v[30:31] op_sel_hi:[1,0,1]
	v_readlane_b32 s0, v156, 56
	s_nop 1
	v_pk_fma_f32 v[0:1], v[100:101], s[0:1], v[0:1] op_sel_hi:[1,0,1]
	v_pk_fma_f32 v[2:3], v[102:103], s[0:1], v[2:3] op_sel_hi:[1,0,1]
	v_readlane_b32 s0, v158, 0
	s_nop 1
	v_pk_fma_f32 v[6:7], v[98:99], s[0:1], v[6:7] op_sel_hi:[1,0,1]
	v_pk_fma_f32 v[4:5], v[96:97], s[0:1], v[4:5] op_sel_hi:[1,0,1]
	v_readlane_b32 s0, v158, 8
	s_nop 1
	v_pk_fma_f32 v[10:11], v[98:99], s[0:1], v[10:11] op_sel_hi:[1,0,1]
	v_pk_fma_f32 v[8:9], v[96:97], s[0:1], v[8:9] op_sel_hi:[1,0,1]
	v_readlane_b32 s0, v158, 16
	s_nop 1
	v_pk_fma_f32 v[14:15], v[98:99], s[0:1], v[14:15] op_sel_hi:[1,0,1]
	v_pk_fma_f32 v[12:13], v[96:97], s[0:1], v[12:13] op_sel_hi:[1,0,1]
	v_readlane_b32 s0, v158, 24
	s_nop 1
	v_pk_fma_f32 v[18:19], v[98:99], s[0:1], v[18:19] op_sel_hi:[1,0,1]
	v_pk_fma_f32 v[16:17], v[96:97], s[0:1], v[16:17] op_sel_hi:[1,0,1]
	v_readlane_b32 s0, v158, 32
	s_nop 1
	v_pk_fma_f32 v[22:23], v[98:99], s[0:1], v[22:23] op_sel_hi:[1,0,1]
	v_pk_fma_f32 v[20:21], v[96:97], s[0:1], v[20:21] op_sel_hi:[1,0,1]
	v_readlane_b32 s0, v158, 40
	s_nop 1
	v_pk_fma_f32 v[26:27], v[98:99], s[0:1], v[26:27] op_sel_hi:[1,0,1]
	v_pk_fma_f32 v[24:25], v[96:97], s[0:1], v[24:25] op_sel_hi:[1,0,1]
	v_readlane_b32 s0, v158, 48
	s_nop 1
	v_pk_fma_f32 v[30:31], v[98:99], s[0:1], v[30:31] op_sel_hi:[1,0,1]
	v_pk_fma_f32 v[28:29], v[96:97], s[0:1], v[28:29] op_sel_hi:[1,0,1]
	v_readlane_b32 s0, v158, 56
	s_nop 1
	v_pk_fma_f32 v[2:3], v[98:99], s[0:1], v[2:3] op_sel_hi:[1,0,1]
	v_pk_fma_f32 v[0:1], v[96:97], s[0:1], v[0:1] op_sel_hi:[1,0,1]
	v_readlane_b32 s0, v159, 0
	s_nop 1
	v_pk_fma_f32 v[4:5], v[92:93], s[0:1], v[4:5] op_sel_hi:[1,0,1]
	v_pk_fma_f32 v[6:7], v[94:95], s[0:1], v[6:7] op_sel_hi:[1,0,1]
	v_readlane_b32 s0, v159, 8
	s_nop 1
	v_pk_fma_f32 v[8:9], v[92:93], s[0:1], v[8:9] op_sel_hi:[1,0,1]
	v_pk_fma_f32 v[10:11], v[94:95], s[0:1], v[10:11] op_sel_hi:[1,0,1]
	v_readlane_b32 s0, v159, 16
	s_nop 1
	v_pk_fma_f32 v[12:13], v[92:93], s[0:1], v[12:13] op_sel_hi:[1,0,1]
	v_pk_fma_f32 v[14:15], v[94:95], s[0:1], v[14:15] op_sel_hi:[1,0,1]
	v_readlane_b32 s0, v159, 24
	s_nop 1
	v_pk_fma_f32 v[16:17], v[92:93], s[0:1], v[16:17] op_sel_hi:[1,0,1]
	v_pk_fma_f32 v[18:19], v[94:95], s[0:1], v[18:19] op_sel_hi:[1,0,1]
	v_readlane_b32 s0, v159, 32
	s_nop 1
	v_pk_fma_f32 v[20:21], v[92:93], s[0:1], v[20:21] op_sel_hi:[1,0,1]
	v_pk_fma_f32 v[22:23], v[94:95], s[0:1], v[22:23] op_sel_hi:[1,0,1]
	v_readlane_b32 s0, v159, 40
	s_nop 1
	v_pk_fma_f32 v[24:25], v[92:93], s[0:1], v[24:25] op_sel_hi:[1,0,1]
	v_pk_fma_f32 v[26:27], v[94:95], s[0:1], v[26:27] op_sel_hi:[1,0,1]
	v_readlane_b32 s0, v159, 48
	s_nop 1
	v_pk_fma_f32 v[28:29], v[92:93], s[0:1], v[28:29] op_sel_hi:[1,0,1]
	v_pk_fma_f32 v[30:31], v[94:95], s[0:1], v[30:31] op_sel_hi:[1,0,1]
	v_readlane_b32 s0, v159, 56
	s_nop 1
	v_pk_fma_f32 v[0:1], v[92:93], s[0:1], v[0:1] op_sel_hi:[1,0,1]
	v_pk_fma_f32 v[2:3], v[94:95], s[0:1], v[2:3] op_sel_hi:[1,0,1]
	v_readlane_b32 s0, v160, 0
	s_nop 1
	v_pk_fma_f32 v[6:7], v[90:91], s[0:1], v[6:7] op_sel_hi:[1,0,1]
	v_pk_fma_f32 v[4:5], v[88:89], s[0:1], v[4:5] op_sel_hi:[1,0,1]
	v_readlane_b32 s0, v160, 8
	s_nop 1
	v_pk_fma_f32 v[10:11], v[90:91], s[0:1], v[10:11] op_sel_hi:[1,0,1]
	v_pk_fma_f32 v[8:9], v[88:89], s[0:1], v[8:9] op_sel_hi:[1,0,1]
	v_readlane_b32 s0, v160, 16
	s_nop 1
	v_pk_fma_f32 v[14:15], v[90:91], s[0:1], v[14:15] op_sel_hi:[1,0,1]
	v_pk_fma_f32 v[12:13], v[88:89], s[0:1], v[12:13] op_sel_hi:[1,0,1]
	v_readlane_b32 s0, v160, 24
	s_nop 1
	v_pk_fma_f32 v[18:19], v[90:91], s[0:1], v[18:19] op_sel_hi:[1,0,1]
	v_pk_fma_f32 v[16:17], v[88:89], s[0:1], v[16:17] op_sel_hi:[1,0,1]
	v_readlane_b32 s0, v160, 32
	s_nop 1
	v_pk_fma_f32 v[22:23], v[90:91], s[0:1], v[22:23] op_sel_hi:[1,0,1]
	v_pk_fma_f32 v[20:21], v[88:89], s[0:1], v[20:21] op_sel_hi:[1,0,1]
	v_readlane_b32 s0, v160, 40
	s_nop 1
	v_pk_fma_f32 v[26:27], v[90:91], s[0:1], v[26:27] op_sel_hi:[1,0,1]
	v_pk_fma_f32 v[24:25], v[88:89], s[0:1], v[24:25] op_sel_hi:[1,0,1]
	v_readlane_b32 s0, v160, 48
	s_nop 1
	v_pk_fma_f32 v[30:31], v[90:91], s[0:1], v[30:31] op_sel_hi:[1,0,1]
	v_pk_fma_f32 v[28:29], v[88:89], s[0:1], v[28:29] op_sel_hi:[1,0,1]
	v_readlane_b32 s0, v160, 56
	s_nop 1
	v_pk_fma_f32 v[2:3], v[90:91], s[0:1], v[2:3] op_sel_hi:[1,0,1]
	v_pk_fma_f32 v[0:1], v[88:89], s[0:1], v[0:1] op_sel_hi:[1,0,1]
	v_readlane_b32 s0, v161, 0
	s_nop 1
	v_pk_fma_f32 v[4:5], v[84:85], s[0:1], v[4:5] op_sel_hi:[1,0,1]
	v_pk_fma_f32 v[6:7], v[86:87], s[0:1], v[6:7] op_sel_hi:[1,0,1]
	v_readlane_b32 s0, v161, 8
	s_nop 1
	v_pk_fma_f32 v[8:9], v[84:85], s[0:1], v[8:9] op_sel_hi:[1,0,1]
	v_pk_fma_f32 v[10:11], v[86:87], s[0:1], v[10:11] op_sel_hi:[1,0,1]
	v_readlane_b32 s0, v161, 16
	s_nop 1
	v_pk_fma_f32 v[12:13], v[84:85], s[0:1], v[12:13] op_sel_hi:[1,0,1]
	v_pk_fma_f32 v[14:15], v[86:87], s[0:1], v[14:15] op_sel_hi:[1,0,1]
	v_readlane_b32 s0, v161, 24
	s_nop 1
	v_pk_fma_f32 v[16:17], v[84:85], s[0:1], v[16:17] op_sel_hi:[1,0,1]
	v_pk_fma_f32 v[18:19], v[86:87], s[0:1], v[18:19] op_sel_hi:[1,0,1]
	v_readlane_b32 s0, v161, 32
	s_nop 1
	v_pk_fma_f32 v[20:21], v[84:85], s[0:1], v[20:21] op_sel_hi:[1,0,1]
	v_pk_fma_f32 v[22:23], v[86:87], s[0:1], v[22:23] op_sel_hi:[1,0,1]
	v_readlane_b32 s0, v161, 40
	s_nop 1
	v_pk_fma_f32 v[24:25], v[84:85], s[0:1], v[24:25] op_sel_hi:[1,0,1]
	v_pk_fma_f32 v[26:27], v[86:87], s[0:1], v[26:27] op_sel_hi:[1,0,1]
	v_readlane_b32 s0, v161, 48
	s_nop 1
	v_pk_fma_f32 v[28:29], v[84:85], s[0:1], v[28:29] op_sel_hi:[1,0,1]
	v_pk_fma_f32 v[30:31], v[86:87], s[0:1], v[30:31] op_sel_hi:[1,0,1]
	v_readlane_b32 s0, v161, 56
	s_nop 1
	v_pk_fma_f32 v[0:1], v[84:85], s[0:1], v[0:1] op_sel_hi:[1,0,1]
	v_pk_fma_f32 v[2:3], v[86:87], s[0:1], v[2:3] op_sel_hi:[1,0,1]
	v_readlane_b32 s0, v162, 0
	s_nop 1
	v_pk_fma_f32 v[6:7], v[82:83], s[0:1], v[6:7] op_sel_hi:[1,0,1]
	v_pk_fma_f32 v[4:5], v[80:81], s[0:1], v[4:5] op_sel_hi:[1,0,1]
	v_readlane_b32 s0, v162, 8
	s_nop 1
	v_pk_fma_f32 v[10:11], v[82:83], s[0:1], v[10:11] op_sel_hi:[1,0,1]
	v_pk_fma_f32 v[8:9], v[80:81], s[0:1], v[8:9] op_sel_hi:[1,0,1]
	v_readlane_b32 s0, v162, 16
	s_nop 1
	v_pk_fma_f32 v[14:15], v[82:83], s[0:1], v[14:15] op_sel_hi:[1,0,1]
	v_pk_fma_f32 v[12:13], v[80:81], s[0:1], v[12:13] op_sel_hi:[1,0,1]
	v_readlane_b32 s0, v162, 24
	s_nop 1
	v_pk_fma_f32 v[18:19], v[82:83], s[0:1], v[18:19] op_sel_hi:[1,0,1]
	v_pk_fma_f32 v[16:17], v[80:81], s[0:1], v[16:17] op_sel_hi:[1,0,1]
	v_readlane_b32 s0, v162, 32
	s_nop 1
	v_pk_fma_f32 v[22:23], v[82:83], s[0:1], v[22:23] op_sel_hi:[1,0,1]
	v_pk_fma_f32 v[20:21], v[80:81], s[0:1], v[20:21] op_sel_hi:[1,0,1]
	v_readlane_b32 s0, v162, 40
	s_nop 1
	v_pk_fma_f32 v[26:27], v[82:83], s[0:1], v[26:27] op_sel_hi:[1,0,1]
	v_pk_fma_f32 v[24:25], v[80:81], s[0:1], v[24:25] op_sel_hi:[1,0,1]
	v_readlane_b32 s0, v162, 48
	s_nop 1
	v_pk_fma_f32 v[30:31], v[82:83], s[0:1], v[30:31] op_sel_hi:[1,0,1]
	v_pk_fma_f32 v[28:29], v[80:81], s[0:1], v[28:29] op_sel_hi:[1,0,1]
	v_readlane_b32 s0, v162, 56
	s_nop 1
	v_pk_fma_f32 v[2:3], v[82:83], s[0:1], v[2:3] op_sel_hi:[1,0,1]
	v_pk_fma_f32 v[0:1], v[80:81], s[0:1], v[0:1] op_sel_hi:[1,0,1]
	v_readlane_b32 s0, v163, 0
	s_nop 1
	v_pk_fma_f32 v[4:5], v[76:77], s[0:1], v[4:5] op_sel_hi:[1,0,1]
	v_pk_fma_f32 v[6:7], v[78:79], s[0:1], v[6:7] op_sel_hi:[1,0,1]
	v_readlane_b32 s0, v163, 8
	s_nop 1
	v_pk_fma_f32 v[8:9], v[76:77], s[0:1], v[8:9] op_sel_hi:[1,0,1]
	v_pk_fma_f32 v[10:11], v[78:79], s[0:1], v[10:11] op_sel_hi:[1,0,1]
	v_readlane_b32 s0, v163, 16
	s_nop 1
	v_pk_fma_f32 v[12:13], v[76:77], s[0:1], v[12:13] op_sel_hi:[1,0,1]
	v_pk_fma_f32 v[14:15], v[78:79], s[0:1], v[14:15] op_sel_hi:[1,0,1]
	v_readlane_b32 s0, v163, 24
	s_nop 1
	v_pk_fma_f32 v[16:17], v[76:77], s[0:1], v[16:17] op_sel_hi:[1,0,1]
	v_pk_fma_f32 v[18:19], v[78:79], s[0:1], v[18:19] op_sel_hi:[1,0,1]
	v_readlane_b32 s0, v163, 32
	s_nop 1
	v_pk_fma_f32 v[20:21], v[76:77], s[0:1], v[20:21] op_sel_hi:[1,0,1]
	v_pk_fma_f32 v[22:23], v[78:79], s[0:1], v[22:23] op_sel_hi:[1,0,1]
	v_readlane_b32 s0, v163, 40
	s_nop 1
	v_pk_fma_f32 v[24:25], v[76:77], s[0:1], v[24:25] op_sel_hi:[1,0,1]
	v_pk_fma_f32 v[26:27], v[78:79], s[0:1], v[26:27] op_sel_hi:[1,0,1]
	v_readlane_b32 s0, v163, 48
	s_nop 1
	v_pk_fma_f32 v[28:29], v[76:77], s[0:1], v[28:29] op_sel_hi:[1,0,1]
	v_pk_fma_f32 v[30:31], v[78:79], s[0:1], v[30:31] op_sel_hi:[1,0,1]
	v_readlane_b32 s0, v163, 56
	s_nop 1
	v_pk_fma_f32 v[0:1], v[76:77], s[0:1], v[0:1] op_sel_hi:[1,0,1]
	v_pk_fma_f32 v[2:3], v[78:79], s[0:1], v[2:3] op_sel_hi:[1,0,1]
	v_readlane_b32 s0, v164, 0
	s_nop 1
	v_pk_fma_f32 v[6:7], v[74:75], s[0:1], v[6:7] op_sel_hi:[1,0,1]
	v_pk_fma_f32 v[4:5], v[72:73], s[0:1], v[4:5] op_sel_hi:[1,0,1]
	v_readlane_b32 s0, v164, 8
	s_nop 1
	v_pk_fma_f32 v[10:11], v[74:75], s[0:1], v[10:11] op_sel_hi:[1,0,1]
	v_pk_fma_f32 v[8:9], v[72:73], s[0:1], v[8:9] op_sel_hi:[1,0,1]
	v_readlane_b32 s0, v164, 16
	s_nop 1
	v_pk_fma_f32 v[14:15], v[74:75], s[0:1], v[14:15] op_sel_hi:[1,0,1]
	v_pk_fma_f32 v[12:13], v[72:73], s[0:1], v[12:13] op_sel_hi:[1,0,1]
	v_readlane_b32 s0, v164, 24
	s_nop 1
	v_pk_fma_f32 v[18:19], v[74:75], s[0:1], v[18:19] op_sel_hi:[1,0,1]
	v_pk_fma_f32 v[16:17], v[72:73], s[0:1], v[16:17] op_sel_hi:[1,0,1]
	v_readlane_b32 s0, v164, 32
	s_nop 1
	v_pk_fma_f32 v[22:23], v[74:75], s[0:1], v[22:23] op_sel_hi:[1,0,1]
	v_pk_fma_f32 v[20:21], v[72:73], s[0:1], v[20:21] op_sel_hi:[1,0,1]
	v_readlane_b32 s0, v164, 40
	s_nop 1
	v_pk_fma_f32 v[26:27], v[74:75], s[0:1], v[26:27] op_sel_hi:[1,0,1]
	v_pk_fma_f32 v[24:25], v[72:73], s[0:1], v[24:25] op_sel_hi:[1,0,1]
	v_readlane_b32 s0, v164, 48
	s_nop 1
	v_pk_fma_f32 v[30:31], v[74:75], s[0:1], v[30:31] op_sel_hi:[1,0,1]
	v_pk_fma_f32 v[28:29], v[72:73], s[0:1], v[28:29] op_sel_hi:[1,0,1]
	v_readlane_b32 s0, v164, 56
	s_nop 1
	v_pk_fma_f32 v[2:3], v[74:75], s[0:1], v[2:3] op_sel_hi:[1,0,1]
	v_pk_fma_f32 v[0:1], v[72:73], s[0:1], v[0:1] op_sel_hi:[1,0,1]
	v_readlane_b32 s0, v165, 0
	s_nop 1
	v_pk_fma_f32 v[4:5], v[68:69], s[0:1], v[4:5] op_sel_hi:[1,0,1]
	v_pk_fma_f32 v[6:7], v[70:71], s[0:1], v[6:7] op_sel_hi:[1,0,1]
	v_readlane_b32 s0, v165, 8
	s_nop 1
	v_pk_fma_f32 v[8:9], v[68:69], s[0:1], v[8:9] op_sel_hi:[1,0,1]
	v_pk_fma_f32 v[10:11], v[70:71], s[0:1], v[10:11] op_sel_hi:[1,0,1]
	v_readlane_b32 s0, v165, 16
	s_nop 1
	v_pk_fma_f32 v[12:13], v[68:69], s[0:1], v[12:13] op_sel_hi:[1,0,1]
	v_pk_fma_f32 v[14:15], v[70:71], s[0:1], v[14:15] op_sel_hi:[1,0,1]
	v_readlane_b32 s0, v165, 24
	s_nop 1
	v_pk_fma_f32 v[16:17], v[68:69], s[0:1], v[16:17] op_sel_hi:[1,0,1]
	v_pk_fma_f32 v[18:19], v[70:71], s[0:1], v[18:19] op_sel_hi:[1,0,1]
	v_readlane_b32 s0, v165, 32
	s_nop 1
	v_pk_fma_f32 v[20:21], v[68:69], s[0:1], v[20:21] op_sel_hi:[1,0,1]
	v_pk_fma_f32 v[22:23], v[70:71], s[0:1], v[22:23] op_sel_hi:[1,0,1]
	v_readlane_b32 s0, v165, 40
	s_nop 1
	v_pk_fma_f32 v[24:25], v[68:69], s[0:1], v[24:25] op_sel_hi:[1,0,1]
	v_pk_fma_f32 v[26:27], v[70:71], s[0:1], v[26:27] op_sel_hi:[1,0,1]
	v_readlane_b32 s0, v165, 48
	s_nop 1
	v_pk_fma_f32 v[28:29], v[68:69], s[0:1], v[28:29] op_sel_hi:[1,0,1]
	v_pk_fma_f32 v[30:31], v[70:71], s[0:1], v[30:31] op_sel_hi:[1,0,1]
	v_readlane_b32 s0, v165, 56
	s_nop 1
	v_pk_fma_f32 v[32:33], v[68:69], s[0:1], v[0:1] op_sel_hi:[1,0,1]
	v_pk_fma_f32 v[34:35], v[70:71], s[0:1], v[2:3] op_sel_hi:[1,0,1]
	v_readlane_b32 s0, v166, 0
	s_waitcnt vmcnt(0)
	s_nop 0
	v_pk_fma_f32 v[2:3], v[66:67], s[0:1], v[6:7] op_sel_hi:[1,0,1]
	v_pk_fma_f32 v[0:1], v[64:65], s[0:1], v[4:5] op_sel_hi:[1,0,1]
	v_readlane_b32 s0, v166, 8
	s_nop 1
	v_pk_fma_f32 v[6:7], v[66:67], s[0:1], v[10:11] op_sel_hi:[1,0,1]
	v_pk_fma_f32 v[4:5], v[64:65], s[0:1], v[8:9] op_sel_hi:[1,0,1]
	v_readlane_b32 s0, v166, 16
	s_nop 1
	v_pk_fma_f32 v[10:11], v[66:67], s[0:1], v[14:15] op_sel_hi:[1,0,1]
	v_pk_fma_f32 v[8:9], v[64:65], s[0:1], v[12:13] op_sel_hi:[1,0,1]
	v_readlane_b32 s0, v166, 24
	s_nop 1
	v_pk_fma_f32 v[14:15], v[66:67], s[0:1], v[18:19] op_sel_hi:[1,0,1]
	v_pk_fma_f32 v[12:13], v[64:65], s[0:1], v[16:17] op_sel_hi:[1,0,1]
	v_readlane_b32 s0, v166, 32
	s_nop 1
	v_pk_fma_f32 v[18:19], v[66:67], s[0:1], v[22:23] op_sel_hi:[1,0,1]
	v_pk_fma_f32 v[16:17], v[64:65], s[0:1], v[20:21] op_sel_hi:[1,0,1]
	v_readlane_b32 s0, v166, 40
	s_nop 1
	v_pk_fma_f32 v[22:23], v[66:67], s[0:1], v[26:27] op_sel_hi:[1,0,1]
	v_pk_fma_f32 v[20:21], v[64:65], s[0:1], v[24:25] op_sel_hi:[1,0,1]
	v_readlane_b32 s0, v166, 48
	s_nop 1
	v_pk_fma_f32 v[26:27], v[66:67], s[0:1], v[30:31] op_sel_hi:[1,0,1]
	v_pk_fma_f32 v[24:25], v[64:65], s[0:1], v[28:29] op_sel_hi:[1,0,1]
	v_readlane_b32 s0, v166, 56
	s_nop 1
	v_pk_fma_f32 v[28:29], v[64:65], s[0:1], v[32:33] op_sel_hi:[1,0,1]
	v_lshlrev_b32_e32 v32, 13, v129
	v_lshlrev_b32_e32 v33, 4, v131
	v_add3_u32 v32, 0, v32, v33
	v_pk_fma_f32 v[30:31], v[66:67], s[0:1], v[34:35] op_sel_hi:[1,0,1]
	ds_write_b128 v32, v[0:3]
	ds_write_b128 v32, v[4:7] offset:1024
	ds_write_b128 v32, v[8:11] offset:2048
	ds_write_b128 v32, v[12:15] offset:3072
	ds_write_b128 v32, v[16:19] offset:4096
	ds_write_b128 v32, v[20:23] offset:5120
	ds_write_b128 v32, v[24:27] offset:6144
	ds_write_b128 v32, v[28:31] offset:7168
	v_and_b32_e32 v0, 7, v130
	v_cmp_eq_u32_e32 vcc, 0, v0
	s_and_saveexec_b64 s[2:3], vcc
	s_cbranch_execz .LBB0_500
	v_add_f32_e32 v0, 0, v133
	v_add_f32_e32 v0, v135, v0
	v_add_f32_e32 v0, v136, v0
	v_add_f32_e32 v0, v137, v0
	v_add_f32_e32 v0, v138, v0
	v_add_f32_e32 v0, v139, v0
	v_add_f32_e32 v0, v140, v0
	v_add_f32_e32 v0, v141, v0
	v_add_f32_e32 v0, v142, v0
	v_add_f32_e32 v0, v143, v0
	v_add_f32_e32 v0, v144, v0
	v_add_f32_e32 v0, v145, v0
	v_add_f32_e32 v0, v146, v0
	v_add_f32_e32 v0, v147, v0
	v_add_f32_e32 v0, v148, v0
	v_add_f32_e32 v0, v149, v0
	v_add_f32_e32 v0, v150, v0
	v_add_f32_e32 v0, v151, v0
	v_add_f32_e32 v0, v152, v0
	v_add_f32_e32 v0, v153, v0
	v_add_f32_e32 v0, v154, v0
	v_add_f32_e32 v0, v155, v0
	v_add_f32_e32 v0, v156, v0
	v_add_f32_e32 v0, v158, v0
	v_add_f32_e32 v0, v159, v0
	v_add_f32_e32 v0, v160, v0
	v_add_f32_e32 v0, v161, v0
	v_add_f32_e32 v0, v162, v0
	v_add_f32_e32 v0, v163, v0
	v_add_f32_e32 v0, v164, v0
	v_lshrrev_b32_e32 v2, 1, v130
	v_add_f32_e32 v0, v165, v0
	v_and_b32_e32 v1, 0xffffffc0, v132
	s_add_i32 s0, 0, 0x10000
	v_and_b32_e32 v2, 28, v2
	v_add_f32_e32 v0, v166, v0
	v_add3_u32 v1, s0, v1, v2
	ds_write2_b32 v1, v134, v0 offset1:8
	s_branch .LBB0_500
